# GEMM loops: s_setprio 1 raised before the hand-off barrier instead of after it (36 sites)
# baseline (speedup 1.0000x reference)
.LBB0_81:
	s_add_u32 s20, s94, 0xfce78080
	s_addc_u32 s59, s95, -1
	s_cmp_lg_u32 s58, 12
	s_cselect_b32 s20, s20, 0
	s_cselect_b32 s59, s59, 0
	s_add_u32 vcc_lo, s40, s20
	s_addc_u32 vcc_hi, s41, s59
	s_add_i32 s82, 0, 0x10000
	s_add_u32 s96, s42, s20
	v_add_u32_e32 v143, s82, v141
	s_addc_u32 s97, s43, s59
	s_add_i32 s20, 0, 0x14000
	ds_read_b128 v[144:147], v143
	ds_read_b128 v[148:151], v143 offset:1024
	ds_read_b128 v[152:155], v143 offset:2048
	ds_read_b128 v[158:161], v143 offset:3072
	v_add_u32_e32 v143, s20, v141
	ds_read_b128 v[162:165], v143
	ds_read_b128 v[196:199], v143 offset:1024
	ds_read_b128 v[200:203], v143 offset:2048
	ds_read_b128 v[204:207], v143 offset:3072
	v_lshl_add_u64 v[176:177], v[138:139], 0, s[94:95]
	s_add_i32 m0, s16, 0xc000
	ds_read_b128 v[208:211], v142
	ds_read_b128 v[212:215], v142 offset:1024
	ds_read_b128 v[216:219], v142 offset:2048
	ds_read_b128 v[220:223], v142 offset:3072
	ds_read_b128 v[224:227], v142 offset:4096
	ds_read_b128 v[228:231], v142 offset:5120
	ds_read_b128 v[232:235], v142 offset:6144
	ds_read_b128 v[236:239], v142 offset:7168
	global_load_lds_dwordx4 v[176:177], off
	v_lshl_add_u64 v[176:177], v[136:137], 0, s[94:95]
	s_add_i32 m0, s16, 0xe000
	s_nop 0
	global_load_lds_dwordx4 v[176:177], off
	s_waitcnt vmcnt(8)
	s_waitcnt lgkmcnt(0)
	s_setprio 1
	s_barrier
	s_waitcnt lgkmcnt(0)
	v_mfma_f32_16x16x32_bf16 v[126:129], v[144:147], v[208:211], v[126:129]
	v_mfma_f32_16x16x32_bf16 v[122:125], v[152:155], v[208:211], v[122:125]
	v_mfma_f32_16x16x32_bf16 v[118:121], v[144:147], v[216:219], v[118:121]
	v_mfma_f32_16x16x32_bf16 v[114:117], v[152:155], v[216:219], v[114:117]
	v_mfma_f32_16x16x32_bf16 v[102:105], v[144:147], v[224:227], v[102:105]
	v_mfma_f32_16x16x32_bf16 v[98:101], v[152:155], v[224:227], v[98:101]
	v_mfma_f32_16x16x32_bf16 v[86:89], v[144:147], v[232:235], v[86:89]
	v_mfma_f32_16x16x32_bf16 v[82:85], v[152:155], v[232:235], v[82:85]
	s_setprio 0
	s_setprio 1
	v_mfma_f32_16x16x32_bf16 v[126:129], v[148:151], v[212:215], v[126:129]
	v_mfma_f32_16x16x32_bf16 v[122:125], v[158:161], v[212:215], v[122:125]
	v_mfma_f32_16x16x32_bf16 v[118:121], v[148:151], v[220:223], v[118:121]
	v_mfma_f32_16x16x32_bf16 v[114:117], v[158:161], v[220:223], v[114:117]
	v_mfma_f32_16x16x32_bf16 v[102:105], v[148:151], v[228:231], v[102:105]
	v_mfma_f32_16x16x32_bf16 v[98:101], v[158:161], v[228:231], v[98:101]
	v_mfma_f32_16x16x32_bf16 v[86:89], v[148:151], v[236:239], v[86:89]
	v_mfma_f32_16x16x32_bf16 v[82:85], v[158:161], v[236:239], v[82:85]
	s_setprio 0
	s_setprio 1
	v_mfma_f32_16x16x32_bf16 v[110:113], v[162:165], v[208:211], v[110:113]
	v_mfma_f32_16x16x32_bf16 v[106:109], v[200:203], v[208:211], v[106:109]
	v_mfma_f32_16x16x32_bf16 v[94:97], v[162:165], v[216:219], v[94:97]
	v_mfma_f32_16x16x32_bf16 v[90:93], v[200:203], v[216:219], v[90:93]
	v_mfma_f32_16x16x32_bf16 v[78:81], v[162:165], v[224:227], v[78:81]
	v_mfma_f32_16x16x32_bf16 v[74:77], v[200:203], v[224:227], v[74:77]
	v_mfma_f32_16x16x32_bf16 v[70:73], v[162:165], v[232:235], v[70:73]
	v_mfma_f32_16x16x32_bf16 v[66:69], v[200:203], v[232:235], v[66:69]
	s_setprio 0
	s_setprio 1
	v_mfma_f32_16x16x32_bf16 v[110:113], v[196:199], v[212:215], v[110:113]
	v_mfma_f32_16x16x32_bf16 v[106:109], v[204:207], v[212:215], v[106:109]
	v_mfma_f32_16x16x32_bf16 v[94:97], v[196:199], v[220:223], v[94:97]
	v_mfma_f32_16x16x32_bf16 v[90:93], v[204:207], v[220:223], v[90:93]
	v_mfma_f32_16x16x32_bf16 v[78:81], v[196:199], v[228:231], v[78:81]
	v_mfma_f32_16x16x32_bf16 v[74:77], v[204:207], v[228:231], v[74:77]
	v_mfma_f32_16x16x32_bf16 v[70:73], v[196:199], v[236:239], v[70:73]
	v_mfma_f32_16x16x32_bf16 v[66:69], v[204:207], v[236:239], v[66:69]
	s_setprio 0
	s_barrier
	s_add_i32 s59, s82, s3
	v_lshl_add_u64 v[176:177], s[96:97], 0, v[0:1]
	s_mov_b32 m0, s59
	ds_read_b128 v[208:211], v142 offset:16384
	ds_read_b128 v[212:215], v142 offset:17408
	ds_read_b128 v[216:219], v142 offset:18432
	ds_read_b128 v[220:223], v142 offset:19456
	ds_read_b128 v[224:227], v142 offset:20480
	ds_read_b128 v[228:231], v142 offset:21504
	ds_read_b128 v[232:235], v142 offset:22528
	ds_read_b128 v[236:239], v142 offset:23552
	global_load_lds_dwordx4 v[176:177], off
	s_add_i32 m0, s59, 0x2000
	s_add_u32 s82, s96, 0x580000
	v_lshl_add_u64 v[178:179], s[96:97], 0, v[134:135]
	s_addc_u32 s83, s97, 0
	s_add_i32 s20, s20, s3
	global_load_lds_dwordx4 v[178:179], off
	v_lshl_add_u64 v[194:195], s[82:83], 0, v[0:1]
	s_mov_b32 m0, s20
	v_lshl_add_u64 v[240:241], vcc, 0, v[132:133]
	global_load_lds_dwordx4 v[194:195], off
	v_lshl_add_u64 v[194:195], s[82:83], 0, v[134:135]
	s_add_i32 m0, s20, 0x2000
	s_nop 0
	global_load_lds_dwordx4 v[194:195], off
	v_lshl_add_u64 v[194:195], vcc, 0, v[130:131]
	s_mov_b32 m0, s16
	s_nop 0
	global_load_lds_dwordx4 v[194:195], off
	s_mov_b32 m0, s17
	s_nop 0
	global_load_lds_dwordx4 v[240:241], off
	s_waitcnt vmcnt(8)
	s_waitcnt lgkmcnt(0)
	s_setprio 1
	s_barrier
	s_waitcnt lgkmcnt(0)
	v_mfma_f32_16x16x32_bf16 v[62:65], v[144:147], v[208:211], v[62:65]
	v_mfma_f32_16x16x32_bf16 v[58:61], v[152:155], v[208:211], v[58:61]
	v_mfma_f32_16x16x32_bf16 v[54:57], v[144:147], v[216:219], v[54:57]
	v_mfma_f32_16x16x32_bf16 v[50:53], v[152:155], v[216:219], v[50:53]
	v_mfma_f32_16x16x32_bf16 v[38:41], v[144:147], v[224:227], v[38:41]
	v_mfma_f32_16x16x32_bf16 v[34:37], v[152:155], v[224:227], v[34:37]
	v_mfma_f32_16x16x32_bf16 v[22:25], v[144:147], v[232:235], v[22:25]
	v_mfma_f32_16x16x32_bf16 v[18:21], v[152:155], v[232:235], v[18:21]
	s_setprio 0
	s_setprio 1
	v_mfma_f32_16x16x32_bf16 v[62:65], v[148:151], v[212:215], v[62:65]
	v_mfma_f32_16x16x32_bf16 v[58:61], v[158:161], v[212:215], v[58:61]
	v_mfma_f32_16x16x32_bf16 v[54:57], v[148:151], v[220:223], v[54:57]
	v_mfma_f32_16x16x32_bf16 v[50:53], v[158:161], v[220:223], v[50:53]
	v_mfma_f32_16x16x32_bf16 v[38:41], v[148:151], v[228:231], v[38:41]
	v_mfma_f32_16x16x32_bf16 v[34:37], v[158:161], v[228:231], v[34:37]
	v_mfma_f32_16x16x32_bf16 v[22:25], v[148:151], v[236:239], v[22:25]
	v_mfma_f32_16x16x32_bf16 v[18:21], v[158:161], v[236:239], v[18:21]
	s_setprio 0
	s_setprio 1
	v_mfma_f32_16x16x32_bf16 v[46:49], v[162:165], v[208:211], v[46:49]
	v_mfma_f32_16x16x32_bf16 v[42:45], v[200:203], v[208:211], v[42:45]
	v_mfma_f32_16x16x32_bf16 v[30:33], v[162:165], v[216:219], v[30:33]
	v_mfma_f32_16x16x32_bf16 v[26:29], v[200:203], v[216:219], v[26:29]
	v_mfma_f32_16x16x32_bf16 v[14:17], v[162:165], v[224:227], v[14:17]
	v_mfma_f32_16x16x32_bf16 v[10:13], v[200:203], v[224:227], v[10:13]
	v_mfma_f32_16x16x32_bf16 v[6:9], v[162:165], v[232:235], v[6:9]
	v_mfma_f32_16x16x32_bf16 v[2:5], v[200:203], v[232:235], v[2:5]
	s_setprio 0
	s_setprio 1
	v_mfma_f32_16x16x32_bf16 v[46:49], v[196:199], v[212:215], v[46:49]
	v_mfma_f32_16x16x32_bf16 v[42:45], v[204:207], v[212:215], v[42:45]
	v_mfma_f32_16x16x32_bf16 v[30:33], v[196:199], v[220:223], v[30:33]
	v_mfma_f32_16x16x32_bf16 v[26:29], v[204:207], v[220:223], v[26:29]
	v_mfma_f32_16x16x32_bf16 v[14:17], v[196:199], v[228:231], v[14:17]
	v_mfma_f32_16x16x32_bf16 v[10:13], v[204:207], v[228:231], v[10:13]
	v_mfma_f32_16x16x32_bf16 v[6:9], v[196:199], v[236:239], v[6:9]
	v_mfma_f32_16x16x32_bf16 v[2:5], v[204:207], v[236:239], v[2:5]
	s_setprio 0
	s_barrier
	s_add_i32 s20, 0, 0x18000
	v_add_u32_e32 v143, s20, v141
	s_add_i32 s59, 0, 0x1c000
	ds_read_b128 v[144:147], v143
	ds_read_b128 v[148:151], v143 offset:1024
	ds_read_b128 v[152:155], v143 offset:2048
	ds_read_b128 v[158:161], v143 offset:3072
	v_add_u32_e32 v143, s59, v141
	ds_read_b128 v[162:165], v143
	ds_read_b128 v[196:199], v143 offset:1024
	ds_read_b128 v[200:203], v143 offset:2048
	ds_read_b128 v[204:207], v143 offset:3072
	s_add_u32 s82, vcc_lo, 0x40000
	s_addc_u32 s83, vcc_hi, 0
	s_mov_b32 m0, s28
	v_lshl_add_u64 v[242:243], s[82:83], 0, v[130:131]
	ds_read_b128 v[208:211], v142 offset:32768
	ds_read_b128 v[212:215], v142 offset:33792
	ds_read_b128 v[216:219], v142 offset:34816
	ds_read_b128 v[220:223], v142 offset:35840
	ds_read_b128 v[224:227], v142 offset:36864
	ds_read_b128 v[228:231], v142 offset:37888
	ds_read_b128 v[232:235], v142 offset:38912
	ds_read_b128 v[236:239], v142 offset:39936
	global_load_lds_dwordx4 v[242:243], off
	v_lshl_add_u64 v[242:243], s[82:83], 0, v[132:133]
	s_mov_b32 m0, s70
	s_nop 0
	global_load_lds_dwordx4 v[242:243], off
	s_waitcnt vmcnt(8)
	s_waitcnt lgkmcnt(0)
	s_setprio 1
	s_barrier
	s_waitcnt lgkmcnt(0)
	v_mfma_f32_16x16x32_bf16 v[126:129], v[144:147], v[208:211], v[126:129]
	v_mfma_f32_16x16x32_bf16 v[122:125], v[152:155], v[208:211], v[122:125]
	v_mfma_f32_16x16x32_bf16 v[118:121], v[144:147], v[216:219], v[118:121]
	v_mfma_f32_16x16x32_bf16 v[114:117], v[152:155], v[216:219], v[114:117]
	v_mfma_f32_16x16x32_bf16 v[102:105], v[144:147], v[224:227], v[102:105]
	v_mfma_f32_16x16x32_bf16 v[98:101], v[152:155], v[224:227], v[98:101]
	v_mfma_f32_16x16x32_bf16 v[86:89], v[144:147], v[232:235], v[86:89]
	v_mfma_f32_16x16x32_bf16 v[82:85], v[152:155], v[232:235], v[82:85]
	s_setprio 0
	s_setprio 1
	v_mfma_f32_16x16x32_bf16 v[126:129], v[148:151], v[212:215], v[126:129]
	v_mfma_f32_16x16x32_bf16 v[122:125], v[158:161], v[212:215], v[122:125]
	v_mfma_f32_16x16x32_bf16 v[118:121], v[148:151], v[220:223], v[118:121]
	v_mfma_f32_16x16x32_bf16 v[114:117], v[158:161], v[220:223], v[114:117]
	v_mfma_f32_16x16x32_bf16 v[102:105], v[148:151], v[228:231], v[102:105]
	v_mfma_f32_16x16x32_bf16 v[98:101], v[158:161], v[228:231], v[98:101]
	v_mfma_f32_16x16x32_bf16 v[86:89], v[148:151], v[236:239], v[86:89]
	v_mfma_f32_16x16x32_bf16 v[82:85], v[158:161], v[236:239], v[82:85]
	s_setprio 0
	s_setprio 1
	v_mfma_f32_16x16x32_bf16 v[110:113], v[162:165], v[208:211], v[110:113]
	v_mfma_f32_16x16x32_bf16 v[106:109], v[200:203], v[208:211], v[106:109]
	v_mfma_f32_16x16x32_bf16 v[94:97], v[162:165], v[216:219], v[94:97]
	v_mfma_f32_16x16x32_bf16 v[90:93], v[200:203], v[216:219], v[90:93]
	v_mfma_f32_16x16x32_bf16 v[78:81], v[162:165], v[224:227], v[78:81]
	v_mfma_f32_16x16x32_bf16 v[74:77], v[200:203], v[224:227], v[74:77]
	v_mfma_f32_16x16x32_bf16 v[70:73], v[162:165], v[232:235], v[70:73]
	v_mfma_f32_16x16x32_bf16 v[66:69], v[200:203], v[232:235], v[66:69]
	s_setprio 0
	s_setprio 1
	v_mfma_f32_16x16x32_bf16 v[110:113], v[196:199], v[212:215], v[110:113]
	v_mfma_f32_16x16x32_bf16 v[106:109], v[204:207], v[212:215], v[106:109]
	v_mfma_f32_16x16x32_bf16 v[94:97], v[196:199], v[220:223], v[94:97]
	v_mfma_f32_16x16x32_bf16 v[90:93], v[204:207], v[220:223], v[90:93]
	v_mfma_f32_16x16x32_bf16 v[78:81], v[196:199], v[228:231], v[78:81]
	v_mfma_f32_16x16x32_bf16 v[74:77], v[204:207], v[228:231], v[74:77]
	v_mfma_f32_16x16x32_bf16 v[70:73], v[196:199], v[236:239], v[70:73]
	v_mfma_f32_16x16x32_bf16 v[66:69], v[204:207], v[236:239], v[66:69]
	s_setprio 0
	s_barrier
	s_add_i32 s20, s20, s3
	v_lshl_add_u64 v[176:177], v[176:177], 0, s[24:25]
	s_mov_b32 m0, s20
	ds_read_b128 v[208:211], v142 offset:49152
	ds_read_b128 v[212:215], v142 offset:50176
	ds_read_b128 v[216:219], v142 offset:51200
	ds_read_b128 v[220:223], v142 offset:52224
	ds_read_b128 v[224:227], v142 offset:53248
	ds_read_b128 v[228:231], v142 offset:54272
	ds_read_b128 v[232:235], v142 offset:55296
	ds_read_b128 v[236:239], v142 offset:56320
	global_load_lds_dwordx4 v[176:177], off
	s_add_i32 m0, s20, 0x2000
	s_add_u32 s82, s96, 0x580080
	v_lshl_add_u64 v[176:177], v[178:179], 0, s[24:25]
	s_addc_u32 s83, s97, 0
	s_add_i32 s20, s59, s3
	global_load_lds_dwordx4 v[176:177], off
	v_lshl_add_u64 v[176:177], s[82:83], 0, v[0:1]
	s_mov_b32 m0, s20
	s_nop 0
	global_load_lds_dwordx4 v[176:177], off
	v_lshl_add_u64 v[176:177], s[82:83], 0, v[134:135]
	s_add_i32 m0, s20, 0x2000
	s_nop 0
	global_load_lds_dwordx4 v[176:177], off
	v_lshl_add_u64 v[176:177], v[194:195], 0, s[24:25]
	s_mov_b32 m0, s86
	s_nop 0
	global_load_lds_dwordx4 v[176:177], off
	v_lshl_add_u64 v[176:177], v[240:241], 0, s[24:25]
	s_mov_b32 m0, s87
	s_nop 0
	global_load_lds_dwordx4 v[176:177], off
	s_waitcnt vmcnt(8)
	s_waitcnt lgkmcnt(0)
	s_setprio 1
	s_barrier
	s_waitcnt lgkmcnt(0)
	v_mfma_f32_16x16x32_bf16 v[62:65], v[144:147], v[208:211], v[62:65]
	v_mfma_f32_16x16x32_bf16 v[58:61], v[152:155], v[208:211], v[58:61]
	v_mfma_f32_16x16x32_bf16 v[54:57], v[144:147], v[216:219], v[54:57]
	v_mfma_f32_16x16x32_bf16 v[50:53], v[152:155], v[216:219], v[50:53]
	v_mfma_f32_16x16x32_bf16 v[38:41], v[144:147], v[224:227], v[38:41]
	v_mfma_f32_16x16x32_bf16 v[34:37], v[152:155], v[224:227], v[34:37]
	v_mfma_f32_16x16x32_bf16 v[22:25], v[144:147], v[232:235], v[22:25]
	v_mfma_f32_16x16x32_bf16 v[18:21], v[152:155], v[232:235], v[18:21]
	s_setprio 0
	s_setprio 1
	v_mfma_f32_16x16x32_bf16 v[62:65], v[148:151], v[212:215], v[62:65]
	v_mfma_f32_16x16x32_bf16 v[58:61], v[158:161], v[212:215], v[58:61]
	v_mfma_f32_16x16x32_bf16 v[54:57], v[148:151], v[220:223], v[54:57]
	v_mfma_f32_16x16x32_bf16 v[50:53], v[158:161], v[220:223], v[50:53]
	v_mfma_f32_16x16x32_bf16 v[38:41], v[148:151], v[228:231], v[38:41]
	v_mfma_f32_16x16x32_bf16 v[34:37], v[158:161], v[228:231], v[34:37]
	v_mfma_f32_16x16x32_bf16 v[22:25], v[148:151], v[236:239], v[22:25]
	v_mfma_f32_16x16x32_bf16 v[18:21], v[158:161], v[236:239], v[18:21]
	s_setprio 0
	s_setprio 1
	v_mfma_f32_16x16x32_bf16 v[46:49], v[162:165], v[208:211], v[46:49]
	v_mfma_f32_16x16x32_bf16 v[42:45], v[200:203], v[208:211], v[42:45]
	v_mfma_f32_16x16x32_bf16 v[30:33], v[162:165], v[216:219], v[30:33]
	v_mfma_f32_16x16x32_bf16 v[26:29], v[200:203], v[216:219], v[26:29]
	v_mfma_f32_16x16x32_bf16 v[14:17], v[162:165], v[224:227], v[14:17]
	v_mfma_f32_16x16x32_bf16 v[10:13], v[200:203], v[224:227], v[10:13]
	v_mfma_f32_16x16x32_bf16 v[6:9], v[162:165], v[232:235], v[6:9]
	v_mfma_f32_16x16x32_bf16 v[2:5], v[200:203], v[232:235], v[2:5]
	s_setprio 0
	s_setprio 1
	v_mfma_f32_16x16x32_bf16 v[46:49], v[196:199], v[212:215], v[46:49]
	v_mfma_f32_16x16x32_bf16 v[42:45], v[204:207], v[212:215], v[42:45]
	v_mfma_f32_16x16x32_bf16 v[30:33], v[196:199], v[220:223], v[30:33]
	v_mfma_f32_16x16x32_bf16 v[26:29], v[204:207], v[220:223], v[26:29]
	v_mfma_f32_16x16x32_bf16 v[14:17], v[196:199], v[228:231], v[14:17]
	v_mfma_f32_16x16x32_bf16 v[10:13], v[204:207], v[228:231], v[10:13]
	v_mfma_f32_16x16x32_bf16 v[6:9], v[196:199], v[236:239], v[6:9]
	v_mfma_f32_16x16x32_bf16 v[2:5], v[204:207], v[236:239], v[2:5]
	s_setprio 0
	s_barrier
	s_add_i32 s58, s58, 2
	s_add_u32 s94, s94, 0x100
	s_addc_u32 s95, s95, 0
	s_cmp_gt_u32 s58, 13
	s_cbranch_scc0 .LBB0_81
	s_waitcnt vmcnt(0)
	s_cmpk_lt_u32 s1, 0x100
	s_cbranch_scc0 .LBB0_84
	s_barrier

.LBB0_173:
	s_add_u32 s20, s18, 0xf5678080
	s_addc_u32 s40, s19, -1
	s_cmp_lg_u32 s47, 12
	s_cselect_b32 s20, s20, 0
	s_cselect_b32 s41, s40, 0
	s_add_u32 s42, s2, s20
	s_addc_u32 s43, s3, s41
	s_add_i32 s52, 0, 0x10000
	s_add_u32 s40, s8, s20
	v_add_u32_e32 v143, s52, v141
	s_addc_u32 s41, s9, s41
	s_add_i32 s20, 0, 0x14000
	ds_read_b128 v[144:147], v143
	ds_read_b128 v[148:151], v143 offset:1024
	ds_read_b128 v[152:155], v143 offset:2048
	ds_read_b128 v[158:161], v143 offset:3072
	v_add_u32_e32 v143, s20, v141
	ds_read_b128 v[162:165], v143
	ds_read_b128 v[196:199], v143 offset:1024
	ds_read_b128 v[200:203], v143 offset:2048
	ds_read_b128 v[204:207], v143 offset:3072
	v_lshl_add_u64 v[176:177], v[138:139], 0, s[18:19]
	s_add_i32 m0, s12, 0xc000
	ds_read_b128 v[208:211], v142
	ds_read_b128 v[212:215], v142 offset:1024
	ds_read_b128 v[216:219], v142 offset:2048
	ds_read_b128 v[220:223], v142 offset:3072
	ds_read_b128 v[224:227], v142 offset:4096
	ds_read_b128 v[228:231], v142 offset:5120
	ds_read_b128 v[232:235], v142 offset:6144
	ds_read_b128 v[236:239], v142 offset:7168
	global_load_lds_dwordx4 v[176:177], off
	v_lshl_add_u64 v[176:177], v[136:137], 0, s[18:19]
	s_add_i32 m0, s12, 0xe000
	s_nop 0
	global_load_lds_dwordx4 v[176:177], off
	s_waitcnt vmcnt(8)
	s_waitcnt lgkmcnt(0)
	s_setprio 1
	s_barrier
	s_waitcnt lgkmcnt(0)
	v_mfma_f32_16x16x32_bf16 v[126:129], v[144:147], v[208:211], v[126:129]
	v_mfma_f32_16x16x32_bf16 v[122:125], v[152:155], v[208:211], v[122:125]
	v_mfma_f32_16x16x32_bf16 v[118:121], v[144:147], v[216:219], v[118:121]
	v_mfma_f32_16x16x32_bf16 v[114:117], v[152:155], v[216:219], v[114:117]
	v_mfma_f32_16x16x32_bf16 v[102:105], v[144:147], v[224:227], v[102:105]
	v_mfma_f32_16x16x32_bf16 v[98:101], v[152:155], v[224:227], v[98:101]
	v_mfma_f32_16x16x32_bf16 v[86:89], v[144:147], v[232:235], v[86:89]
	v_mfma_f32_16x16x32_bf16 v[82:85], v[152:155], v[232:235], v[82:85]
	s_setprio 0
	s_setprio 1
	v_mfma_f32_16x16x32_bf16 v[126:129], v[148:151], v[212:215], v[126:129]
	v_mfma_f32_16x16x32_bf16 v[122:125], v[158:161], v[212:215], v[122:125]
	v_mfma_f32_16x16x32_bf16 v[118:121], v[148:151], v[220:223], v[118:121]
	v_mfma_f32_16x16x32_bf16 v[114:117], v[158:161], v[220:223], v[114:117]
	v_mfma_f32_16x16x32_bf16 v[102:105], v[148:151], v[228:231], v[102:105]
	v_mfma_f32_16x16x32_bf16 v[98:101], v[158:161], v[228:231], v[98:101]
	v_mfma_f32_16x16x32_bf16 v[86:89], v[148:151], v[236:239], v[86:89]
	v_mfma_f32_16x16x32_bf16 v[82:85], v[158:161], v[236:239], v[82:85]
	s_setprio 0
	s_setprio 1
	v_mfma_f32_16x16x32_bf16 v[110:113], v[162:165], v[208:211], v[110:113]
	v_mfma_f32_16x16x32_bf16 v[106:109], v[200:203], v[208:211], v[106:109]
	v_mfma_f32_16x16x32_bf16 v[94:97], v[162:165], v[216:219], v[94:97]
	v_mfma_f32_16x16x32_bf16 v[90:93], v[200:203], v[216:219], v[90:93]
	v_mfma_f32_16x16x32_bf16 v[78:81], v[162:165], v[224:227], v[78:81]
	v_mfma_f32_16x16x32_bf16 v[74:77], v[200:203], v[224:227], v[74:77]
	v_mfma_f32_16x16x32_bf16 v[70:73], v[162:165], v[232:235], v[70:73]
	v_mfma_f32_16x16x32_bf16 v[66:69], v[200:203], v[232:235], v[66:69]
	s_setprio 0
	s_setprio 1
	v_mfma_f32_16x16x32_bf16 v[110:113], v[196:199], v[212:215], v[110:113]
	v_mfma_f32_16x16x32_bf16 v[106:109], v[204:207], v[212:215], v[106:109]
	v_mfma_f32_16x16x32_bf16 v[94:97], v[196:199], v[220:223], v[94:97]
	v_mfma_f32_16x16x32_bf16 v[90:93], v[204:207], v[220:223], v[90:93]
	v_mfma_f32_16x16x32_bf16 v[78:81], v[196:199], v[228:231], v[78:81]
	v_mfma_f32_16x16x32_bf16 v[74:77], v[204:207], v[228:231], v[74:77]
	v_mfma_f32_16x16x32_bf16 v[70:73], v[196:199], v[236:239], v[70:73]
	v_mfma_f32_16x16x32_bf16 v[66:69], v[204:207], v[236:239], v[66:69]
	s_setprio 0
	s_barrier
	s_add_i32 s52, s52, s11
	v_lshl_add_u64 v[176:177], s[40:41], 0, v[0:1]
	s_mov_b32 m0, s52
	ds_read_b128 v[208:211], v142 offset:16384
	ds_read_b128 v[212:215], v142 offset:17408
	ds_read_b128 v[216:219], v142 offset:18432
	ds_read_b128 v[220:223], v142 offset:19456
	ds_read_b128 v[224:227], v142 offset:20480
	ds_read_b128 v[228:231], v142 offset:21504
	ds_read_b128 v[232:235], v142 offset:22528
	ds_read_b128 v[236:239], v142 offset:23552
	global_load_lds_dwordx4 v[176:177], off
	s_add_i32 m0, s52, 0x2000
	s_add_u32 s52, s40, 0x40000
	v_lshl_add_u64 v[178:179], s[40:41], 0, v[134:135]
	s_addc_u32 s53, s41, 0
	s_add_i32 s20, s20, s11
	global_load_lds_dwordx4 v[178:179], off
	v_lshl_add_u64 v[194:195], s[52:53], 0, v[0:1]
	s_mov_b32 m0, s20
	v_lshl_add_u64 v[240:241], s[42:43], 0, v[132:133]
	global_load_lds_dwordx4 v[194:195], off
	v_lshl_add_u64 v[194:195], s[52:53], 0, v[134:135]
	s_add_i32 m0, s20, 0x2000
	s_nop 0
	global_load_lds_dwordx4 v[194:195], off
	v_lshl_add_u64 v[194:195], s[42:43], 0, v[130:131]
	s_mov_b32 m0, s12
	s_nop 0
	global_load_lds_dwordx4 v[194:195], off
	s_mov_b32 m0, s13
	s_nop 0
	global_load_lds_dwordx4 v[240:241], off
	s_waitcnt vmcnt(8)
	s_waitcnt lgkmcnt(0)
	s_setprio 1
	s_barrier
	s_waitcnt lgkmcnt(0)
	v_mfma_f32_16x16x32_bf16 v[62:65], v[144:147], v[208:211], v[62:65]
	v_mfma_f32_16x16x32_bf16 v[58:61], v[152:155], v[208:211], v[58:61]
	v_mfma_f32_16x16x32_bf16 v[54:57], v[144:147], v[216:219], v[54:57]
	v_mfma_f32_16x16x32_bf16 v[50:53], v[152:155], v[216:219], v[50:53]
	v_mfma_f32_16x16x32_bf16 v[38:41], v[144:147], v[224:227], v[38:41]
	v_mfma_f32_16x16x32_bf16 v[34:37], v[152:155], v[224:227], v[34:37]
	v_mfma_f32_16x16x32_bf16 v[22:25], v[144:147], v[232:235], v[22:25]
	v_mfma_f32_16x16x32_bf16 v[18:21], v[152:155], v[232:235], v[18:21]
	s_setprio 0
	s_setprio 1
	v_mfma_f32_16x16x32_bf16 v[62:65], v[148:151], v[212:215], v[62:65]
	v_mfma_f32_16x16x32_bf16 v[58:61], v[158:161], v[212:215], v[58:61]
	v_mfma_f32_16x16x32_bf16 v[54:57], v[148:151], v[220:223], v[54:57]
	v_mfma_f32_16x16x32_bf16 v[50:53], v[158:161], v[220:223], v[50:53]
	v_mfma_f32_16x16x32_bf16 v[38:41], v[148:151], v[228:231], v[38:41]
	v_mfma_f32_16x16x32_bf16 v[34:37], v[158:161], v[228:231], v[34:37]
	v_mfma_f32_16x16x32_bf16 v[22:25], v[148:151], v[236:239], v[22:25]
	v_mfma_f32_16x16x32_bf16 v[18:21], v[158:161], v[236:239], v[18:21]
	s_setprio 0
	s_setprio 1
	v_mfma_f32_16x16x32_bf16 v[46:49], v[162:165], v[208:211], v[46:49]
	v_mfma_f32_16x16x32_bf16 v[42:45], v[200:203], v[208:211], v[42:45]
	v_mfma_f32_16x16x32_bf16 v[30:33], v[162:165], v[216:219], v[30:33]
	v_mfma_f32_16x16x32_bf16 v[26:29], v[200:203], v[216:219], v[26:29]
	v_mfma_f32_16x16x32_bf16 v[14:17], v[162:165], v[224:227], v[14:17]
	v_mfma_f32_16x16x32_bf16 v[10:13], v[200:203], v[224:227], v[10:13]
	v_mfma_f32_16x16x32_bf16 v[6:9], v[162:165], v[232:235], v[6:9]
	v_mfma_f32_16x16x32_bf16 v[2:5], v[200:203], v[232:235], v[2:5]
	s_setprio 0
	s_setprio 1
	v_mfma_f32_16x16x32_bf16 v[46:49], v[196:199], v[212:215], v[46:49]
	v_mfma_f32_16x16x32_bf16 v[42:45], v[204:207], v[212:215], v[42:45]
	v_mfma_f32_16x16x32_bf16 v[30:33], v[196:199], v[220:223], v[30:33]
	v_mfma_f32_16x16x32_bf16 v[26:29], v[204:207], v[220:223], v[26:29]
	v_mfma_f32_16x16x32_bf16 v[14:17], v[196:199], v[228:231], v[14:17]
	v_mfma_f32_16x16x32_bf16 v[10:13], v[204:207], v[228:231], v[10:13]
	v_mfma_f32_16x16x32_bf16 v[6:9], v[196:199], v[236:239], v[6:9]
	v_mfma_f32_16x16x32_bf16 v[2:5], v[204:207], v[236:239], v[2:5]
	s_setprio 0
	s_barrier
	s_add_i32 s20, 0, 0x18000
	v_add_u32_e32 v143, s20, v141
	s_add_i32 s52, 0, 0x1c000
	ds_read_b128 v[144:147], v143
	ds_read_b128 v[148:151], v143 offset:1024
	ds_read_b128 v[152:155], v143 offset:2048
	ds_read_b128 v[158:161], v143 offset:3072
	v_add_u32_e32 v143, s52, v141
	ds_read_b128 v[162:165], v143
	ds_read_b128 v[196:199], v143 offset:1024
	ds_read_b128 v[200:203], v143 offset:2048
	ds_read_b128 v[204:207], v143 offset:3072
	s_add_u32 s42, s42, 0x40000
	s_addc_u32 s43, s43, 0
	s_mov_b32 m0, s16
	v_lshl_add_u64 v[242:243], s[42:43], 0, v[130:131]
	ds_read_b128 v[208:211], v142 offset:32768
	ds_read_b128 v[212:215], v142 offset:33792
	ds_read_b128 v[216:219], v142 offset:34816
	ds_read_b128 v[220:223], v142 offset:35840
	ds_read_b128 v[224:227], v142 offset:36864
	ds_read_b128 v[228:231], v142 offset:37888
	ds_read_b128 v[232:235], v142 offset:38912
	ds_read_b128 v[236:239], v142 offset:39936
	global_load_lds_dwordx4 v[242:243], off
	v_lshl_add_u64 v[242:243], s[42:43], 0, v[132:133]
	s_mov_b32 m0, s17
	s_nop 0
	global_load_lds_dwordx4 v[242:243], off
	s_waitcnt vmcnt(8)
	s_waitcnt lgkmcnt(0)
	s_setprio 1
	s_barrier
	s_waitcnt lgkmcnt(0)
	v_mfma_f32_16x16x32_bf16 v[126:129], v[144:147], v[208:211], v[126:129]
	v_mfma_f32_16x16x32_bf16 v[122:125], v[152:155], v[208:211], v[122:125]
	v_mfma_f32_16x16x32_bf16 v[118:121], v[144:147], v[216:219], v[118:121]
	v_mfma_f32_16x16x32_bf16 v[114:117], v[152:155], v[216:219], v[114:117]
	v_mfma_f32_16x16x32_bf16 v[102:105], v[144:147], v[224:227], v[102:105]
	v_mfma_f32_16x16x32_bf16 v[98:101], v[152:155], v[224:227], v[98:101]
	v_mfma_f32_16x16x32_bf16 v[86:89], v[144:147], v[232:235], v[86:89]
	v_mfma_f32_16x16x32_bf16 v[82:85], v[152:155], v[232:235], v[82:85]
	s_setprio 0
	s_setprio 1
	v_mfma_f32_16x16x32_bf16 v[126:129], v[148:151], v[212:215], v[126:129]
	v_mfma_f32_16x16x32_bf16 v[122:125], v[158:161], v[212:215], v[122:125]
	v_mfma_f32_16x16x32_bf16 v[118:121], v[148:151], v[220:223], v[118:121]
	v_mfma_f32_16x16x32_bf16 v[114:117], v[158:161], v[220:223], v[114:117]
	v_mfma_f32_16x16x32_bf16 v[102:105], v[148:151], v[228:231], v[102:105]
	v_mfma_f32_16x16x32_bf16 v[98:101], v[158:161], v[228:231], v[98:101]
	v_mfma_f32_16x16x32_bf16 v[86:89], v[148:151], v[236:239], v[86:89]
	v_mfma_f32_16x16x32_bf16 v[82:85], v[158:161], v[236:239], v[82:85]
	s_setprio 0
	s_setprio 1
	v_mfma_f32_16x16x32_bf16 v[110:113], v[162:165], v[208:211], v[110:113]
	v_mfma_f32_16x16x32_bf16 v[106:109], v[200:203], v[208:211], v[106:109]
	v_mfma_f32_16x16x32_bf16 v[94:97], v[162:165], v[216:219], v[94:97]
	v_mfma_f32_16x16x32_bf16 v[90:93], v[200:203], v[216:219], v[90:93]
	v_mfma_f32_16x16x32_bf16 v[78:81], v[162:165], v[224:227], v[78:81]
	v_mfma_f32_16x16x32_bf16 v[74:77], v[200:203], v[224:227], v[74:77]
	v_mfma_f32_16x16x32_bf16 v[70:73], v[162:165], v[232:235], v[70:73]
	v_mfma_f32_16x16x32_bf16 v[66:69], v[200:203], v[232:235], v[66:69]
	s_setprio 0
	s_setprio 1
	v_mfma_f32_16x16x32_bf16 v[110:113], v[196:199], v[212:215], v[110:113]
	v_mfma_f32_16x16x32_bf16 v[106:109], v[204:207], v[212:215], v[106:109]
	v_mfma_f32_16x16x32_bf16 v[94:97], v[196:199], v[220:223], v[94:97]
	v_mfma_f32_16x16x32_bf16 v[90:93], v[204:207], v[220:223], v[90:93]
	v_mfma_f32_16x16x32_bf16 v[78:81], v[196:199], v[228:231], v[78:81]
	v_mfma_f32_16x16x32_bf16 v[74:77], v[204:207], v[228:231], v[74:77]
	v_mfma_f32_16x16x32_bf16 v[70:73], v[196:199], v[236:239], v[70:73]
	v_mfma_f32_16x16x32_bf16 v[66:69], v[204:207], v[236:239], v[66:69]
	s_setprio 0
	s_barrier
	s_add_i32 s20, s20, s11
	v_lshl_add_u64 v[176:177], v[176:177], 0, s[24:25]
	s_mov_b32 m0, s20
	ds_read_b128 v[208:211], v142 offset:49152
	ds_read_b128 v[212:215], v142 offset:50176
	ds_read_b128 v[216:219], v142 offset:51200
	ds_read_b128 v[220:223], v142 offset:52224
	ds_read_b128 v[224:227], v142 offset:53248
	ds_read_b128 v[228:231], v142 offset:54272
	ds_read_b128 v[232:235], v142 offset:55296
	ds_read_b128 v[236:239], v142 offset:56320
	global_load_lds_dwordx4 v[176:177], off
	s_add_i32 m0, s20, 0x2000
	s_add_u32 s40, s40, 0x40080
	v_lshl_add_u64 v[176:177], v[178:179], 0, s[24:25]
	s_addc_u32 s41, s41, 0
	s_add_i32 s20, s52, s11
	global_load_lds_dwordx4 v[176:177], off
	v_lshl_add_u64 v[176:177], s[40:41], 0, v[0:1]
	s_mov_b32 m0, s20
	s_nop 0
	global_load_lds_dwordx4 v[176:177], off
	v_lshl_add_u64 v[176:177], s[40:41], 0, v[134:135]
	s_add_i32 m0, s20, 0x2000
	s_nop 0
	global_load_lds_dwordx4 v[176:177], off
	v_lshl_add_u64 v[176:177], v[194:195], 0, s[24:25]
	s_mov_b32 m0, s28
	s_nop 0
	global_load_lds_dwordx4 v[176:177], off
	v_lshl_add_u64 v[176:177], v[240:241], 0, s[24:25]
	s_mov_b32 m0, s46
	s_nop 0
	global_load_lds_dwordx4 v[176:177], off
	s_waitcnt vmcnt(8)
	s_waitcnt lgkmcnt(0)
	s_setprio 1
	s_barrier
	s_waitcnt lgkmcnt(0)
	v_mfma_f32_16x16x32_bf16 v[62:65], v[144:147], v[208:211], v[62:65]
	v_mfma_f32_16x16x32_bf16 v[58:61], v[152:155], v[208:211], v[58:61]
	v_mfma_f32_16x16x32_bf16 v[54:57], v[144:147], v[216:219], v[54:57]
	v_mfma_f32_16x16x32_bf16 v[50:53], v[152:155], v[216:219], v[50:53]
	v_mfma_f32_16x16x32_bf16 v[38:41], v[144:147], v[224:227], v[38:41]
	v_mfma_f32_16x16x32_bf16 v[34:37], v[152:155], v[224:227], v[34:37]
	v_mfma_f32_16x16x32_bf16 v[22:25], v[144:147], v[232:235], v[22:25]
	v_mfma_f32_16x16x32_bf16 v[18:21], v[152:155], v[232:235], v[18:21]
	s_setprio 0
	s_setprio 1
	v_mfma_f32_16x16x32_bf16 v[62:65], v[148:151], v[212:215], v[62:65]
	v_mfma_f32_16x16x32_bf16 v[58:61], v[158:161], v[212:215], v[58:61]
	v_mfma_f32_16x16x32_bf16 v[54:57], v[148:151], v[220:223], v[54:57]
	v_mfma_f32_16x16x32_bf16 v[50:53], v[158:161], v[220:223], v[50:53]
	v_mfma_f32_16x16x32_bf16 v[38:41], v[148:151], v[228:231], v[38:41]
	v_mfma_f32_16x16x32_bf16 v[34:37], v[158:161], v[228:231], v[34:37]
	v_mfma_f32_16x16x32_bf16 v[22:25], v[148:151], v[236:239], v[22:25]
	v_mfma_f32_16x16x32_bf16 v[18:21], v[158:161], v[236:239], v[18:21]
	s_setprio 0
	s_setprio 1
	v_mfma_f32_16x16x32_bf16 v[46:49], v[162:165], v[208:211], v[46:49]
	v_mfma_f32_16x16x32_bf16 v[42:45], v[200:203], v[208:211], v[42:45]
	v_mfma_f32_16x16x32_bf16 v[30:33], v[162:165], v[216:219], v[30:33]
	v_mfma_f32_16x16x32_bf16 v[26:29], v[200:203], v[216:219], v[26:29]
	v_mfma_f32_16x16x32_bf16 v[14:17], v[162:165], v[224:227], v[14:17]
	v_mfma_f32_16x16x32_bf16 v[10:13], v[200:203], v[224:227], v[10:13]
	v_mfma_f32_16x16x32_bf16 v[6:9], v[162:165], v[232:235], v[6:9]
	v_mfma_f32_16x16x32_bf16 v[2:5], v[200:203], v[232:235], v[2:5]
	s_setprio 0
	s_setprio 1
	v_mfma_f32_16x16x32_bf16 v[46:49], v[196:199], v[212:215], v[46:49]
	v_mfma_f32_16x16x32_bf16 v[42:45], v[204:207], v[212:215], v[42:45]
	v_mfma_f32_16x16x32_bf16 v[30:33], v[196:199], v[220:223], v[30:33]
	v_mfma_f32_16x16x32_bf16 v[26:29], v[204:207], v[220:223], v[26:29]
	v_mfma_f32_16x16x32_bf16 v[14:17], v[196:199], v[228:231], v[14:17]
	v_mfma_f32_16x16x32_bf16 v[10:13], v[204:207], v[228:231], v[10:13]
	v_mfma_f32_16x16x32_bf16 v[6:9], v[196:199], v[236:239], v[6:9]
	v_mfma_f32_16x16x32_bf16 v[2:5], v[204:207], v[236:239], v[2:5]
	s_setprio 0
	s_barrier
	s_add_i32 s47, s47, 2
	s_add_u32 s18, s18, 0x100
	s_addc_u32 s19, s19, 0
	s_cmp_gt_u32 s47, 13
	s_cbranch_scc0 .LBB0_173
	s_waitcnt vmcnt(0)
	s_cmpk_lt_u32 s1, 0x100
	s_cbranch_scc0 .LBB0_169
	s_barrier
	s_branch .LBB0_169

.LBB0_336:
	s_add_u32 s20, s12, s56
	s_addc_u32 s58, s13, s57
	s_cmpk_eq_i32 s56, 0x700
	s_cselect_b64 s[6:7], -1, 0
	s_and_b64 s[10:11], s[6:7], exec
	s_cselect_b32 s62, vcc_lo, s20
	s_cselect_b32 s63, s97, s58
	s_and_b64 s[66:67], s[2:3], s[6:7]
	s_and_b64 s[6:7], s[66:67], exec
	s_cselect_b32 s10, s86, s40
	s_add_u32 s6, s16, s56
	s_addc_u32 s7, s17, s57
	s_add_u32 s11, s6, 0x3148100
	s_addc_u32 s20, s7, 0
	s_cmpk_eq_i32 s56, 0x700
	s_cselect_b64 s[6:7], -1, 0
	s_and_b64 s[6:7], s[6:7], exec
	s_cselect_b32 s58, s10, s11
	s_and_b64 s[6:7], s[66:67], exec
	s_cselect_b32 s10, s93, s41
	s_cmpk_eq_i32 s56, 0x700
	s_cselect_b64 s[84:85], -1, 0
	s_and_b64 s[6:7], s[84:85], exec
	s_cselect_b32 s59, s10, s20
	s_and_b64 s[6:7], s[66:67], exec
	s_mov_b32 s6, 0x20000
	s_cselect_b32 s66, s6, 0x40000
	s_cselect_b32 s10, 9, 10
	s_add_i32 s6, 0, 0x10000
	v_add_u32_e32 v154, s6, v143
	s_add_i32 s7, 0, 0x14000
	ds_read_b128 v[146:149], v154
	ds_read_b128 v[150:153], v154 offset:1024
	ds_read_b128 v[158:161], v154 offset:2048
	ds_read_b128 v[162:165], v154 offset:3072
	v_add_u32_e32 v154, s7, v143
	ds_read_b128 v[196:199], v154
	ds_read_b128 v[200:203], v154 offset:1024
	ds_read_b128 v[204:207], v154 offset:2048
	ds_read_b128 v[208:211], v154 offset:3072
	v_lshlrev_b32_e32 v0, s10, v134
	v_lshlrev_b32_e32 v145, s10, v136
	v_lshlrev_b32_e32 v155, s10, v138
	v_lshlrev_b32_e32 v157, s10, v139
	v_add_lshl_u32 v154, v0, v135, 1
	v_add_lshl_u32 v0, v155, v135, 1
	v_add_lshl_u32 v244, v145, v137, 1
	s_add_i32 s20, s87, 0
	v_lshl_add_u64 v[246:247], v[132:133], 0, s[56:57]
	s_add_i32 m0, s20, 0xc000
	ds_read_b128 v[212:215], v144
	ds_read_b128 v[216:219], v144 offset:1024
	ds_read_b128 v[220:223], v144 offset:2048
	ds_read_b128 v[224:227], v144 offset:3072
	ds_read_b128 v[228:231], v144 offset:4096
	ds_read_b128 v[232:235], v144 offset:5120
	ds_read_b128 v[236:239], v144 offset:6144
	ds_read_b128 v[240:243], v144 offset:7168
	global_load_lds_dwordx4 v[246:247], off
	v_lshl_add_u64 v[246:247], v[130:131], 0, s[56:57]
	s_add_i32 m0, s20, 0xe000
	s_nop 0
	global_load_lds_dwordx4 v[246:247], off
	s_waitcnt vmcnt(8)
	s_waitcnt lgkmcnt(0)
	s_setprio 1
	s_barrier
	s_waitcnt lgkmcnt(0)
	v_mfma_f32_16x16x32_bf16 v[126:129], v[146:149], v[212:215], v[126:129]
	v_mfma_f32_16x16x32_bf16 v[122:125], v[158:161], v[212:215], v[122:125]
	v_mfma_f32_16x16x32_bf16 v[110:113], v[146:149], v[220:223], v[110:113]
	v_mfma_f32_16x16x32_bf16 v[106:109], v[158:161], v[220:223], v[106:109]
	v_mfma_f32_16x16x32_bf16 v[94:97], v[146:149], v[228:231], v[94:97]
	v_mfma_f32_16x16x32_bf16 v[90:93], v[158:161], v[228:231], v[90:93]
	v_mfma_f32_16x16x32_bf16 v[78:81], v[146:149], v[236:239], v[78:81]
	v_mfma_f32_16x16x32_bf16 v[74:77], v[158:161], v[236:239], v[74:77]
	s_setprio 0
	s_setprio 1
	v_mfma_f32_16x16x32_bf16 v[126:129], v[150:153], v[216:219], v[126:129]
	v_mfma_f32_16x16x32_bf16 v[122:125], v[162:165], v[216:219], v[122:125]
	v_mfma_f32_16x16x32_bf16 v[110:113], v[150:153], v[224:227], v[110:113]
	v_mfma_f32_16x16x32_bf16 v[106:109], v[162:165], v[224:227], v[106:109]
	v_mfma_f32_16x16x32_bf16 v[94:97], v[150:153], v[232:235], v[94:97]
	v_mfma_f32_16x16x32_bf16 v[90:93], v[162:165], v[232:235], v[90:93]
	v_mfma_f32_16x16x32_bf16 v[78:81], v[150:153], v[240:243], v[78:81]
	v_mfma_f32_16x16x32_bf16 v[74:77], v[162:165], v[240:243], v[74:77]
	s_setprio 0
	s_setprio 1
	v_mfma_f32_16x16x32_bf16 v[118:121], v[196:199], v[212:215], v[118:121]
	v_mfma_f32_16x16x32_bf16 v[114:117], v[204:207], v[212:215], v[114:117]
	v_mfma_f32_16x16x32_bf16 v[102:105], v[196:199], v[220:223], v[102:105]
	v_mfma_f32_16x16x32_bf16 v[98:101], v[204:207], v[220:223], v[98:101]
	v_mfma_f32_16x16x32_bf16 v[86:89], v[196:199], v[228:231], v[86:89]
	v_mfma_f32_16x16x32_bf16 v[82:85], v[204:207], v[228:231], v[82:85]
	v_mfma_f32_16x16x32_bf16 v[70:73], v[196:199], v[236:239], v[70:73]
	v_mfma_f32_16x16x32_bf16 v[66:69], v[204:207], v[236:239], v[66:69]
	s_setprio 0
	s_setprio 1
	v_mfma_f32_16x16x32_bf16 v[118:121], v[200:203], v[216:219], v[118:121]
	v_mfma_f32_16x16x32_bf16 v[114:117], v[208:211], v[216:219], v[114:117]
	v_mfma_f32_16x16x32_bf16 v[102:105], v[200:203], v[224:227], v[102:105]
	v_mfma_f32_16x16x32_bf16 v[98:101], v[208:211], v[224:227], v[98:101]
	v_mfma_f32_16x16x32_bf16 v[86:89], v[200:203], v[232:235], v[86:89]
	v_mfma_f32_16x16x32_bf16 v[82:85], v[208:211], v[232:235], v[82:85]
	v_mfma_f32_16x16x32_bf16 v[70:73], v[200:203], v[240:243], v[70:73]
	v_mfma_f32_16x16x32_bf16 v[66:69], v[208:211], v[240:243], v[66:69]
	s_setprio 0
	s_barrier
	s_add_i32 s10, s6, s87
	s_mov_b32 m0, s10
	ds_read_b128 v[212:215], v144 offset:16384
	ds_read_b128 v[216:219], v144 offset:17408
	ds_read_b128 v[220:223], v144 offset:18432
	ds_read_b128 v[224:227], v144 offset:19456
	ds_read_b128 v[228:231], v144 offset:20480
	ds_read_b128 v[232:235], v144 offset:21504
	ds_read_b128 v[236:239], v144 offset:22528
	ds_read_b128 v[240:243], v144 offset:23552
	global_load_lds_dwordx4 v0, s[62:63]
	s_add_i32 m0, s10, 0x2000
	v_add_lshl_u32 v246, v157, v137, 1
	v_mov_b32_e32 v247, v1
	s_add_u32 s10, s62, s66
	v_lshl_add_u64 v[248:249], s[62:63], 0, v[0:1]
	v_lshl_add_u64 v[250:251], s[62:63], 0, v[246:247]
	global_load_lds_dwordx4 v246, s[62:63]
	s_addc_u32 s11, s63, 0
	s_add_i32 s62, s7, s87
	s_mov_b32 m0, s62
	v_mov_b32_e32 v155, v1
	global_load_lds_dwordx4 v0, s[10:11]
	s_add_i32 m0, s62, 0x2000
	v_mov_b32_e32 v245, v1
	global_load_lds_dwordx4 v246, s[10:11]
	s_mov_b32 m0, s20
	v_lshl_add_u64 v[194:195], s[10:11], 0, v[0:1]
	global_load_lds_dwordx4 v154, s[58:59]
	s_add_i32 m0, s20, 0x2000
	v_lshl_add_u64 v[176:177], s[10:11], 0, v[246:247]
	global_load_lds_dwordx4 v244, s[58:59]
	s_waitcnt vmcnt(8)
	s_waitcnt lgkmcnt(0)
	v_lshl_add_u64 v[246:247], s[58:59], 0, v[154:155]
	v_lshl_add_u64 v[178:179], s[58:59], 0, v[244:245]
	s_setprio 1
	s_barrier
	s_waitcnt lgkmcnt(0)
	v_mfma_f32_16x16x32_bf16 v[62:65], v[146:149], v[212:215], v[62:65]
	v_mfma_f32_16x16x32_bf16 v[58:61], v[158:161], v[212:215], v[58:61]
	v_mfma_f32_16x16x32_bf16 v[46:49], v[146:149], v[220:223], v[46:49]
	v_mfma_f32_16x16x32_bf16 v[42:45], v[158:161], v[220:223], v[42:45]
	v_mfma_f32_16x16x32_bf16 v[30:33], v[146:149], v[228:231], v[30:33]
	v_mfma_f32_16x16x32_bf16 v[26:29], v[158:161], v[228:231], v[26:29]
	v_mfma_f32_16x16x32_bf16 v[14:17], v[146:149], v[236:239], v[14:17]
	v_mfma_f32_16x16x32_bf16 v[10:13], v[158:161], v[236:239], v[10:13]
	s_setprio 0
	s_setprio 1
	v_mfma_f32_16x16x32_bf16 v[62:65], v[150:153], v[216:219], v[62:65]
	v_mfma_f32_16x16x32_bf16 v[58:61], v[162:165], v[216:219], v[58:61]
	v_mfma_f32_16x16x32_bf16 v[46:49], v[150:153], v[224:227], v[46:49]
	v_mfma_f32_16x16x32_bf16 v[42:45], v[162:165], v[224:227], v[42:45]
	v_mfma_f32_16x16x32_bf16 v[30:33], v[150:153], v[232:235], v[30:33]
	v_mfma_f32_16x16x32_bf16 v[26:29], v[162:165], v[232:235], v[26:29]
	v_mfma_f32_16x16x32_bf16 v[14:17], v[150:153], v[240:243], v[14:17]
	v_mfma_f32_16x16x32_bf16 v[10:13], v[162:165], v[240:243], v[10:13]
	s_setprio 0
	s_setprio 1
	v_mfma_f32_16x16x32_bf16 v[54:57], v[196:199], v[212:215], v[54:57]
	v_mfma_f32_16x16x32_bf16 v[50:53], v[204:207], v[212:215], v[50:53]
	v_mfma_f32_16x16x32_bf16 v[38:41], v[196:199], v[220:223], v[38:41]
	v_mfma_f32_16x16x32_bf16 v[34:37], v[204:207], v[220:223], v[34:37]
	v_mfma_f32_16x16x32_bf16 v[22:25], v[196:199], v[228:231], v[22:25]
	v_mfma_f32_16x16x32_bf16 v[18:21], v[204:207], v[228:231], v[18:21]
	v_mfma_f32_16x16x32_bf16 v[6:9], v[196:199], v[236:239], v[6:9]
	v_mfma_f32_16x16x32_bf16 v[2:5], v[204:207], v[236:239], v[2:5]
	s_setprio 0
	s_setprio 1
	v_mfma_f32_16x16x32_bf16 v[54:57], v[200:203], v[216:219], v[54:57]
	v_mfma_f32_16x16x32_bf16 v[50:53], v[208:211], v[216:219], v[50:53]
	v_mfma_f32_16x16x32_bf16 v[38:41], v[200:203], v[224:227], v[38:41]
	v_mfma_f32_16x16x32_bf16 v[34:37], v[208:211], v[224:227], v[34:37]
	v_mfma_f32_16x16x32_bf16 v[22:25], v[200:203], v[232:235], v[22:25]
	v_mfma_f32_16x16x32_bf16 v[18:21], v[208:211], v[232:235], v[18:21]
	v_mfma_f32_16x16x32_bf16 v[6:9], v[200:203], v[240:243], v[6:9]
	v_mfma_f32_16x16x32_bf16 v[2:5], v[208:211], v[240:243], v[2:5]
	s_setprio 0
	s_barrier
	s_add_i32 s10, 0, 0x18000
	v_add_u32_e32 v0, s10, v143
	s_add_i32 s11, 0, 0x1c000
	ds_read_b128 v[146:149], v0
	ds_read_b128 v[150:153], v0 offset:1024
	ds_read_b128 v[158:161], v0 offset:2048
	ds_read_b128 v[162:165], v0 offset:3072
	v_add_u32_e32 v0, s11, v143
	ds_read_b128 v[196:199], v0
	ds_read_b128 v[200:203], v0 offset:1024
	ds_read_b128 v[204:207], v0 offset:2048
	ds_read_b128 v[208:211], v0 offset:3072
	s_add_u32 s58, s58, s66
	s_addc_u32 s59, s59, 0
	s_add_i32 m0, s20, 0x4000
	ds_read_b128 v[212:215], v144 offset:32768
	ds_read_b128 v[216:219], v144 offset:33792
	ds_read_b128 v[220:223], v144 offset:34816
	ds_read_b128 v[224:227], v144 offset:35840
	ds_read_b128 v[228:231], v144 offset:36864
	ds_read_b128 v[232:235], v144 offset:37888
	ds_read_b128 v[236:239], v144 offset:38912
	ds_read_b128 v[240:243], v144 offset:39936
	global_load_lds_dwordx4 v154, s[58:59]
	s_add_i32 m0, s20, 0x6000
	s_nop 0
	global_load_lds_dwordx4 v244, s[58:59]
	s_waitcnt vmcnt(8)
	s_waitcnt lgkmcnt(0)
	s_setprio 1
	s_barrier
	s_waitcnt lgkmcnt(0)
	v_mfma_f32_16x16x32_bf16 v[126:129], v[146:149], v[212:215], v[126:129]
	v_mfma_f32_16x16x32_bf16 v[122:125], v[158:161], v[212:215], v[122:125]
	v_mfma_f32_16x16x32_bf16 v[110:113], v[146:149], v[220:223], v[110:113]
	v_mfma_f32_16x16x32_bf16 v[106:109], v[158:161], v[220:223], v[106:109]
	v_mfma_f32_16x16x32_bf16 v[94:97], v[146:149], v[228:231], v[94:97]
	v_mfma_f32_16x16x32_bf16 v[90:93], v[158:161], v[228:231], v[90:93]
	v_mfma_f32_16x16x32_bf16 v[78:81], v[146:149], v[236:239], v[78:81]
	v_mfma_f32_16x16x32_bf16 v[74:77], v[158:161], v[236:239], v[74:77]
	s_setprio 0
	s_setprio 1
	v_mfma_f32_16x16x32_bf16 v[126:129], v[150:153], v[216:219], v[126:129]
	v_mfma_f32_16x16x32_bf16 v[122:125], v[162:165], v[216:219], v[122:125]
	v_mfma_f32_16x16x32_bf16 v[110:113], v[150:153], v[224:227], v[110:113]
	v_mfma_f32_16x16x32_bf16 v[106:109], v[162:165], v[224:227], v[106:109]
	v_mfma_f32_16x16x32_bf16 v[94:97], v[150:153], v[232:235], v[94:97]
	v_mfma_f32_16x16x32_bf16 v[90:93], v[162:165], v[232:235], v[90:93]
	v_mfma_f32_16x16x32_bf16 v[78:81], v[150:153], v[240:243], v[78:81]
	v_mfma_f32_16x16x32_bf16 v[74:77], v[162:165], v[240:243], v[74:77]
	s_setprio 0
	s_setprio 1
	v_mfma_f32_16x16x32_bf16 v[118:121], v[196:199], v[212:215], v[118:121]
	v_mfma_f32_16x16x32_bf16 v[114:117], v[204:207], v[212:215], v[114:117]
	v_mfma_f32_16x16x32_bf16 v[102:105], v[196:199], v[220:223], v[102:105]
	v_mfma_f32_16x16x32_bf16 v[98:101], v[204:207], v[220:223], v[98:101]
	v_mfma_f32_16x16x32_bf16 v[86:89], v[196:199], v[228:231], v[86:89]
	v_mfma_f32_16x16x32_bf16 v[82:85], v[204:207], v[228:231], v[82:85]
	v_mfma_f32_16x16x32_bf16 v[70:73], v[196:199], v[236:239], v[70:73]
	v_mfma_f32_16x16x32_bf16 v[66:69], v[204:207], v[236:239], v[66:69]
	s_setprio 0
	s_setprio 1
	v_mfma_f32_16x16x32_bf16 v[118:121], v[200:203], v[216:219], v[118:121]
	v_mfma_f32_16x16x32_bf16 v[114:117], v[208:211], v[216:219], v[114:117]
	v_mfma_f32_16x16x32_bf16 v[102:105], v[200:203], v[224:227], v[102:105]
	v_mfma_f32_16x16x32_bf16 v[98:101], v[208:211], v[224:227], v[98:101]
	v_mfma_f32_16x16x32_bf16 v[86:89], v[200:203], v[232:235], v[86:89]
	v_mfma_f32_16x16x32_bf16 v[82:85], v[208:211], v[232:235], v[82:85]
	v_mfma_f32_16x16x32_bf16 v[70:73], v[200:203], v[240:243], v[70:73]
	v_mfma_f32_16x16x32_bf16 v[66:69], v[208:211], v[240:243], v[66:69]
	s_setprio 0
	s_barrier
	s_add_i32 s58, s10, s87
	v_lshl_add_u64 v[154:155], v[248:249], 0, s[24:25]
	s_mov_b32 m0, s58
	ds_read_b128 v[212:215], v144 offset:49152
	ds_read_b128 v[216:219], v144 offset:50176
	ds_read_b128 v[220:223], v144 offset:51200
	ds_read_b128 v[224:227], v144 offset:52224
	ds_read_b128 v[228:231], v144 offset:53248
	ds_read_b128 v[232:235], v144 offset:54272
	ds_read_b128 v[236:239], v144 offset:55296
	ds_read_b128 v[240:243], v144 offset:56320
	global_load_lds_dwordx4 v[154:155], off
	v_lshl_add_u64 v[154:155], v[250:251], 0, s[24:25]
	s_add_i32 m0, s58, 0x2000
	s_add_i32 s58, s11, s87
	global_load_lds_dwordx4 v[154:155], off
	v_lshl_add_u64 v[154:155], v[194:195], 0, s[24:25]
	s_mov_b32 m0, s58
	s_nop 0
	global_load_lds_dwordx4 v[154:155], off
	v_lshl_add_u64 v[154:155], v[176:177], 0, s[24:25]
	s_add_i32 m0, s58, 0x2000
	s_nop 0
	global_load_lds_dwordx4 v[154:155], off
	v_lshl_add_u64 v[154:155], v[246:247], 0, s[24:25]
	s_add_i32 m0, s20, 0x8000
	s_nop 0
	global_load_lds_dwordx4 v[154:155], off
	v_lshl_add_u64 v[154:155], v[178:179], 0, s[24:25]
	s_add_i32 m0, s20, 0xa000
	s_nop 0
	global_load_lds_dwordx4 v[154:155], off
	s_waitcnt vmcnt(8)
	s_waitcnt lgkmcnt(0)
	s_setprio 1
	s_barrier
	s_waitcnt lgkmcnt(0)
	v_mfma_f32_16x16x32_bf16 v[62:65], v[146:149], v[212:215], v[62:65]
	v_mfma_f32_16x16x32_bf16 v[58:61], v[158:161], v[212:215], v[58:61]
	v_mfma_f32_16x16x32_bf16 v[46:49], v[146:149], v[220:223], v[46:49]
	v_mfma_f32_16x16x32_bf16 v[42:45], v[158:161], v[220:223], v[42:45]
	v_mfma_f32_16x16x32_bf16 v[30:33], v[146:149], v[228:231], v[30:33]
	v_mfma_f32_16x16x32_bf16 v[26:29], v[158:161], v[228:231], v[26:29]
	v_mfma_f32_16x16x32_bf16 v[14:17], v[146:149], v[236:239], v[14:17]
	v_mfma_f32_16x16x32_bf16 v[10:13], v[158:161], v[236:239], v[10:13]
	s_setprio 0
	s_setprio 1
	v_mfma_f32_16x16x32_bf16 v[62:65], v[150:153], v[216:219], v[62:65]
	v_mfma_f32_16x16x32_bf16 v[58:61], v[162:165], v[216:219], v[58:61]
	v_mfma_f32_16x16x32_bf16 v[46:49], v[150:153], v[224:227], v[46:49]
	v_mfma_f32_16x16x32_bf16 v[42:45], v[162:165], v[224:227], v[42:45]
	v_mfma_f32_16x16x32_bf16 v[30:33], v[150:153], v[232:235], v[30:33]
	v_mfma_f32_16x16x32_bf16 v[26:29], v[162:165], v[232:235], v[26:29]
	v_mfma_f32_16x16x32_bf16 v[14:17], v[150:153], v[240:243], v[14:17]
	v_mfma_f32_16x16x32_bf16 v[10:13], v[162:165], v[240:243], v[10:13]
	s_setprio 0
	s_setprio 1
	v_mfma_f32_16x16x32_bf16 v[54:57], v[196:199], v[212:215], v[54:57]
	v_mfma_f32_16x16x32_bf16 v[50:53], v[204:207], v[212:215], v[50:53]
	v_mfma_f32_16x16x32_bf16 v[38:41], v[196:199], v[220:223], v[38:41]
	v_mfma_f32_16x16x32_bf16 v[34:37], v[204:207], v[220:223], v[34:37]
	v_mfma_f32_16x16x32_bf16 v[22:25], v[196:199], v[228:231], v[22:25]
	v_mfma_f32_16x16x32_bf16 v[18:21], v[204:207], v[228:231], v[18:21]
	v_mfma_f32_16x16x32_bf16 v[6:9], v[196:199], v[236:239], v[6:9]
	v_mfma_f32_16x16x32_bf16 v[2:5], v[204:207], v[236:239], v[2:5]
	s_setprio 0
	s_setprio 1
	v_mfma_f32_16x16x32_bf16 v[54:57], v[200:203], v[216:219], v[54:57]
	v_mfma_f32_16x16x32_bf16 v[50:53], v[208:211], v[216:219], v[50:53]
	v_mfma_f32_16x16x32_bf16 v[38:41], v[200:203], v[224:227], v[38:41]
	v_mfma_f32_16x16x32_bf16 v[34:37], v[208:211], v[224:227], v[34:37]
	v_mfma_f32_16x16x32_bf16 v[22:25], v[200:203], v[232:235], v[22:25]
	v_mfma_f32_16x16x32_bf16 v[18:21], v[208:211], v[232:235], v[18:21]
	v_mfma_f32_16x16x32_bf16 v[6:9], v[200:203], v[240:243], v[6:9]
	v_mfma_f32_16x16x32_bf16 v[2:5], v[208:211], v[240:243], v[2:5]
	s_setprio 0
	s_barrier
	s_add_i32 vcc_hi, vcc_hi, 2
	s_add_u32 s56, s56, 0x100
	s_addc_u32 s57, s57, 0
	s_cmp_lt_u32 vcc_hi, 14
	s_cbranch_scc1 .LBB0_336
	v_mul_f32_e32 v0, 0xbfb8aa3b, v126
	v_exp_f32_e32 v0, v0
	v_mul_f32_e32 v126, 0xbfb8aa3b, v127
	v_exp_f32_e32 v132, v126
	v_mul_f32_e32 v128, 0xbfb8aa3b, v128
	v_exp_f32_e32 v128, v128
	v_lshl_add_u32 v130, s96, 16, v142
	v_mul_f32_e32 v129, 0xbfb8aa3b, v129
	v_add_f32_e32 v0, 1.0, v0
	v_ashrrev_i32_e32 v131, 31, v130
	v_exp_f32_e32 v129, v129
	v_rcp_f32_e32 v0, v0
	v_lshl_add_u64 v[126:127], s[0:1], 0, v[130:131]
	v_add_f32_e32 v130, 1.0, v132
	v_rcp_f32_e32 v130, v130
	v_add_f32_e32 v128, 1.0, v128
	v_rcp_f32_e32 v128, v128
	v_add_f32_e32 v129, 1.0, v129
	v_fma_f32 v0, v0, s21, 0.5
	v_rcp_f32_e32 v129, v129
	v_max_f32_e32 v0, 1.0, v0
	v_fma_f32 v130, v130, s21, 0.5
	v_mul_f32_e32 v122, 0xbfb8aa3b, v122
	v_cvt_pk_u8_f32 v0, v0, 0, 0
	v_max_f32_e32 v130, 1.0, v130
	v_fma_f32 v128, v128, s21, 0.5
	v_exp_f32_e32 v122, v122
	v_mul_f32_e32 v123, 0xbfb8aa3b, v123
	v_cvt_pk_u8_f32 v0, v130, 1, v0
	v_max_f32_e32 v128, 1.0, v128
	v_exp_f32_e32 v123, v123
	v_cvt_pk_u8_f32 v0, v128, 2, v0
	v_fma_f32 v128, v129, s21, 0.5
	v_max_f32_e32 v128, 1.0, v128
	v_cvt_pk_u8_f32 v0, v128, 3, v0
	v_add_f32_e32 v122, 1.0, v122
	v_rcp_f32_e32 v122, v122
	global_store_dword v[126:127], v0, off
	v_add_f32_e32 v0, 1.0, v123
	v_rcp_f32_e32 v0, v0
	v_mul_f32_e32 v123, 0xbfb8aa3b, v124
	v_exp_f32_e32 v123, v123
	v_mul_f32_e32 v124, 0xbfb8aa3b, v125
	v_exp_f32_e32 v124, v124
	v_fma_f32 v122, v122, s21, 0.5
	v_max_f32_e32 v122, 1.0, v122
	v_fma_f32 v0, v0, s21, 0.5
	v_cvt_pk_u8_f32 v122, v122, 0, 0
	v_max_f32_e32 v0, 1.0, v0
	v_add_f32_e32 v123, 1.0, v123
	v_rcp_f32_e32 v123, v123
	v_cvt_pk_u8_f32 v0, v0, 1, v122
	v_add_f32_e32 v122, 1.0, v124
	v_rcp_f32_e32 v122, v122
	v_mul_f32_e32 v118, 0xbfb8aa3b, v118
	v_exp_f32_e32 v118, v118
	v_mul_f32_e32 v119, 0xbfb8aa3b, v119
	v_fma_f32 v123, v123, s21, 0.5
	v_exp_f32_e32 v119, v119
	v_max_f32_e32 v123, 1.0, v123
	v_fma_f32 v122, v122, s21, 0.5
	v_cvt_pk_u8_f32 v0, v123, 2, v0
	v_max_f32_e32 v122, 1.0, v122
	v_cvt_pk_u8_f32 v0, v122, 3, v0
	v_add_f32_e32 v118, 1.0, v118
	v_rcp_f32_e32 v118, v118
	global_store_dword v[126:127], v0, off offset:256
	v_add_f32_e32 v0, 1.0, v119
	v_rcp_f32_e32 v0, v0
	v_mul_f32_e32 v119, 0xbfb8aa3b, v120
	v_exp_f32_e32 v119, v119
	v_mul_f32_e32 v120, 0xbfb8aa3b, v121
	v_exp_f32_e32 v120, v120
	v_fma_f32 v118, v118, s21, 0.5
	v_max_f32_e32 v118, 1.0, v118
	v_fma_f32 v0, v0, s21, 0.5
	v_cvt_pk_u8_f32 v118, v118, 0, 0
	v_max_f32_e32 v0, 1.0, v0
	v_add_f32_e32 v119, 1.0, v119
	v_rcp_f32_e32 v119, v119
	v_cvt_pk_u8_f32 v0, v0, 1, v118
	v_add_f32_e32 v118, 1.0, v120
	v_rcp_f32_e32 v118, v118
	v_mul_f32_e32 v114, 0xbfb8aa3b, v114
	v_exp_f32_e32 v114, v114
	v_mul_f32_e32 v115, 0xbfb8aa3b, v115
	v_fma_f32 v119, v119, s21, 0.5
	v_exp_f32_e32 v115, v115
	v_max_f32_e32 v119, 1.0, v119
	v_fma_f32 v118, v118, s21, 0.5
	v_cvt_pk_u8_f32 v0, v119, 2, v0
	v_max_f32_e32 v118, 1.0, v118
	v_cvt_pk_u8_f32 v0, v118, 3, v0
	v_add_f32_e32 v114, 1.0, v114
	v_rcp_f32_e32 v114, v114
	global_store_dword v[126:127], v0, off offset:512
	v_add_f32_e32 v0, 1.0, v115
	v_rcp_f32_e32 v0, v0
	v_mul_f32_e32 v115, 0xbfb8aa3b, v116
	v_exp_f32_e32 v115, v115
	v_mul_f32_e32 v116, 0xbfb8aa3b, v117
	v_exp_f32_e32 v116, v116
	v_fma_f32 v114, v114, s21, 0.5
	v_max_f32_e32 v114, 1.0, v114
	v_fma_f32 v0, v0, s21, 0.5
	v_cvt_pk_u8_f32 v114, v114, 0, 0
	v_max_f32_e32 v0, 1.0, v0
	v_add_f32_e32 v115, 1.0, v115
	v_rcp_f32_e32 v115, v115
	v_cvt_pk_u8_f32 v0, v0, 1, v114
	v_add_f32_e32 v114, 1.0, v116
	v_rcp_f32_e32 v114, v114
	v_mul_f32_e32 v110, 0xbfb8aa3b, v110
	v_exp_f32_e32 v110, v110
	v_mul_f32_e32 v111, 0xbfb8aa3b, v111
	v_fma_f32 v115, v115, s21, 0.5
	v_exp_f32_e32 v111, v111
	v_max_f32_e32 v115, 1.0, v115
	v_fma_f32 v114, v114, s21, 0.5
	v_cvt_pk_u8_f32 v0, v115, 2, v0
	v_max_f32_e32 v114, 1.0, v114
	v_cvt_pk_u8_f32 v0, v114, 3, v0
	v_add_f32_e32 v110, 1.0, v110
	v_rcp_f32_e32 v110, v110
	global_store_dword v[126:127], v0, off offset:768
	v_add_f32_e32 v0, 1.0, v111
	v_rcp_f32_e32 v0, v0
	v_mul_f32_e32 v111, 0xbfb8aa3b, v112
	v_exp_f32_e32 v111, v111
	v_mul_f32_e32 v112, 0xbfb8aa3b, v113
	v_exp_f32_e32 v112, v112
	v_fma_f32 v110, v110, s21, 0.5
	v_max_f32_e32 v110, 1.0, v110
	v_fma_f32 v0, v0, s21, 0.5
	v_cvt_pk_u8_f32 v110, v110, 0, 0
	v_max_f32_e32 v0, 1.0, v0
	v_add_f32_e32 v111, 1.0, v111
	v_rcp_f32_e32 v111, v111
	v_cvt_pk_u8_f32 v0, v0, 1, v110
	v_add_f32_e32 v110, 1.0, v112
	v_rcp_f32_e32 v110, v110
	v_mul_f32_e32 v106, 0xbfb8aa3b, v106
	v_exp_f32_e32 v106, v106
	v_mul_f32_e32 v107, 0xbfb8aa3b, v107
	v_fma_f32 v111, v111, s21, 0.5
	v_exp_f32_e32 v107, v107
	v_max_f32_e32 v111, 1.0, v111
	v_fma_f32 v110, v110, s21, 0.5
	v_cvt_pk_u8_f32 v0, v111, 2, v0
	v_max_f32_e32 v110, 1.0, v110
	v_cvt_pk_u8_f32 v0, v110, 3, v0
	v_add_f32_e32 v106, 1.0, v106
	v_rcp_f32_e32 v106, v106
	global_store_dword v[126:127], v0, off offset:1024
	v_add_f32_e32 v0, 1.0, v107
	v_rcp_f32_e32 v0, v0
	v_mul_f32_e32 v107, 0xbfb8aa3b, v108
	v_exp_f32_e32 v107, v107
	v_mul_f32_e32 v108, 0xbfb8aa3b, v109
	v_exp_f32_e32 v108, v108
	v_fma_f32 v106, v106, s21, 0.5
	v_max_f32_e32 v106, 1.0, v106
	v_fma_f32 v0, v0, s21, 0.5
	v_cvt_pk_u8_f32 v106, v106, 0, 0
	v_max_f32_e32 v0, 1.0, v0
	v_add_f32_e32 v107, 1.0, v107
	v_rcp_f32_e32 v107, v107
	v_cvt_pk_u8_f32 v0, v0, 1, v106
	v_add_f32_e32 v106, 1.0, v108
	v_rcp_f32_e32 v106, v106
	v_mul_f32_e32 v102, 0xbfb8aa3b, v102
	v_exp_f32_e32 v102, v102
	v_mul_f32_e32 v103, 0xbfb8aa3b, v103
	v_fma_f32 v107, v107, s21, 0.5
	v_exp_f32_e32 v103, v103
	v_max_f32_e32 v107, 1.0, v107
	v_fma_f32 v106, v106, s21, 0.5
	v_cvt_pk_u8_f32 v0, v107, 2, v0
	v_max_f32_e32 v106, 1.0, v106
	v_cvt_pk_u8_f32 v0, v106, 3, v0
	v_add_f32_e32 v102, 1.0, v102
	v_rcp_f32_e32 v102, v102
	global_store_dword v[126:127], v0, off offset:1280
	v_add_f32_e32 v0, 1.0, v103
	v_rcp_f32_e32 v0, v0
	v_mul_f32_e32 v103, 0xbfb8aa3b, v104
	v_exp_f32_e32 v103, v103
	v_mul_f32_e32 v104, 0xbfb8aa3b, v105
	v_exp_f32_e32 v104, v104
	v_fma_f32 v102, v102, s21, 0.5
	v_max_f32_e32 v102, 1.0, v102
	v_fma_f32 v0, v0, s21, 0.5
	v_cvt_pk_u8_f32 v102, v102, 0, 0
	v_max_f32_e32 v0, 1.0, v0
	v_add_f32_e32 v103, 1.0, v103
	v_rcp_f32_e32 v103, v103
	v_cvt_pk_u8_f32 v0, v0, 1, v102
	v_add_f32_e32 v102, 1.0, v104
	v_rcp_f32_e32 v102, v102
	v_mul_f32_e32 v98, 0xbfb8aa3b, v98
	v_exp_f32_e32 v98, v98
	v_mul_f32_e32 v99, 0xbfb8aa3b, v99
	v_fma_f32 v103, v103, s21, 0.5
	v_exp_f32_e32 v99, v99
	v_max_f32_e32 v103, 1.0, v103
	v_fma_f32 v102, v102, s21, 0.5
	v_cvt_pk_u8_f32 v0, v103, 2, v0
	v_max_f32_e32 v102, 1.0, v102
	v_cvt_pk_u8_f32 v0, v102, 3, v0
	v_add_f32_e32 v98, 1.0, v98
	v_rcp_f32_e32 v98, v98
	global_store_dword v[126:127], v0, off offset:1536
	v_add_f32_e32 v0, 1.0, v99
	v_rcp_f32_e32 v0, v0
	v_mul_f32_e32 v99, 0xbfb8aa3b, v100
	v_exp_f32_e32 v99, v99
	v_mul_f32_e32 v100, 0xbfb8aa3b, v101
	v_exp_f32_e32 v100, v100
	v_fma_f32 v98, v98, s21, 0.5
	v_max_f32_e32 v98, 1.0, v98
	v_fma_f32 v0, v0, s21, 0.5
	v_cvt_pk_u8_f32 v98, v98, 0, 0
	v_max_f32_e32 v0, 1.0, v0
	v_add_f32_e32 v99, 1.0, v99
	v_rcp_f32_e32 v99, v99
	v_cvt_pk_u8_f32 v0, v0, 1, v98
	v_add_f32_e32 v98, 1.0, v100
	v_rcp_f32_e32 v98, v98
	v_mul_f32_e32 v94, 0xbfb8aa3b, v94
	v_exp_f32_e32 v94, v94
	v_mul_f32_e32 v95, 0xbfb8aa3b, v95
	v_fma_f32 v99, v99, s21, 0.5
	v_exp_f32_e32 v95, v95
	v_max_f32_e32 v99, 1.0, v99
	v_fma_f32 v98, v98, s21, 0.5
	v_cvt_pk_u8_f32 v0, v99, 2, v0
	v_max_f32_e32 v98, 1.0, v98
	v_cvt_pk_u8_f32 v0, v98, 3, v0
	v_add_f32_e32 v94, 1.0, v94
	v_rcp_f32_e32 v94, v94
	global_store_dword v[126:127], v0, off offset:1792
	v_add_f32_e32 v0, 1.0, v95
	v_rcp_f32_e32 v0, v0
	v_mul_f32_e32 v95, 0xbfb8aa3b, v96
	v_exp_f32_e32 v95, v95
	v_mul_f32_e32 v96, 0xbfb8aa3b, v97
	v_exp_f32_e32 v96, v96
	v_fma_f32 v94, v94, s21, 0.5
	v_max_f32_e32 v94, 1.0, v94
	v_fma_f32 v0, v0, s21, 0.5
	v_cvt_pk_u8_f32 v94, v94, 0, 0
	v_max_f32_e32 v0, 1.0, v0
	v_add_f32_e32 v95, 1.0, v95
	v_rcp_f32_e32 v95, v95
	v_cvt_pk_u8_f32 v0, v0, 1, v94
	v_add_f32_e32 v94, 1.0, v96
	v_rcp_f32_e32 v94, v94
	v_mul_f32_e32 v90, 0xbfb8aa3b, v90
	v_exp_f32_e32 v90, v90
	v_mul_f32_e32 v91, 0xbfb8aa3b, v91
	v_fma_f32 v95, v95, s21, 0.5
	v_exp_f32_e32 v91, v91
	v_max_f32_e32 v95, 1.0, v95
	v_fma_f32 v94, v94, s21, 0.5
	v_cvt_pk_u8_f32 v0, v95, 2, v0
	v_max_f32_e32 v94, 1.0, v94
	v_cvt_pk_u8_f32 v0, v94, 3, v0
	v_add_f32_e32 v90, 1.0, v90
	v_rcp_f32_e32 v90, v90
	global_store_dword v[126:127], v0, off offset:2048
	v_add_f32_e32 v0, 1.0, v91
	v_rcp_f32_e32 v0, v0
	v_mul_f32_e32 v91, 0xbfb8aa3b, v92
	v_exp_f32_e32 v91, v91
	v_mul_f32_e32 v92, 0xbfb8aa3b, v93
	v_exp_f32_e32 v92, v92
	v_fma_f32 v90, v90, s21, 0.5
	v_max_f32_e32 v90, 1.0, v90
	v_fma_f32 v0, v0, s21, 0.5
	v_cvt_pk_u8_f32 v90, v90, 0, 0
	v_max_f32_e32 v0, 1.0, v0
	v_add_f32_e32 v91, 1.0, v91
	v_rcp_f32_e32 v91, v91
	v_cvt_pk_u8_f32 v0, v0, 1, v90
	v_add_f32_e32 v90, 1.0, v92
	v_rcp_f32_e32 v90, v90
	v_mul_f32_e32 v86, 0xbfb8aa3b, v86
	v_exp_f32_e32 v86, v86
	v_mul_f32_e32 v87, 0xbfb8aa3b, v87
	v_fma_f32 v91, v91, s21, 0.5
	v_exp_f32_e32 v87, v87
	v_max_f32_e32 v91, 1.0, v91
	v_fma_f32 v90, v90, s21, 0.5
	v_cvt_pk_u8_f32 v0, v91, 2, v0
	v_max_f32_e32 v90, 1.0, v90
	v_cvt_pk_u8_f32 v0, v90, 3, v0
	v_add_f32_e32 v86, 1.0, v86
	v_rcp_f32_e32 v86, v86
	global_store_dword v[126:127], v0, off offset:2304
	v_add_f32_e32 v0, 1.0, v87
	v_rcp_f32_e32 v0, v0
	v_mul_f32_e32 v87, 0xbfb8aa3b, v88
	v_exp_f32_e32 v87, v87
	v_mul_f32_e32 v88, 0xbfb8aa3b, v89
	v_exp_f32_e32 v88, v88
	v_fma_f32 v86, v86, s21, 0.5
	v_max_f32_e32 v86, 1.0, v86
	v_fma_f32 v0, v0, s21, 0.5
	v_cvt_pk_u8_f32 v86, v86, 0, 0
	v_max_f32_e32 v0, 1.0, v0
	v_add_f32_e32 v87, 1.0, v87
	v_rcp_f32_e32 v87, v87
	v_cvt_pk_u8_f32 v0, v0, 1, v86
	v_add_f32_e32 v86, 1.0, v88
	v_rcp_f32_e32 v86, v86
	v_mul_f32_e32 v82, 0xbfb8aa3b, v82
	v_exp_f32_e32 v82, v82
	v_mul_f32_e32 v83, 0xbfb8aa3b, v83
	v_fma_f32 v87, v87, s21, 0.5
	v_exp_f32_e32 v83, v83
	v_max_f32_e32 v87, 1.0, v87
	v_fma_f32 v86, v86, s21, 0.5
	v_cvt_pk_u8_f32 v0, v87, 2, v0
	v_max_f32_e32 v86, 1.0, v86
	v_cvt_pk_u8_f32 v0, v86, 3, v0
	v_add_f32_e32 v82, 1.0, v82
	v_rcp_f32_e32 v82, v82
	global_store_dword v[126:127], v0, off offset:2560
	v_add_f32_e32 v0, 1.0, v83
	v_rcp_f32_e32 v0, v0
	v_mul_f32_e32 v83, 0xbfb8aa3b, v84
	v_exp_f32_e32 v83, v83
	v_mul_f32_e32 v84, 0xbfb8aa3b, v85
	v_exp_f32_e32 v84, v84
	v_fma_f32 v82, v82, s21, 0.5
	v_max_f32_e32 v82, 1.0, v82
	v_fma_f32 v0, v0, s21, 0.5
	v_cvt_pk_u8_f32 v82, v82, 0, 0
	v_max_f32_e32 v0, 1.0, v0
	v_add_f32_e32 v83, 1.0, v83
	v_rcp_f32_e32 v83, v83
	v_cvt_pk_u8_f32 v0, v0, 1, v82
	v_add_f32_e32 v82, 1.0, v84
	v_rcp_f32_e32 v82, v82
	v_mul_f32_e32 v78, 0xbfb8aa3b, v78
	v_exp_f32_e32 v78, v78
	v_mul_f32_e32 v79, 0xbfb8aa3b, v79
	v_fma_f32 v83, v83, s21, 0.5
	v_exp_f32_e32 v79, v79
	v_max_f32_e32 v83, 1.0, v83
	v_fma_f32 v82, v82, s21, 0.5
	v_cvt_pk_u8_f32 v0, v83, 2, v0
	v_max_f32_e32 v82, 1.0, v82
	v_cvt_pk_u8_f32 v0, v82, 3, v0
	v_add_f32_e32 v78, 1.0, v78
	v_rcp_f32_e32 v78, v78
	global_store_dword v[126:127], v0, off offset:2816
	v_add_f32_e32 v0, 1.0, v79
	v_rcp_f32_e32 v0, v0
	v_mul_f32_e32 v79, 0xbfb8aa3b, v80
	v_exp_f32_e32 v79, v79
	v_mul_f32_e32 v80, 0xbfb8aa3b, v81
	v_exp_f32_e32 v80, v80
	v_fma_f32 v78, v78, s21, 0.5
	v_max_f32_e32 v78, 1.0, v78
	v_fma_f32 v0, v0, s21, 0.5
	v_cvt_pk_u8_f32 v78, v78, 0, 0
	v_max_f32_e32 v0, 1.0, v0
	v_add_f32_e32 v79, 1.0, v79
	v_rcp_f32_e32 v79, v79
	v_cvt_pk_u8_f32 v0, v0, 1, v78
	v_add_f32_e32 v78, 1.0, v80
	v_rcp_f32_e32 v78, v78
	v_mul_f32_e32 v74, 0xbfb8aa3b, v74
	v_exp_f32_e32 v74, v74
	v_mul_f32_e32 v75, 0xbfb8aa3b, v75
	v_fma_f32 v79, v79, s21, 0.5
	v_exp_f32_e32 v75, v75
	v_max_f32_e32 v79, 1.0, v79
	v_fma_f32 v78, v78, s21, 0.5
	v_cvt_pk_u8_f32 v0, v79, 2, v0
	v_max_f32_e32 v78, 1.0, v78
	v_cvt_pk_u8_f32 v0, v78, 3, v0
	v_add_f32_e32 v74, 1.0, v74
	v_rcp_f32_e32 v74, v74
	global_store_dword v[126:127], v0, off offset:3072
	v_add_f32_e32 v0, 1.0, v75
	v_rcp_f32_e32 v0, v0
	v_mul_f32_e32 v75, 0xbfb8aa3b, v76
	v_exp_f32_e32 v75, v75
	v_mul_f32_e32 v76, 0xbfb8aa3b, v77
	v_exp_f32_e32 v76, v76
	v_fma_f32 v74, v74, s21, 0.5
	v_max_f32_e32 v74, 1.0, v74
	v_fma_f32 v0, v0, s21, 0.5
	v_cvt_pk_u8_f32 v74, v74, 0, 0
	v_max_f32_e32 v0, 1.0, v0
	v_add_f32_e32 v75, 1.0, v75
	v_rcp_f32_e32 v75, v75
	v_cvt_pk_u8_f32 v0, v0, 1, v74
	v_add_f32_e32 v74, 1.0, v76
	v_rcp_f32_e32 v74, v74
	v_mul_f32_e32 v70, 0xbfb8aa3b, v70
	v_exp_f32_e32 v70, v70
	v_mul_f32_e32 v71, 0xbfb8aa3b, v71
	v_fma_f32 v75, v75, s21, 0.5
	v_exp_f32_e32 v71, v71
	v_max_f32_e32 v75, 1.0, v75
	v_fma_f32 v74, v74, s21, 0.5
	v_cvt_pk_u8_f32 v0, v75, 2, v0
	v_max_f32_e32 v74, 1.0, v74
	v_cvt_pk_u8_f32 v0, v74, 3, v0
	v_add_f32_e32 v70, 1.0, v70
	v_rcp_f32_e32 v70, v70
	global_store_dword v[126:127], v0, off offset:3328
	v_add_f32_e32 v0, 1.0, v71
	v_rcp_f32_e32 v0, v0
	v_mul_f32_e32 v71, 0xbfb8aa3b, v72
	v_exp_f32_e32 v71, v71
	v_mul_f32_e32 v72, 0xbfb8aa3b, v73
	v_exp_f32_e32 v72, v72
	v_fma_f32 v70, v70, s21, 0.5
	v_max_f32_e32 v70, 1.0, v70
	v_fma_f32 v0, v0, s21, 0.5
	v_cvt_pk_u8_f32 v70, v70, 0, 0
	v_max_f32_e32 v0, 1.0, v0
	v_add_f32_e32 v71, 1.0, v71
	v_rcp_f32_e32 v71, v71
	v_cvt_pk_u8_f32 v0, v0, 1, v70
	v_add_f32_e32 v70, 1.0, v72
	v_rcp_f32_e32 v70, v70
	v_mul_f32_e32 v66, 0xbfb8aa3b, v66
	v_exp_f32_e32 v66, v66
	v_mul_f32_e32 v67, 0xbfb8aa3b, v67
	v_fma_f32 v71, v71, s21, 0.5
	v_exp_f32_e32 v67, v67
	v_max_f32_e32 v71, 1.0, v71
	v_fma_f32 v70, v70, s21, 0.5
	v_cvt_pk_u8_f32 v0, v71, 2, v0
	v_max_f32_e32 v70, 1.0, v70
	v_cvt_pk_u8_f32 v0, v70, 3, v0
	v_add_f32_e32 v66, 1.0, v66
	v_rcp_f32_e32 v66, v66
	global_store_dword v[126:127], v0, off offset:3584
	v_add_f32_e32 v0, 1.0, v67
	v_rcp_f32_e32 v0, v0
	v_mul_f32_e32 v67, 0xbfb8aa3b, v68
	v_exp_f32_e32 v67, v67
	v_mul_f32_e32 v68, 0xbfb8aa3b, v69
	v_exp_f32_e32 v68, v68
	v_fma_f32 v66, v66, s21, 0.5
	v_max_f32_e32 v66, 1.0, v66
	v_fma_f32 v0, v0, s21, 0.5
	v_cvt_pk_u8_f32 v66, v66, 0, 0
	v_max_f32_e32 v0, 1.0, v0
	v_add_f32_e32 v67, 1.0, v67
	v_rcp_f32_e32 v67, v67
	v_cvt_pk_u8_f32 v0, v0, 1, v66
	v_add_f32_e32 v66, 1.0, v68
	v_rcp_f32_e32 v66, v66
	v_mul_f32_e32 v62, 0xbfb8aa3b, v62
	v_exp_f32_e32 v62, v62
	v_mul_f32_e32 v63, 0xbfb8aa3b, v63
	v_fma_f32 v67, v67, s21, 0.5
	v_exp_f32_e32 v63, v63
	v_max_f32_e32 v67, 1.0, v67
	v_fma_f32 v66, v66, s21, 0.5
	v_cvt_pk_u8_f32 v0, v67, 2, v0
	v_max_f32_e32 v66, 1.0, v66
	v_cvt_pk_u8_f32 v0, v66, 3, v0
	v_add_f32_e32 v62, 1.0, v62
	v_rcp_f32_e32 v62, v62
	global_store_dword v[126:127], v0, off offset:3840
	v_add_f32_e32 v0, 1.0, v63
	v_rcp_f32_e32 v0, v0
	v_mul_f32_e32 v63, 0xbfb8aa3b, v64
	v_exp_f32_e32 v63, v63
	v_mul_f32_e32 v64, 0xbfb8aa3b, v65
	v_exp_f32_e32 v64, v64
	v_fma_f32 v62, v62, s21, 0.5
	v_max_f32_e32 v62, 1.0, v62
	v_fma_f32 v0, v0, s21, 0.5
	v_cvt_pk_u8_f32 v62, v62, 0, 0
	v_max_f32_e32 v0, 1.0, v0
	v_add_f32_e32 v63, 1.0, v63
	v_rcp_f32_e32 v63, v63
	v_cvt_pk_u8_f32 v0, v0, 1, v62
	v_add_f32_e32 v62, 1.0, v64
	v_rcp_f32_e32 v62, v62
	v_mul_f32_e32 v58, 0xbfb8aa3b, v58
	v_fma_f32 v63, v63, s21, 0.5
	v_exp_f32_e32 v58, v58
	v_mul_f32_e32 v59, 0xbfb8aa3b, v59
	v_max_f32_e32 v63, 1.0, v63
	v_fma_f32 v62, v62, s21, 0.5
	v_exp_f32_e32 v59, v59
	v_cvt_pk_u8_f32 v0, v63, 2, v0
	v_max_f32_e32 v62, 1.0, v62
	v_cvt_pk_u8_f32 v0, v62, 3, v0
	v_add_co_u32_e32 v62, vcc, s77, v126
	v_add_f32_e32 v58, 1.0, v58
	s_nop 0
	v_addc_co_u32_e32 v63, vcc, 0, v127, vcc
	v_rcp_f32_e32 v58, v58
	global_store_dword v[62:63], v0, off
	v_add_f32_e32 v0, 1.0, v59
	v_rcp_f32_e32 v0, v0
	v_mul_f32_e32 v59, 0xbfb8aa3b, v60
	v_exp_f32_e32 v59, v59
	v_mul_f32_e32 v60, 0xbfb8aa3b, v61
	v_exp_f32_e32 v60, v60
	v_fma_f32 v58, v58, s21, 0.5
	v_max_f32_e32 v58, 1.0, v58
	v_fma_f32 v0, v0, s21, 0.5
	v_cvt_pk_u8_f32 v58, v58, 0, 0
	v_max_f32_e32 v0, 1.0, v0
	v_add_f32_e32 v59, 1.0, v59
	v_rcp_f32_e32 v59, v59
	v_cvt_pk_u8_f32 v0, v0, 1, v58
	v_add_f32_e32 v58, 1.0, v60
	v_rcp_f32_e32 v58, v58
	v_mul_f32_e32 v54, 0xbfb8aa3b, v54
	v_exp_f32_e32 v54, v54
	v_mul_f32_e32 v55, 0xbfb8aa3b, v55
	v_fma_f32 v59, v59, s21, 0.5
	v_exp_f32_e32 v55, v55
	v_max_f32_e32 v59, 1.0, v59
	v_fma_f32 v58, v58, s21, 0.5
	v_cvt_pk_u8_f32 v0, v59, 2, v0
	v_max_f32_e32 v58, 1.0, v58
	v_cvt_pk_u8_f32 v0, v58, 3, v0
	v_add_f32_e32 v54, 1.0, v54
	v_rcp_f32_e32 v54, v54
	global_store_dword v[62:63], v0, off offset:256
	v_add_f32_e32 v0, 1.0, v55
	v_rcp_f32_e32 v0, v0
	v_mul_f32_e32 v55, 0xbfb8aa3b, v56
	v_exp_f32_e32 v55, v55
	v_mul_f32_e32 v56, 0xbfb8aa3b, v57
	v_exp_f32_e32 v56, v56
	v_fma_f32 v54, v54, s21, 0.5
	v_max_f32_e32 v54, 1.0, v54
	v_fma_f32 v0, v0, s21, 0.5
	v_cvt_pk_u8_f32 v54, v54, 0, 0
	v_max_f32_e32 v0, 1.0, v0
	v_add_f32_e32 v55, 1.0, v55
	v_rcp_f32_e32 v55, v55
	v_cvt_pk_u8_f32 v0, v0, 1, v54
	v_add_f32_e32 v54, 1.0, v56
	v_rcp_f32_e32 v54, v54
	v_mul_f32_e32 v50, 0xbfb8aa3b, v50
	v_exp_f32_e32 v50, v50
	v_mul_f32_e32 v51, 0xbfb8aa3b, v51
	v_fma_f32 v55, v55, s21, 0.5
	v_exp_f32_e32 v51, v51
	v_max_f32_e32 v55, 1.0, v55
	v_fma_f32 v54, v54, s21, 0.5
	v_cvt_pk_u8_f32 v0, v55, 2, v0
	v_max_f32_e32 v54, 1.0, v54
	v_cvt_pk_u8_f32 v0, v54, 3, v0
	v_add_f32_e32 v50, 1.0, v50
	v_rcp_f32_e32 v50, v50
	global_store_dword v[62:63], v0, off offset:512
	v_add_f32_e32 v0, 1.0, v51
	v_rcp_f32_e32 v0, v0
	v_mul_f32_e32 v51, 0xbfb8aa3b, v52
	v_exp_f32_e32 v51, v51
	v_mul_f32_e32 v52, 0xbfb8aa3b, v53
	v_exp_f32_e32 v52, v52
	v_fma_f32 v50, v50, s21, 0.5
	v_max_f32_e32 v50, 1.0, v50
	v_fma_f32 v0, v0, s21, 0.5
	v_cvt_pk_u8_f32 v50, v50, 0, 0
	v_max_f32_e32 v0, 1.0, v0
	v_add_f32_e32 v51, 1.0, v51
	v_rcp_f32_e32 v51, v51
	v_cvt_pk_u8_f32 v0, v0, 1, v50
	v_add_f32_e32 v50, 1.0, v52
	v_rcp_f32_e32 v50, v50
	v_mul_f32_e32 v46, 0xbfb8aa3b, v46
	v_exp_f32_e32 v46, v46
	v_mul_f32_e32 v47, 0xbfb8aa3b, v47
	v_fma_f32 v51, v51, s21, 0.5
	v_exp_f32_e32 v47, v47
	v_max_f32_e32 v51, 1.0, v51
	v_fma_f32 v50, v50, s21, 0.5
	v_cvt_pk_u8_f32 v0, v51, 2, v0
	v_max_f32_e32 v50, 1.0, v50
	v_cvt_pk_u8_f32 v0, v50, 3, v0
	v_add_f32_e32 v46, 1.0, v46
	v_rcp_f32_e32 v46, v46
	global_store_dword v[62:63], v0, off offset:768
	v_add_f32_e32 v0, 1.0, v47
	v_rcp_f32_e32 v0, v0
	v_mul_f32_e32 v47, 0xbfb8aa3b, v48
	v_exp_f32_e32 v47, v47
	v_mul_f32_e32 v48, 0xbfb8aa3b, v49
	v_exp_f32_e32 v48, v48
	v_fma_f32 v46, v46, s21, 0.5
	v_max_f32_e32 v46, 1.0, v46
	v_fma_f32 v0, v0, s21, 0.5
	v_cvt_pk_u8_f32 v46, v46, 0, 0
	v_max_f32_e32 v0, 1.0, v0
	v_add_f32_e32 v47, 1.0, v47
	v_rcp_f32_e32 v47, v47
	v_cvt_pk_u8_f32 v0, v0, 1, v46
	v_add_f32_e32 v46, 1.0, v48
	v_rcp_f32_e32 v46, v46
	v_mul_f32_e32 v42, 0xbfb8aa3b, v42
	v_exp_f32_e32 v42, v42
	v_mul_f32_e32 v43, 0xbfb8aa3b, v43
	v_fma_f32 v47, v47, s21, 0.5
	v_exp_f32_e32 v43, v43
	v_max_f32_e32 v47, 1.0, v47
	v_fma_f32 v46, v46, s21, 0.5
	v_cvt_pk_u8_f32 v0, v47, 2, v0
	v_max_f32_e32 v46, 1.0, v46
	v_cvt_pk_u8_f32 v0, v46, 3, v0
	v_add_f32_e32 v42, 1.0, v42
	v_rcp_f32_e32 v42, v42
	global_store_dword v[62:63], v0, off offset:1024
	v_add_f32_e32 v0, 1.0, v43
	v_rcp_f32_e32 v0, v0
	v_mul_f32_e32 v43, 0xbfb8aa3b, v44
	v_exp_f32_e32 v43, v43
	v_mul_f32_e32 v44, 0xbfb8aa3b, v45
	v_exp_f32_e32 v44, v44
	v_fma_f32 v42, v42, s21, 0.5
	v_max_f32_e32 v42, 1.0, v42
	v_fma_f32 v0, v0, s21, 0.5
	v_cvt_pk_u8_f32 v42, v42, 0, 0
	v_max_f32_e32 v0, 1.0, v0
	v_add_f32_e32 v43, 1.0, v43
	v_rcp_f32_e32 v43, v43
	v_cvt_pk_u8_f32 v0, v0, 1, v42
	v_add_f32_e32 v42, 1.0, v44
	v_rcp_f32_e32 v42, v42
	v_mul_f32_e32 v38, 0xbfb8aa3b, v38
	v_exp_f32_e32 v38, v38
	v_mul_f32_e32 v39, 0xbfb8aa3b, v39
	v_fma_f32 v43, v43, s21, 0.5
	v_exp_f32_e32 v39, v39
	v_max_f32_e32 v43, 1.0, v43
	v_fma_f32 v42, v42, s21, 0.5
	v_cvt_pk_u8_f32 v0, v43, 2, v0
	v_max_f32_e32 v42, 1.0, v42
	v_cvt_pk_u8_f32 v0, v42, 3, v0
	v_add_f32_e32 v38, 1.0, v38
	v_rcp_f32_e32 v38, v38
	global_store_dword v[62:63], v0, off offset:1280
	v_add_f32_e32 v0, 1.0, v39
	v_rcp_f32_e32 v0, v0
	v_mul_f32_e32 v39, 0xbfb8aa3b, v40
	v_exp_f32_e32 v39, v39
	v_mul_f32_e32 v40, 0xbfb8aa3b, v41
	v_exp_f32_e32 v40, v40
	v_fma_f32 v38, v38, s21, 0.5
	v_max_f32_e32 v38, 1.0, v38
	v_fma_f32 v0, v0, s21, 0.5
	v_cvt_pk_u8_f32 v38, v38, 0, 0
	v_max_f32_e32 v0, 1.0, v0
	v_add_f32_e32 v39, 1.0, v39
	v_rcp_f32_e32 v39, v39
	v_cvt_pk_u8_f32 v0, v0, 1, v38
	v_add_f32_e32 v38, 1.0, v40
	v_rcp_f32_e32 v38, v38
	v_mul_f32_e32 v34, 0xbfb8aa3b, v34
	v_exp_f32_e32 v34, v34
	v_mul_f32_e32 v35, 0xbfb8aa3b, v35
	v_fma_f32 v39, v39, s21, 0.5
	v_exp_f32_e32 v35, v35
	v_max_f32_e32 v39, 1.0, v39
	v_fma_f32 v38, v38, s21, 0.5
	v_cvt_pk_u8_f32 v0, v39, 2, v0
	v_max_f32_e32 v38, 1.0, v38
	v_cvt_pk_u8_f32 v0, v38, 3, v0
	v_add_f32_e32 v34, 1.0, v34
	v_rcp_f32_e32 v34, v34
	global_store_dword v[62:63], v0, off offset:1536
	v_add_f32_e32 v0, 1.0, v35
	v_rcp_f32_e32 v0, v0
	v_mul_f32_e32 v35, 0xbfb8aa3b, v36
	v_exp_f32_e32 v35, v35
	v_mul_f32_e32 v36, 0xbfb8aa3b, v37
	v_exp_f32_e32 v36, v36
	v_fma_f32 v34, v34, s21, 0.5
	v_max_f32_e32 v34, 1.0, v34
	v_fma_f32 v0, v0, s21, 0.5
	v_cvt_pk_u8_f32 v34, v34, 0, 0
	v_max_f32_e32 v0, 1.0, v0
	v_add_f32_e32 v35, 1.0, v35
	v_rcp_f32_e32 v35, v35
	v_cvt_pk_u8_f32 v0, v0, 1, v34
	v_add_f32_e32 v34, 1.0, v36
	v_rcp_f32_e32 v34, v34
	v_mul_f32_e32 v30, 0xbfb8aa3b, v30
	v_exp_f32_e32 v30, v30
	v_mul_f32_e32 v31, 0xbfb8aa3b, v31
	v_fma_f32 v35, v35, s21, 0.5
	v_exp_f32_e32 v31, v31
	v_max_f32_e32 v35, 1.0, v35
	v_fma_f32 v34, v34, s21, 0.5
	v_cvt_pk_u8_f32 v0, v35, 2, v0
	v_max_f32_e32 v34, 1.0, v34
	v_cvt_pk_u8_f32 v0, v34, 3, v0
	v_add_f32_e32 v30, 1.0, v30
	v_rcp_f32_e32 v30, v30
	global_store_dword v[62:63], v0, off offset:1792
	v_add_f32_e32 v0, 1.0, v31
	v_rcp_f32_e32 v0, v0
	v_mul_f32_e32 v31, 0xbfb8aa3b, v32
	v_exp_f32_e32 v31, v31
	v_mul_f32_e32 v32, 0xbfb8aa3b, v33
	v_exp_f32_e32 v32, v32
	v_fma_f32 v30, v30, s21, 0.5
	v_max_f32_e32 v30, 1.0, v30
	v_fma_f32 v0, v0, s21, 0.5
	v_cvt_pk_u8_f32 v30, v30, 0, 0
	v_max_f32_e32 v0, 1.0, v0
	v_add_f32_e32 v31, 1.0, v31
	v_rcp_f32_e32 v31, v31
	v_cvt_pk_u8_f32 v0, v0, 1, v30
	v_add_f32_e32 v30, 1.0, v32
	v_rcp_f32_e32 v30, v30
	v_mul_f32_e32 v26, 0xbfb8aa3b, v26
	v_exp_f32_e32 v26, v26
	v_mul_f32_e32 v27, 0xbfb8aa3b, v27
	v_fma_f32 v31, v31, s21, 0.5
	v_exp_f32_e32 v27, v27
	v_max_f32_e32 v31, 1.0, v31
	v_fma_f32 v30, v30, s21, 0.5
	v_cvt_pk_u8_f32 v0, v31, 2, v0
	v_max_f32_e32 v30, 1.0, v30
	v_cvt_pk_u8_f32 v0, v30, 3, v0
	v_add_f32_e32 v26, 1.0, v26
	v_rcp_f32_e32 v26, v26
	global_store_dword v[62:63], v0, off offset:2048
	v_add_f32_e32 v0, 1.0, v27
	v_rcp_f32_e32 v0, v0
	v_mul_f32_e32 v27, 0xbfb8aa3b, v28
	v_exp_f32_e32 v27, v27
	v_mul_f32_e32 v28, 0xbfb8aa3b, v29
	v_exp_f32_e32 v28, v28
	v_fma_f32 v26, v26, s21, 0.5
	v_max_f32_e32 v26, 1.0, v26
	v_fma_f32 v0, v0, s21, 0.5
	v_cvt_pk_u8_f32 v26, v26, 0, 0
	v_max_f32_e32 v0, 1.0, v0
	v_add_f32_e32 v27, 1.0, v27
	v_rcp_f32_e32 v27, v27
	v_cvt_pk_u8_f32 v0, v0, 1, v26
	v_add_f32_e32 v26, 1.0, v28
	v_rcp_f32_e32 v26, v26
	v_mul_f32_e32 v22, 0xbfb8aa3b, v22
	v_exp_f32_e32 v22, v22
	v_mul_f32_e32 v23, 0xbfb8aa3b, v23
	v_fma_f32 v27, v27, s21, 0.5
	v_exp_f32_e32 v23, v23
	v_max_f32_e32 v27, 1.0, v27
	v_fma_f32 v26, v26, s21, 0.5
	v_cvt_pk_u8_f32 v0, v27, 2, v0
	v_max_f32_e32 v26, 1.0, v26
	v_cvt_pk_u8_f32 v0, v26, 3, v0
	v_add_f32_e32 v22, 1.0, v22
	v_rcp_f32_e32 v22, v22
	global_store_dword v[62:63], v0, off offset:2304
	v_add_f32_e32 v0, 1.0, v23
	v_rcp_f32_e32 v0, v0
	v_mul_f32_e32 v23, 0xbfb8aa3b, v24
	v_exp_f32_e32 v23, v23
	v_mul_f32_e32 v24, 0xbfb8aa3b, v25
	v_exp_f32_e32 v24, v24
	v_fma_f32 v22, v22, s21, 0.5
	v_max_f32_e32 v22, 1.0, v22
	v_fma_f32 v0, v0, s21, 0.5
	v_cvt_pk_u8_f32 v22, v22, 0, 0
	v_max_f32_e32 v0, 1.0, v0
	v_add_f32_e32 v23, 1.0, v23
	v_rcp_f32_e32 v23, v23
	v_cvt_pk_u8_f32 v0, v0, 1, v22
	v_add_f32_e32 v22, 1.0, v24
	v_rcp_f32_e32 v22, v22
	v_mul_f32_e32 v18, 0xbfb8aa3b, v18
	v_exp_f32_e32 v18, v18
	v_mul_f32_e32 v19, 0xbfb8aa3b, v19
	v_fma_f32 v23, v23, s21, 0.5
	v_exp_f32_e32 v19, v19
	v_max_f32_e32 v23, 1.0, v23
	v_fma_f32 v22, v22, s21, 0.5
	v_cvt_pk_u8_f32 v0, v23, 2, v0
	v_max_f32_e32 v22, 1.0, v22
	v_cvt_pk_u8_f32 v0, v22, 3, v0
	v_add_f32_e32 v18, 1.0, v18
	v_rcp_f32_e32 v18, v18
	global_store_dword v[62:63], v0, off offset:2560
	v_add_f32_e32 v0, 1.0, v19
	v_rcp_f32_e32 v0, v0
	v_mul_f32_e32 v19, 0xbfb8aa3b, v20
	v_exp_f32_e32 v19, v19
	v_mul_f32_e32 v20, 0xbfb8aa3b, v21
	v_exp_f32_e32 v20, v20
	v_fma_f32 v18, v18, s21, 0.5
	v_max_f32_e32 v18, 1.0, v18
	v_fma_f32 v0, v0, s21, 0.5
	v_cvt_pk_u8_f32 v18, v18, 0, 0
	v_max_f32_e32 v0, 1.0, v0
	v_add_f32_e32 v19, 1.0, v19
	v_rcp_f32_e32 v19, v19
	v_cvt_pk_u8_f32 v0, v0, 1, v18
	v_add_f32_e32 v18, 1.0, v20
	v_rcp_f32_e32 v18, v18
	v_mul_f32_e32 v14, 0xbfb8aa3b, v14
	v_exp_f32_e32 v14, v14
	v_mul_f32_e32 v15, 0xbfb8aa3b, v15
	v_fma_f32 v19, v19, s21, 0.5
	v_exp_f32_e32 v15, v15
	v_max_f32_e32 v19, 1.0, v19
	v_fma_f32 v18, v18, s21, 0.5
	v_cvt_pk_u8_f32 v0, v19, 2, v0
	v_max_f32_e32 v18, 1.0, v18
	v_cvt_pk_u8_f32 v0, v18, 3, v0
	v_add_f32_e32 v14, 1.0, v14
	v_rcp_f32_e32 v14, v14
	global_store_dword v[62:63], v0, off offset:2816
	v_add_f32_e32 v0, 1.0, v15
	v_rcp_f32_e32 v0, v0
	v_mul_f32_e32 v15, 0xbfb8aa3b, v16
	v_exp_f32_e32 v15, v15
	v_mul_f32_e32 v16, 0xbfb8aa3b, v17
	v_exp_f32_e32 v16, v16
	v_fma_f32 v14, v14, s21, 0.5
	v_max_f32_e32 v14, 1.0, v14
	v_fma_f32 v0, v0, s21, 0.5
	v_cvt_pk_u8_f32 v14, v14, 0, 0
	v_max_f32_e32 v0, 1.0, v0
	v_add_f32_e32 v15, 1.0, v15
	v_rcp_f32_e32 v15, v15
	v_cvt_pk_u8_f32 v0, v0, 1, v14
	v_add_f32_e32 v14, 1.0, v16
	v_rcp_f32_e32 v14, v14
	v_mul_f32_e32 v10, 0xbfb8aa3b, v10
	v_exp_f32_e32 v10, v10
	v_mul_f32_e32 v11, 0xbfb8aa3b, v11
	v_fma_f32 v15, v15, s21, 0.5
	v_exp_f32_e32 v11, v11
	v_max_f32_e32 v15, 1.0, v15
	v_fma_f32 v14, v14, s21, 0.5
	v_cvt_pk_u8_f32 v0, v15, 2, v0
	v_max_f32_e32 v14, 1.0, v14
	v_cvt_pk_u8_f32 v0, v14, 3, v0
	v_add_f32_e32 v10, 1.0, v10
	v_rcp_f32_e32 v10, v10
	global_store_dword v[62:63], v0, off offset:3072
	v_add_f32_e32 v0, 1.0, v11
	v_rcp_f32_e32 v0, v0
	v_mul_f32_e32 v11, 0xbfb8aa3b, v12
	v_exp_f32_e32 v11, v11
	v_mul_f32_e32 v12, 0xbfb8aa3b, v13
	v_exp_f32_e32 v12, v12
	v_fma_f32 v10, v10, s21, 0.5
	v_max_f32_e32 v10, 1.0, v10
	v_fma_f32 v0, v0, s21, 0.5
	v_cvt_pk_u8_f32 v10, v10, 0, 0
	v_max_f32_e32 v0, 1.0, v0
	v_add_f32_e32 v11, 1.0, v11
	v_rcp_f32_e32 v11, v11
	v_cvt_pk_u8_f32 v0, v0, 1, v10
	v_add_f32_e32 v10, 1.0, v12
	v_rcp_f32_e32 v10, v10
	v_mul_f32_e32 v6, 0xbfb8aa3b, v6
	v_exp_f32_e32 v6, v6
	v_mul_f32_e32 v7, 0xbfb8aa3b, v7
	v_fma_f32 v11, v11, s21, 0.5
	v_exp_f32_e32 v7, v7
	v_max_f32_e32 v11, 1.0, v11
	v_fma_f32 v10, v10, s21, 0.5
	v_cvt_pk_u8_f32 v0, v11, 2, v0
	v_max_f32_e32 v10, 1.0, v10
	v_cvt_pk_u8_f32 v0, v10, 3, v0
	v_add_f32_e32 v6, 1.0, v6
	v_rcp_f32_e32 v6, v6
	global_store_dword v[62:63], v0, off offset:3328
	v_add_f32_e32 v0, 1.0, v7
	v_rcp_f32_e32 v0, v0
	v_mul_f32_e32 v7, 0xbfb8aa3b, v8
	v_exp_f32_e32 v7, v7
	v_mul_f32_e32 v8, 0xbfb8aa3b, v9
	v_exp_f32_e32 v8, v8
	v_fma_f32 v6, v6, s21, 0.5
	v_max_f32_e32 v6, 1.0, v6
	v_fma_f32 v0, v0, s21, 0.5
	v_cvt_pk_u8_f32 v6, v6, 0, 0
	v_max_f32_e32 v0, 1.0, v0
	v_add_f32_e32 v7, 1.0, v7
	v_rcp_f32_e32 v7, v7
	v_cvt_pk_u8_f32 v0, v0, 1, v6
	v_add_f32_e32 v6, 1.0, v8
	v_rcp_f32_e32 v6, v6
	v_mul_f32_e32 v2, 0xbfb8aa3b, v2
	v_exp_f32_e32 v2, v2
	v_mul_f32_e32 v3, 0xbfb8aa3b, v3
	v_fma_f32 v7, v7, s21, 0.5
	v_exp_f32_e32 v3, v3
	v_max_f32_e32 v7, 1.0, v7
	v_fma_f32 v6, v6, s21, 0.5
	v_cvt_pk_u8_f32 v0, v7, 2, v0
	v_max_f32_e32 v6, 1.0, v6
	v_cvt_pk_u8_f32 v0, v6, 3, v0
	v_add_f32_e32 v2, 1.0, v2
	v_rcp_f32_e32 v2, v2
	global_store_dword v[62:63], v0, off offset:3584
	v_add_f32_e32 v0, 1.0, v3
	v_rcp_f32_e32 v0, v0
	v_mul_f32_e32 v3, 0xbfb8aa3b, v4
	v_exp_f32_e32 v3, v3
	v_mul_f32_e32 v4, 0xbfb8aa3b, v5
	v_exp_f32_e32 v4, v4
	v_fma_f32 v2, v2, s21, 0.5
	v_max_f32_e32 v2, 1.0, v2
	v_fma_f32 v0, v0, s21, 0.5
	v_cvt_pk_u8_f32 v2, v2, 0, 0
	v_max_f32_e32 v0, 1.0, v0
	v_add_f32_e32 v3, 1.0, v3
	v_rcp_f32_e32 v3, v3
	v_cvt_pk_u8_f32 v0, v0, 1, v2
	v_add_f32_e32 v2, 1.0, v4
	v_rcp_f32_e32 v2, v2
	v_fma_f32 v3, v3, s21, 0.5
	s_add_i32 s96, s96, 1
	v_max_f32_e32 v3, 1.0, v3
	v_fma_f32 v2, v2, s21, 0.5
	s_add_u32 s12, s12, 0x200000
	v_cvt_pk_u8_f32 v0, v3, 2, v0
	v_max_f32_e32 v2, 1.0, v2
	s_addc_u32 s13, s13, 0
	v_cvt_pk_u8_f32 v0, v2, 3, v0
	s_cmp_lg_u32 s96, 3
	s_mov_b32 s97, 0x12000
	global_store_dword v[62:63], v0, off offset:3840
	s_cbranch_scc1 .LBB0_328
	s_lshl_b64 s[2:3], s[8:9], 10
	s_add_u32 s12, s72, s18
	s_addc_u32 s13, s73, s19
	v_mov_b32_e32 v2, v1
	v_mov_b32_e32 v3, v1
	s_add_u32 s16, s72, s2
	v_mov_b32_e32 v0, v1
	v_mov_b64_e32 v[6:7], v[2:3]
	v_mov_b64_e32 v[10:11], v[2:3]
	v_mov_b64_e32 v[22:23], v[2:3]
	v_mov_b64_e32 v[26:27], v[2:3]
	v_mov_b64_e32 v[38:39], v[2:3]
	v_mov_b64_e32 v[42:43], v[2:3]
	v_mov_b64_e32 v[54:55], v[2:3]
	v_mov_b64_e32 v[58:59], v[2:3]
	v_mov_b64_e32 v[14:15], v[2:3]
	v_mov_b64_e32 v[18:19], v[2:3]
	v_mov_b64_e32 v[30:31], v[2:3]
	v_mov_b64_e32 v[34:35], v[2:3]
	v_mov_b64_e32 v[46:47], v[2:3]
	v_mov_b64_e32 v[50:51], v[2:3]
	v_mov_b64_e32 v[62:63], v[2:3]
	v_mov_b64_e32 v[66:67], v[2:3]
	v_mov_b64_e32 v[70:71], v[2:3]
	v_mov_b64_e32 v[74:75], v[2:3]
	v_mov_b64_e32 v[86:87], v[2:3]
	v_mov_b64_e32 v[90:91], v[2:3]
	v_mov_b64_e32 v[102:103], v[2:3]
	v_mov_b64_e32 v[106:107], v[2:3]
	v_mov_b64_e32 v[118:119], v[2:3]
	v_mov_b64_e32 v[122:123], v[2:3]
	v_mov_b64_e32 v[78:79], v[2:3]
	v_mov_b64_e32 v[82:83], v[2:3]
	v_mov_b64_e32 v[94:95], v[2:3]
	v_mov_b64_e32 v[98:99], v[2:3]
	v_mov_b64_e32 v[110:111], v[2:3]
	v_mov_b64_e32 v[114:115], v[2:3]
	v_mov_b64_e32 v[126:127], v[2:3]
	v_mov_b64_e32 v[130:131], v[2:3]
	s_addc_u32 s17, s73, s3
	s_mov_b32 s56, 0
	v_mov_b64_e32 v[4:5], v[0:1]
	v_mov_b64_e32 v[8:9], v[0:1]
	v_mov_b64_e32 v[20:21], v[0:1]
	v_mov_b64_e32 v[24:25], v[0:1]
	v_mov_b64_e32 v[36:37], v[0:1]
	v_mov_b64_e32 v[40:41], v[0:1]
	v_mov_b64_e32 v[52:53], v[0:1]
	v_mov_b64_e32 v[56:57], v[0:1]
	v_mov_b64_e32 v[12:13], v[0:1]
	v_mov_b64_e32 v[16:17], v[0:1]
	v_mov_b64_e32 v[28:29], v[0:1]
	v_mov_b64_e32 v[32:33], v[0:1]
	v_mov_b64_e32 v[44:45], v[0:1]
	v_mov_b64_e32 v[48:49], v[0:1]
	v_mov_b64_e32 v[60:61], v[0:1]
	v_mov_b64_e32 v[64:65], v[0:1]
	v_mov_b64_e32 v[68:69], v[0:1]
	v_mov_b64_e32 v[72:73], v[0:1]
	v_mov_b64_e32 v[84:85], v[0:1]
	v_mov_b64_e32 v[88:89], v[0:1]
	v_mov_b64_e32 v[100:101], v[0:1]
	v_mov_b64_e32 v[104:105], v[0:1]
	v_mov_b64_e32 v[116:117], v[0:1]
	v_mov_b64_e32 v[120:121], v[0:1]
	v_mov_b64_e32 v[76:77], v[0:1]
	v_mov_b64_e32 v[80:81], v[0:1]
	v_mov_b64_e32 v[92:93], v[0:1]
	v_mov_b64_e32 v[96:97], v[0:1]
	v_mov_b64_e32 v[108:109], v[0:1]
	v_mov_b64_e32 v[112:113], v[0:1]
	v_mov_b64_e32 v[124:125], v[0:1]
	v_mov_b64_e32 v[128:129], v[0:1]
	s_movk_i32 s96, 0x5000
	s_branch .LBB0_340

.LBB0_341:
	s_cmpk_eq_i32 s40, 0x400
	s_cselect_b64 s[52:53], -1, 0
	s_and_b64 s[52:53], s[2:3], s[52:53]
	s_and_b64 s[54:55], s[52:53], exec
	s_cselect_b32 s82, s63, s57
	s_add_u32 s83, s18, s40
	s_addc_u32 s87, s19, s41
	s_cmpk_eq_i32 s40, 0x400
	s_cselect_b64 s[54:55], -1, 0
	s_and_b64 s[54:55], s[54:55], exec
	s_cselect_b32 s54, s82, s83
	s_and_b64 s[82:83], s[52:53], exec
	s_cselect_b32 s55, s66, s58
	s_cmpk_eq_i32 s40, 0x400
	v_add_u32_e32 v145, s6, v143
	s_cselect_b64 s[82:83], -1, 0
	ds_read_b128 v[146:149], v145
	ds_read_b128 v[150:153], v145 offset:1024
	ds_read_b128 v[158:161], v145 offset:2048
	ds_read_b128 v[162:165], v145 offset:3072
	v_add_u32_e32 v145, s7, v143
	s_and_b64 s[94:95], s[82:83], exec
	ds_read_b128 v[196:199], v145
	ds_read_b128 v[200:203], v145 offset:1024
	ds_read_b128 v[204:207], v145 offset:2048
	ds_read_b128 v[208:211], v145 offset:3072
	s_cselect_b32 s55, s55, s87
	s_and_b64 s[82:83], s[82:83], s[8:9]
	s_and_b64 s[82:83], s[82:83], exec
	s_cselect_b32 s83, 0, s40
	s_cselect_b32 s82, 0, s41
	s_add_u32 s83, s59, s83
	s_addc_u32 s82, s62, s82
	s_and_b64 s[52:53], s[52:53], exec
	s_cselect_b32 s53, s84, s82
	s_cselect_b32 s52, s70, s83
	v_lshl_add_u64 v[154:155], v[138:139], 0, s[40:41]
	s_add_i32 s87, s85, 0
	v_lshl_add_u64 v[154:155], v[154:155], 0, s[78:79]
	s_add_i32 m0, s87, 0xc000
	ds_read_b128 v[212:215], v144
	ds_read_b128 v[216:219], v144 offset:1024
	ds_read_b128 v[220:223], v144 offset:2048
	ds_read_b128 v[224:227], v144 offset:3072
	ds_read_b128 v[228:231], v144 offset:4096
	ds_read_b128 v[232:235], v144 offset:5120
	ds_read_b128 v[236:239], v144 offset:6144
	ds_read_b128 v[240:243], v144 offset:7168
	global_load_lds_dwordx4 v[154:155], off
	v_lshl_add_u64 v[154:155], v[136:137], 0, s[40:41]
	v_lshl_add_u64 v[154:155], v[154:155], 0, s[78:79]
	s_add_i32 m0, s87, 0xe000
	s_nop 0
	global_load_lds_dwordx4 v[154:155], off
	s_waitcnt vmcnt(8)
	s_waitcnt lgkmcnt(0)
	s_setprio 1
	s_barrier
	s_waitcnt lgkmcnt(0)
	v_mfma_f32_16x16x32_bf16 v[128:131], v[146:149], v[212:215], v[128:131]
	v_mfma_f32_16x16x32_bf16 v[124:127], v[158:161], v[212:215], v[124:127]
	v_mfma_f32_16x16x32_bf16 v[112:115], v[146:149], v[220:223], v[112:115]
	v_mfma_f32_16x16x32_bf16 v[108:111], v[158:161], v[220:223], v[108:111]
	v_mfma_f32_16x16x32_bf16 v[96:99], v[146:149], v[228:231], v[96:99]
	v_mfma_f32_16x16x32_bf16 v[92:95], v[158:161], v[228:231], v[92:95]
	v_mfma_f32_16x16x32_bf16 v[80:83], v[146:149], v[236:239], v[80:83]
	v_mfma_f32_16x16x32_bf16 v[76:79], v[158:161], v[236:239], v[76:79]
	s_setprio 0
	s_setprio 1
	v_mfma_f32_16x16x32_bf16 v[128:131], v[150:153], v[216:219], v[128:131]
	v_mfma_f32_16x16x32_bf16 v[124:127], v[162:165], v[216:219], v[124:127]
	v_mfma_f32_16x16x32_bf16 v[112:115], v[150:153], v[224:227], v[112:115]
	v_mfma_f32_16x16x32_bf16 v[108:111], v[162:165], v[224:227], v[108:111]
	v_mfma_f32_16x16x32_bf16 v[96:99], v[150:153], v[232:235], v[96:99]
	v_mfma_f32_16x16x32_bf16 v[92:95], v[162:165], v[232:235], v[92:95]
	v_mfma_f32_16x16x32_bf16 v[80:83], v[150:153], v[240:243], v[80:83]
	v_mfma_f32_16x16x32_bf16 v[76:79], v[162:165], v[240:243], v[76:79]
	s_setprio 0
	s_setprio 1
	v_mfma_f32_16x16x32_bf16 v[120:123], v[196:199], v[212:215], v[120:123]
	v_mfma_f32_16x16x32_bf16 v[116:119], v[204:207], v[212:215], v[116:119]
	v_mfma_f32_16x16x32_bf16 v[104:107], v[196:199], v[220:223], v[104:107]
	v_mfma_f32_16x16x32_bf16 v[100:103], v[204:207], v[220:223], v[100:103]
	v_mfma_f32_16x16x32_bf16 v[88:91], v[196:199], v[228:231], v[88:91]
	v_mfma_f32_16x16x32_bf16 v[84:87], v[204:207], v[228:231], v[84:87]
	v_mfma_f32_16x16x32_bf16 v[72:75], v[196:199], v[236:239], v[72:75]
	v_mfma_f32_16x16x32_bf16 v[68:71], v[204:207], v[236:239], v[68:71]
	s_setprio 0
	s_setprio 1
	v_mfma_f32_16x16x32_bf16 v[120:123], v[200:203], v[216:219], v[120:123]
	v_mfma_f32_16x16x32_bf16 v[116:119], v[208:211], v[216:219], v[116:119]
	v_mfma_f32_16x16x32_bf16 v[104:107], v[200:203], v[224:227], v[104:107]
	v_mfma_f32_16x16x32_bf16 v[100:103], v[208:211], v[224:227], v[100:103]
	v_mfma_f32_16x16x32_bf16 v[88:91], v[200:203], v[232:235], v[88:91]
	v_mfma_f32_16x16x32_bf16 v[84:87], v[208:211], v[232:235], v[84:87]
	v_mfma_f32_16x16x32_bf16 v[72:75], v[200:203], v[240:243], v[72:75]
	v_mfma_f32_16x16x32_bf16 v[68:71], v[208:211], v[240:243], v[68:71]
	s_setprio 0
	s_barrier
	s_add_i32 s82, s6, s85
	v_lshl_add_u64 v[154:155], s[52:53], 0, v[132:133]
	s_mov_b32 m0, s82
	ds_read_b128 v[212:215], v144 offset:16384
	ds_read_b128 v[216:219], v144 offset:17408
	ds_read_b128 v[220:223], v144 offset:18432
	ds_read_b128 v[224:227], v144 offset:19456
	ds_read_b128 v[228:231], v144 offset:20480
	ds_read_b128 v[232:235], v144 offset:21504
	ds_read_b128 v[236:239], v144 offset:22528
	ds_read_b128 v[240:243], v144 offset:23552
	global_load_lds_dwordx4 v[154:155], off
	s_add_i32 m0, s82, 0x2000
	s_add_u32 s82, s52, 0x20000
	v_lshl_add_u64 v[176:177], s[52:53], 0, v[134:135]
	s_addc_u32 s83, s53, 0
	s_add_i32 s93, s7, s85
	global_load_lds_dwordx4 v[176:177], off
	v_lshl_add_u64 v[178:179], s[82:83], 0, v[132:133]
	s_mov_b32 m0, s93
	v_lshl_add_u64 v[194:195], s[54:55], 0, v[2:3]
	global_load_lds_dwordx4 v[178:179], off
	v_lshl_add_u64 v[178:179], s[82:83], 0, v[134:135]
	s_add_i32 m0, s93, 0x2000
	s_nop 0
	global_load_lds_dwordx4 v[178:179], off
	v_lshl_add_u64 v[178:179], s[54:55], 0, v[0:1]
	s_mov_b32 m0, s87
	s_nop 0
	global_load_lds_dwordx4 v[178:179], off
	s_add_i32 m0, s87, 0x2000
	s_nop 0
	global_load_lds_dwordx4 v[194:195], off
	s_waitcnt vmcnt(8)
	s_waitcnt lgkmcnt(0)
	s_setprio 1
	s_barrier
	s_waitcnt lgkmcnt(0)
	v_mfma_f32_16x16x32_bf16 v[64:67], v[146:149], v[212:215], v[64:67]
	v_mfma_f32_16x16x32_bf16 v[60:63], v[158:161], v[212:215], v[60:63]
	v_mfma_f32_16x16x32_bf16 v[48:51], v[146:149], v[220:223], v[48:51]
	v_mfma_f32_16x16x32_bf16 v[44:47], v[158:161], v[220:223], v[44:47]
	v_mfma_f32_16x16x32_bf16 v[32:35], v[146:149], v[228:231], v[32:35]
	v_mfma_f32_16x16x32_bf16 v[28:31], v[158:161], v[228:231], v[28:31]
	v_mfma_f32_16x16x32_bf16 v[16:19], v[146:149], v[236:239], v[16:19]
	v_mfma_f32_16x16x32_bf16 v[12:15], v[158:161], v[236:239], v[12:15]
	s_setprio 0
	s_setprio 1
	v_mfma_f32_16x16x32_bf16 v[64:67], v[150:153], v[216:219], v[64:67]
	v_mfma_f32_16x16x32_bf16 v[60:63], v[162:165], v[216:219], v[60:63]
	v_mfma_f32_16x16x32_bf16 v[48:51], v[150:153], v[224:227], v[48:51]
	v_mfma_f32_16x16x32_bf16 v[44:47], v[162:165], v[224:227], v[44:47]
	v_mfma_f32_16x16x32_bf16 v[32:35], v[150:153], v[232:235], v[32:35]
	v_mfma_f32_16x16x32_bf16 v[28:31], v[162:165], v[232:235], v[28:31]
	v_mfma_f32_16x16x32_bf16 v[16:19], v[150:153], v[240:243], v[16:19]
	v_mfma_f32_16x16x32_bf16 v[12:15], v[162:165], v[240:243], v[12:15]
	s_setprio 0
	s_setprio 1
	v_mfma_f32_16x16x32_bf16 v[56:59], v[196:199], v[212:215], v[56:59]
	v_mfma_f32_16x16x32_bf16 v[52:55], v[204:207], v[212:215], v[52:55]
	v_mfma_f32_16x16x32_bf16 v[40:43], v[196:199], v[220:223], v[40:43]
	v_mfma_f32_16x16x32_bf16 v[36:39], v[204:207], v[220:223], v[36:39]
	v_mfma_f32_16x16x32_bf16 v[24:27], v[196:199], v[228:231], v[24:27]
	v_mfma_f32_16x16x32_bf16 v[20:23], v[204:207], v[228:231], v[20:23]
	v_mfma_f32_16x16x32_bf16 v[8:11], v[196:199], v[236:239], v[8:11]
	v_mfma_f32_16x16x32_bf16 v[4:7], v[204:207], v[236:239], v[4:7]
	s_setprio 0
	s_setprio 1
	v_mfma_f32_16x16x32_bf16 v[56:59], v[200:203], v[216:219], v[56:59]
	v_mfma_f32_16x16x32_bf16 v[52:55], v[208:211], v[216:219], v[52:55]
	v_mfma_f32_16x16x32_bf16 v[40:43], v[200:203], v[224:227], v[40:43]
	v_mfma_f32_16x16x32_bf16 v[36:39], v[208:211], v[224:227], v[36:39]
	v_mfma_f32_16x16x32_bf16 v[24:27], v[200:203], v[232:235], v[24:27]
	v_mfma_f32_16x16x32_bf16 v[20:23], v[208:211], v[232:235], v[20:23]
	v_mfma_f32_16x16x32_bf16 v[8:11], v[200:203], v[240:243], v[8:11]
	v_mfma_f32_16x16x32_bf16 v[4:7], v[208:211], v[240:243], v[4:7]
	s_setprio 0
	s_barrier
	v_add_u32_e32 v145, s10, v143
	ds_read_b128 v[146:149], v145
	ds_read_b128 v[150:153], v145 offset:1024
	ds_read_b128 v[158:161], v145 offset:2048
	ds_read_b128 v[162:165], v145 offset:3072
	v_add_u32_e32 v145, s11, v143
	ds_read_b128 v[196:199], v145
	ds_read_b128 v[200:203], v145 offset:1024
	ds_read_b128 v[204:207], v145 offset:2048
	ds_read_b128 v[208:211], v145 offset:3072
	s_add_u32 s54, s54, 0x20000
	s_addc_u32 s55, s55, 0
	v_lshl_add_u64 v[244:245], s[54:55], 0, v[0:1]
	s_add_i32 m0, s87, 0x4000
	ds_read_b128 v[212:215], v144 offset:32768
	ds_read_b128 v[216:219], v144 offset:33792
	ds_read_b128 v[220:223], v144 offset:34816
	ds_read_b128 v[224:227], v144 offset:35840
	ds_read_b128 v[228:231], v144 offset:36864
	ds_read_b128 v[232:235], v144 offset:37888
	ds_read_b128 v[236:239], v144 offset:38912
	ds_read_b128 v[240:243], v144 offset:39936
	global_load_lds_dwordx4 v[244:245], off
	v_lshl_add_u64 v[244:245], s[54:55], 0, v[2:3]
	s_add_i32 m0, s87, 0x6000
	s_nop 0
	global_load_lds_dwordx4 v[244:245], off
	s_waitcnt vmcnt(8)
	s_waitcnt lgkmcnt(0)
	s_setprio 1
	s_barrier
	s_waitcnt lgkmcnt(0)
	v_mfma_f32_16x16x32_bf16 v[128:131], v[146:149], v[212:215], v[128:131]
	v_mfma_f32_16x16x32_bf16 v[124:127], v[158:161], v[212:215], v[124:127]
	v_mfma_f32_16x16x32_bf16 v[112:115], v[146:149], v[220:223], v[112:115]
	v_mfma_f32_16x16x32_bf16 v[108:111], v[158:161], v[220:223], v[108:111]
	v_mfma_f32_16x16x32_bf16 v[96:99], v[146:149], v[228:231], v[96:99]
	v_mfma_f32_16x16x32_bf16 v[92:95], v[158:161], v[228:231], v[92:95]
	v_mfma_f32_16x16x32_bf16 v[80:83], v[146:149], v[236:239], v[80:83]
	v_mfma_f32_16x16x32_bf16 v[76:79], v[158:161], v[236:239], v[76:79]
	s_setprio 0
	s_setprio 1
	v_mfma_f32_16x16x32_bf16 v[128:131], v[150:153], v[216:219], v[128:131]
	v_mfma_f32_16x16x32_bf16 v[124:127], v[162:165], v[216:219], v[124:127]
	v_mfma_f32_16x16x32_bf16 v[112:115], v[150:153], v[224:227], v[112:115]
	v_mfma_f32_16x16x32_bf16 v[108:111], v[162:165], v[224:227], v[108:111]
	v_mfma_f32_16x16x32_bf16 v[96:99], v[150:153], v[232:235], v[96:99]
	v_mfma_f32_16x16x32_bf16 v[92:95], v[162:165], v[232:235], v[92:95]
	v_mfma_f32_16x16x32_bf16 v[80:83], v[150:153], v[240:243], v[80:83]
	v_mfma_f32_16x16x32_bf16 v[76:79], v[162:165], v[240:243], v[76:79]
	s_setprio 0
	s_setprio 1
	v_mfma_f32_16x16x32_bf16 v[120:123], v[196:199], v[212:215], v[120:123]
	v_mfma_f32_16x16x32_bf16 v[116:119], v[204:207], v[212:215], v[116:119]
	v_mfma_f32_16x16x32_bf16 v[104:107], v[196:199], v[220:223], v[104:107]
	v_mfma_f32_16x16x32_bf16 v[100:103], v[204:207], v[220:223], v[100:103]
	v_mfma_f32_16x16x32_bf16 v[88:91], v[196:199], v[228:231], v[88:91]
	v_mfma_f32_16x16x32_bf16 v[84:87], v[204:207], v[228:231], v[84:87]
	v_mfma_f32_16x16x32_bf16 v[72:75], v[196:199], v[236:239], v[72:75]
	v_mfma_f32_16x16x32_bf16 v[68:71], v[204:207], v[236:239], v[68:71]
	s_setprio 0
	s_setprio 1
	v_mfma_f32_16x16x32_bf16 v[120:123], v[200:203], v[216:219], v[120:123]
	v_mfma_f32_16x16x32_bf16 v[116:119], v[208:211], v[216:219], v[116:119]
	v_mfma_f32_16x16x32_bf16 v[104:107], v[200:203], v[224:227], v[104:107]
	v_mfma_f32_16x16x32_bf16 v[100:103], v[208:211], v[224:227], v[100:103]
	v_mfma_f32_16x16x32_bf16 v[88:91], v[200:203], v[232:235], v[88:91]
	v_mfma_f32_16x16x32_bf16 v[84:87], v[208:211], v[232:235], v[84:87]
	v_mfma_f32_16x16x32_bf16 v[72:75], v[200:203], v[240:243], v[72:75]
	v_mfma_f32_16x16x32_bf16 v[68:71], v[208:211], v[240:243], v[68:71]
	s_setprio 0
	s_barrier
	s_add_i32 s54, s10, s85
	v_lshl_add_u64 v[154:155], v[154:155], 0, s[24:25]
	s_mov_b32 m0, s54
	ds_read_b128 v[212:215], v144 offset:49152
	ds_read_b128 v[216:219], v144 offset:50176
	ds_read_b128 v[220:223], v144 offset:51200
	ds_read_b128 v[224:227], v144 offset:52224
	ds_read_b128 v[228:231], v144 offset:53248
	ds_read_b128 v[232:235], v144 offset:54272
	ds_read_b128 v[236:239], v144 offset:55296
	ds_read_b128 v[240:243], v144 offset:56320
	global_load_lds_dwordx4 v[154:155], off
	s_add_i32 m0, s54, 0x2000
	s_add_u32 s52, s52, 0x20080
	v_lshl_add_u64 v[154:155], v[176:177], 0, s[24:25]
	s_addc_u32 s53, s53, 0
	s_add_i32 s54, s11, s85
	global_load_lds_dwordx4 v[154:155], off
	v_lshl_add_u64 v[154:155], s[52:53], 0, v[132:133]
	s_mov_b32 m0, s54
	s_nop 0
	global_load_lds_dwordx4 v[154:155], off
	v_lshl_add_u64 v[154:155], s[52:53], 0, v[134:135]
	s_add_i32 m0, s54, 0x2000
	s_nop 0
	global_load_lds_dwordx4 v[154:155], off
	v_lshl_add_u64 v[154:155], v[178:179], 0, s[24:25]
	s_add_i32 m0, s87, 0x8000
	s_nop 0
	global_load_lds_dwordx4 v[154:155], off
	v_lshl_add_u64 v[154:155], v[194:195], 0, s[24:25]
	s_add_i32 m0, s87, 0xa000
	s_nop 0
	global_load_lds_dwordx4 v[154:155], off
	s_waitcnt vmcnt(8)
	s_waitcnt lgkmcnt(0)
	s_setprio 1
	s_barrier
	s_waitcnt lgkmcnt(0)
	v_mfma_f32_16x16x32_bf16 v[64:67], v[146:149], v[212:215], v[64:67]
	v_mfma_f32_16x16x32_bf16 v[60:63], v[158:161], v[212:215], v[60:63]
	v_mfma_f32_16x16x32_bf16 v[48:51], v[146:149], v[220:223], v[48:51]
	v_mfma_f32_16x16x32_bf16 v[44:47], v[158:161], v[220:223], v[44:47]
	v_mfma_f32_16x16x32_bf16 v[32:35], v[146:149], v[228:231], v[32:35]
	v_mfma_f32_16x16x32_bf16 v[28:31], v[158:161], v[228:231], v[28:31]
	v_mfma_f32_16x16x32_bf16 v[16:19], v[146:149], v[236:239], v[16:19]
	v_mfma_f32_16x16x32_bf16 v[12:15], v[158:161], v[236:239], v[12:15]
	s_setprio 0
	s_setprio 1
	v_mfma_f32_16x16x32_bf16 v[64:67], v[150:153], v[216:219], v[64:67]
	v_mfma_f32_16x16x32_bf16 v[60:63], v[162:165], v[216:219], v[60:63]
	v_mfma_f32_16x16x32_bf16 v[48:51], v[150:153], v[224:227], v[48:51]
	v_mfma_f32_16x16x32_bf16 v[44:47], v[162:165], v[224:227], v[44:47]
	v_mfma_f32_16x16x32_bf16 v[32:35], v[150:153], v[232:235], v[32:35]
	v_mfma_f32_16x16x32_bf16 v[28:31], v[162:165], v[232:235], v[28:31]
	v_mfma_f32_16x16x32_bf16 v[16:19], v[150:153], v[240:243], v[16:19]
	v_mfma_f32_16x16x32_bf16 v[12:15], v[162:165], v[240:243], v[12:15]
	s_setprio 0
	s_setprio 1
	v_mfma_f32_16x16x32_bf16 v[56:59], v[196:199], v[212:215], v[56:59]
	v_mfma_f32_16x16x32_bf16 v[52:55], v[204:207], v[212:215], v[52:55]
	v_mfma_f32_16x16x32_bf16 v[40:43], v[196:199], v[220:223], v[40:43]
	v_mfma_f32_16x16x32_bf16 v[36:39], v[204:207], v[220:223], v[36:39]
	v_mfma_f32_16x16x32_bf16 v[24:27], v[196:199], v[228:231], v[24:27]
	v_mfma_f32_16x16x32_bf16 v[20:23], v[204:207], v[228:231], v[20:23]
	v_mfma_f32_16x16x32_bf16 v[8:11], v[196:199], v[236:239], v[8:11]
	v_mfma_f32_16x16x32_bf16 v[4:7], v[204:207], v[236:239], v[4:7]
	s_setprio 0
	s_setprio 1
	v_mfma_f32_16x16x32_bf16 v[56:59], v[200:203], v[216:219], v[56:59]
	v_mfma_f32_16x16x32_bf16 v[52:55], v[208:211], v[216:219], v[52:55]
	v_mfma_f32_16x16x32_bf16 v[40:43], v[200:203], v[224:227], v[40:43]
	v_mfma_f32_16x16x32_bf16 v[36:39], v[208:211], v[224:227], v[36:39]
	v_mfma_f32_16x16x32_bf16 v[24:27], v[200:203], v[232:235], v[24:27]
	v_mfma_f32_16x16x32_bf16 v[20:23], v[208:211], v[232:235], v[20:23]
	v_mfma_f32_16x16x32_bf16 v[8:11], v[200:203], v[240:243], v[8:11]
	v_mfma_f32_16x16x32_bf16 v[4:7], v[208:211], v[240:243], v[4:7]
	s_setprio 0
	s_barrier
	s_add_i32 s86, s86, 2
	s_add_u32 s40, s40, 0x100
	s_addc_u32 s41, s41, 0
	s_cmp_gt_u32 s86, 5
	s_cbranch_scc0 .LBB0_341
	s_cmp_eq_u32 s20, 2
	s_movk_i32 s58, 0x21ff
	s_mov_b64 s[8:9], 0x800
	s_mov_b64 s[18:19], 0x200
	s_cbranch_scc0 .LBB0_346
	s_waitcnt vmcnt(0)
	s_cmpk_gt_u32 s67, 0xff
	s_cbranch_scc1 .LBB0_345
	s_barrier

.LBB0_465:
	s_add_u32 s17, s18, 0xf1598080
	s_addc_u32 s20, s19, -1
	s_cmp_lg_u32 s16, 4
	s_cselect_b32 s17, s17, 0
	s_cselect_b32 s20, s20, 0
	s_add_u32 s42, s2, s17
	s_addc_u32 s43, s3, s20
	s_add_i32 s48, 0, 0x10000
	s_add_u32 s40, s8, s17
	v_add_u32_e32 v143, s48, v141
	s_addc_u32 s41, s9, s20
	s_add_i32 s17, 0, 0x14000
	ds_read_b128 v[144:147], v143
	ds_read_b128 v[148:151], v143 offset:1024
	ds_read_b128 v[152:155], v143 offset:2048
	ds_read_b128 v[158:161], v143 offset:3072
	v_add_u32_e32 v143, s17, v141
	ds_read_b128 v[162:165], v143
	ds_read_b128 v[196:199], v143 offset:1024
	ds_read_b128 v[200:203], v143 offset:2048
	ds_read_b128 v[204:207], v143 offset:3072
	v_lshl_add_u64 v[240:241], v[138:139], 0, s[18:19]
	s_add_i32 m0, s6, 0xc000
	ds_read_b128 v[208:211], v142
	ds_read_b128 v[212:215], v142 offset:1024
	ds_read_b128 v[216:219], v142 offset:2048
	ds_read_b128 v[220:223], v142 offset:3072
	ds_read_b128 v[224:227], v142 offset:4096
	ds_read_b128 v[228:231], v142 offset:5120
	ds_read_b128 v[232:235], v142 offset:6144
	ds_read_b128 v[236:239], v142 offset:7168
	global_load_lds_dwordx4 v[240:241], off
	v_lshl_add_u64 v[240:241], v[136:137], 0, s[18:19]
	s_add_i32 m0, s6, 0xe000
	s_nop 0
	global_load_lds_dwordx4 v[240:241], off
	s_waitcnt vmcnt(8)
	s_waitcnt lgkmcnt(0)
	s_setprio 1
	s_barrier
	s_waitcnt lgkmcnt(0)
	v_mfma_f32_16x16x32_bf16 v[126:129], v[144:147], v[208:211], v[126:129]
	v_mfma_f32_16x16x32_bf16 v[122:125], v[152:155], v[208:211], v[122:125]
	v_mfma_f32_16x16x32_bf16 v[110:113], v[144:147], v[216:219], v[110:113]
	v_mfma_f32_16x16x32_bf16 v[106:109], v[152:155], v[216:219], v[106:109]
	v_mfma_f32_16x16x32_bf16 v[94:97], v[144:147], v[224:227], v[94:97]
	v_mfma_f32_16x16x32_bf16 v[90:93], v[152:155], v[224:227], v[90:93]
	v_mfma_f32_16x16x32_bf16 v[78:81], v[144:147], v[232:235], v[78:81]
	v_mfma_f32_16x16x32_bf16 v[74:77], v[152:155], v[232:235], v[74:77]
	s_setprio 0
	s_setprio 1
	v_mfma_f32_16x16x32_bf16 v[126:129], v[148:151], v[212:215], v[126:129]
	v_mfma_f32_16x16x32_bf16 v[122:125], v[158:161], v[212:215], v[122:125]
	v_mfma_f32_16x16x32_bf16 v[110:113], v[148:151], v[220:223], v[110:113]
	v_mfma_f32_16x16x32_bf16 v[106:109], v[158:161], v[220:223], v[106:109]
	v_mfma_f32_16x16x32_bf16 v[94:97], v[148:151], v[228:231], v[94:97]
	v_mfma_f32_16x16x32_bf16 v[90:93], v[158:161], v[228:231], v[90:93]
	v_mfma_f32_16x16x32_bf16 v[78:81], v[148:151], v[236:239], v[78:81]
	v_mfma_f32_16x16x32_bf16 v[74:77], v[158:161], v[236:239], v[74:77]
	s_setprio 0
	s_setprio 1
	v_mfma_f32_16x16x32_bf16 v[118:121], v[162:165], v[208:211], v[118:121]
	v_mfma_f32_16x16x32_bf16 v[114:117], v[200:203], v[208:211], v[114:117]
	v_mfma_f32_16x16x32_bf16 v[102:105], v[162:165], v[216:219], v[102:105]
	v_mfma_f32_16x16x32_bf16 v[98:101], v[200:203], v[216:219], v[98:101]
	v_mfma_f32_16x16x32_bf16 v[86:89], v[162:165], v[224:227], v[86:89]
	v_mfma_f32_16x16x32_bf16 v[82:85], v[200:203], v[224:227], v[82:85]
	v_mfma_f32_16x16x32_bf16 v[70:73], v[162:165], v[232:235], v[70:73]
	v_mfma_f32_16x16x32_bf16 v[66:69], v[200:203], v[232:235], v[66:69]
	s_setprio 0
	s_setprio 1
	v_mfma_f32_16x16x32_bf16 v[118:121], v[196:199], v[212:215], v[118:121]
	v_mfma_f32_16x16x32_bf16 v[114:117], v[204:207], v[212:215], v[114:117]
	v_mfma_f32_16x16x32_bf16 v[102:105], v[196:199], v[220:223], v[102:105]
	v_mfma_f32_16x16x32_bf16 v[98:101], v[204:207], v[220:223], v[98:101]
	v_mfma_f32_16x16x32_bf16 v[86:89], v[196:199], v[228:231], v[86:89]
	v_mfma_f32_16x16x32_bf16 v[82:85], v[204:207], v[228:231], v[82:85]
	v_mfma_f32_16x16x32_bf16 v[70:73], v[196:199], v[236:239], v[70:73]
	v_mfma_f32_16x16x32_bf16 v[66:69], v[204:207], v[236:239], v[66:69]
	s_setprio 0
	s_barrier
	s_add_i32 s20, s48, s5
	v_lshl_add_u64 v[240:241], s[40:41], 0, v[0:1]
	s_mov_b32 m0, s20
	ds_read_b128 v[208:211], v142 offset:16384
	ds_read_b128 v[212:215], v142 offset:17408
	ds_read_b128 v[216:219], v142 offset:18432
	ds_read_b128 v[220:223], v142 offset:19456
	ds_read_b128 v[224:227], v142 offset:20480
	ds_read_b128 v[228:231], v142 offset:21504
	ds_read_b128 v[232:235], v142 offset:22528
	ds_read_b128 v[236:239], v142 offset:23552
	global_load_lds_dwordx4 v[240:241], off
	s_add_i32 m0, s20, 0x2000
	s_add_u32 s48, s40, 0x20000
	v_lshl_add_u64 v[242:243], s[40:41], 0, v[134:135]
	s_addc_u32 s49, s41, 0
	s_add_i32 s17, s17, s5
	global_load_lds_dwordx4 v[242:243], off
	v_lshl_add_u64 v[244:245], s[48:49], 0, v[0:1]
	s_mov_b32 m0, s17
	v_lshl_add_u64 v[246:247], s[42:43], 0, v[132:133]
	global_load_lds_dwordx4 v[244:245], off
	v_lshl_add_u64 v[244:245], s[48:49], 0, v[134:135]
	s_add_i32 m0, s17, 0x2000
	s_nop 0
	global_load_lds_dwordx4 v[244:245], off
	v_lshl_add_u64 v[244:245], s[42:43], 0, v[130:131]
	s_mov_b32 m0, s6
	s_nop 0
	global_load_lds_dwordx4 v[244:245], off
	s_mov_b32 m0, s7
	s_nop 0
	global_load_lds_dwordx4 v[246:247], off
	s_waitcnt vmcnt(8)
	s_waitcnt lgkmcnt(0)
	s_setprio 1
	s_barrier
	s_waitcnt lgkmcnt(0)
	v_mfma_f32_16x16x32_bf16 v[62:65], v[144:147], v[208:211], v[62:65]
	v_mfma_f32_16x16x32_bf16 v[58:61], v[152:155], v[208:211], v[58:61]
	v_mfma_f32_16x16x32_bf16 v[46:49], v[144:147], v[216:219], v[46:49]
	v_mfma_f32_16x16x32_bf16 v[42:45], v[152:155], v[216:219], v[42:45]
	v_mfma_f32_16x16x32_bf16 v[30:33], v[144:147], v[224:227], v[30:33]
	v_mfma_f32_16x16x32_bf16 v[26:29], v[152:155], v[224:227], v[26:29]
	v_mfma_f32_16x16x32_bf16 v[14:17], v[144:147], v[232:235], v[14:17]
	v_mfma_f32_16x16x32_bf16 v[10:13], v[152:155], v[232:235], v[10:13]
	s_setprio 0
	s_setprio 1
	v_mfma_f32_16x16x32_bf16 v[62:65], v[148:151], v[212:215], v[62:65]
	v_mfma_f32_16x16x32_bf16 v[58:61], v[158:161], v[212:215], v[58:61]
	v_mfma_f32_16x16x32_bf16 v[46:49], v[148:151], v[220:223], v[46:49]
	v_mfma_f32_16x16x32_bf16 v[42:45], v[158:161], v[220:223], v[42:45]
	v_mfma_f32_16x16x32_bf16 v[30:33], v[148:151], v[228:231], v[30:33]
	v_mfma_f32_16x16x32_bf16 v[26:29], v[158:161], v[228:231], v[26:29]
	v_mfma_f32_16x16x32_bf16 v[14:17], v[148:151], v[236:239], v[14:17]
	v_mfma_f32_16x16x32_bf16 v[10:13], v[158:161], v[236:239], v[10:13]
	s_setprio 0
	s_setprio 1
	v_mfma_f32_16x16x32_bf16 v[54:57], v[162:165], v[208:211], v[54:57]
	v_mfma_f32_16x16x32_bf16 v[50:53], v[200:203], v[208:211], v[50:53]
	v_mfma_f32_16x16x32_bf16 v[38:41], v[162:165], v[216:219], v[38:41]
	v_mfma_f32_16x16x32_bf16 v[34:37], v[200:203], v[216:219], v[34:37]
	v_mfma_f32_16x16x32_bf16 v[22:25], v[162:165], v[224:227], v[22:25]
	v_mfma_f32_16x16x32_bf16 v[18:21], v[200:203], v[224:227], v[18:21]
	v_mfma_f32_16x16x32_bf16 v[6:9], v[162:165], v[232:235], v[6:9]
	v_mfma_f32_16x16x32_bf16 v[2:5], v[200:203], v[232:235], v[2:5]
	s_setprio 0
	s_setprio 1
	v_mfma_f32_16x16x32_bf16 v[54:57], v[196:199], v[212:215], v[54:57]
	v_mfma_f32_16x16x32_bf16 v[50:53], v[204:207], v[212:215], v[50:53]
	v_mfma_f32_16x16x32_bf16 v[38:41], v[196:199], v[220:223], v[38:41]
	v_mfma_f32_16x16x32_bf16 v[34:37], v[204:207], v[220:223], v[34:37]
	v_mfma_f32_16x16x32_bf16 v[22:25], v[196:199], v[228:231], v[22:25]
	v_mfma_f32_16x16x32_bf16 v[18:21], v[204:207], v[228:231], v[18:21]
	v_mfma_f32_16x16x32_bf16 v[6:9], v[196:199], v[236:239], v[6:9]
	v_mfma_f32_16x16x32_bf16 v[2:5], v[204:207], v[236:239], v[2:5]
	s_setprio 0
	s_barrier
	s_add_i32 s17, 0, 0x18000
	v_add_u32_e32 v143, s17, v141
	s_add_i32 s20, 0, 0x1c000
	ds_read_b128 v[144:147], v143
	ds_read_b128 v[148:151], v143 offset:1024
	ds_read_b128 v[152:155], v143 offset:2048
	ds_read_b128 v[158:161], v143 offset:3072
	v_add_u32_e32 v143, s20, v141
	ds_read_b128 v[162:165], v143
	ds_read_b128 v[196:199], v143 offset:1024
	ds_read_b128 v[200:203], v143 offset:2048
	ds_read_b128 v[204:207], v143 offset:3072
	s_add_u32 s42, s42, 0x20000
	s_addc_u32 s43, s43, 0
	s_mov_b32 m0, s10
	v_lshl_add_u64 v[248:249], s[42:43], 0, v[130:131]
	ds_read_b128 v[208:211], v142 offset:32768
	ds_read_b128 v[212:215], v142 offset:33792
	ds_read_b128 v[216:219], v142 offset:34816
	ds_read_b128 v[220:223], v142 offset:35840
	ds_read_b128 v[224:227], v142 offset:36864
	ds_read_b128 v[228:231], v142 offset:37888
	ds_read_b128 v[232:235], v142 offset:38912
	ds_read_b128 v[236:239], v142 offset:39936
	global_load_lds_dwordx4 v[248:249], off
	v_lshl_add_u64 v[248:249], s[42:43], 0, v[132:133]
	s_mov_b32 m0, s11
	s_nop 0
	global_load_lds_dwordx4 v[248:249], off
	s_waitcnt vmcnt(8)
	s_waitcnt lgkmcnt(0)
	s_setprio 1
	s_barrier
	s_waitcnt lgkmcnt(0)
	v_mfma_f32_16x16x32_bf16 v[126:129], v[144:147], v[208:211], v[126:129]
	v_mfma_f32_16x16x32_bf16 v[122:125], v[152:155], v[208:211], v[122:125]
	v_mfma_f32_16x16x32_bf16 v[110:113], v[144:147], v[216:219], v[110:113]
	v_mfma_f32_16x16x32_bf16 v[106:109], v[152:155], v[216:219], v[106:109]
	v_mfma_f32_16x16x32_bf16 v[94:97], v[144:147], v[224:227], v[94:97]
	v_mfma_f32_16x16x32_bf16 v[90:93], v[152:155], v[224:227], v[90:93]
	v_mfma_f32_16x16x32_bf16 v[78:81], v[144:147], v[232:235], v[78:81]
	v_mfma_f32_16x16x32_bf16 v[74:77], v[152:155], v[232:235], v[74:77]
	s_setprio 0
	s_setprio 1
	v_mfma_f32_16x16x32_bf16 v[126:129], v[148:151], v[212:215], v[126:129]
	v_mfma_f32_16x16x32_bf16 v[122:125], v[158:161], v[212:215], v[122:125]
	v_mfma_f32_16x16x32_bf16 v[110:113], v[148:151], v[220:223], v[110:113]
	v_mfma_f32_16x16x32_bf16 v[106:109], v[158:161], v[220:223], v[106:109]
	v_mfma_f32_16x16x32_bf16 v[94:97], v[148:151], v[228:231], v[94:97]
	v_mfma_f32_16x16x32_bf16 v[90:93], v[158:161], v[228:231], v[90:93]
	v_mfma_f32_16x16x32_bf16 v[78:81], v[148:151], v[236:239], v[78:81]
	v_mfma_f32_16x16x32_bf16 v[74:77], v[158:161], v[236:239], v[74:77]
	s_setprio 0
	s_setprio 1
	v_mfma_f32_16x16x32_bf16 v[118:121], v[162:165], v[208:211], v[118:121]
	v_mfma_f32_16x16x32_bf16 v[114:117], v[200:203], v[208:211], v[114:117]
	v_mfma_f32_16x16x32_bf16 v[102:105], v[162:165], v[216:219], v[102:105]
	v_mfma_f32_16x16x32_bf16 v[98:101], v[200:203], v[216:219], v[98:101]
	v_mfma_f32_16x16x32_bf16 v[86:89], v[162:165], v[224:227], v[86:89]
	v_mfma_f32_16x16x32_bf16 v[82:85], v[200:203], v[224:227], v[82:85]
	v_mfma_f32_16x16x32_bf16 v[70:73], v[162:165], v[232:235], v[70:73]
	v_mfma_f32_16x16x32_bf16 v[66:69], v[200:203], v[232:235], v[66:69]
	s_setprio 0
	s_setprio 1
	v_mfma_f32_16x16x32_bf16 v[118:121], v[196:199], v[212:215], v[118:121]
	v_mfma_f32_16x16x32_bf16 v[114:117], v[204:207], v[212:215], v[114:117]
	v_mfma_f32_16x16x32_bf16 v[102:105], v[196:199], v[220:223], v[102:105]
	v_mfma_f32_16x16x32_bf16 v[98:101], v[204:207], v[220:223], v[98:101]
	v_mfma_f32_16x16x32_bf16 v[86:89], v[196:199], v[228:231], v[86:89]
	v_mfma_f32_16x16x32_bf16 v[82:85], v[204:207], v[228:231], v[82:85]
	v_mfma_f32_16x16x32_bf16 v[70:73], v[196:199], v[236:239], v[70:73]
	v_mfma_f32_16x16x32_bf16 v[66:69], v[204:207], v[236:239], v[66:69]
	s_setprio 0
	s_barrier
	s_add_i32 s17, s17, s5
	v_lshl_add_u64 v[240:241], v[240:241], 0, s[24:25]
	s_mov_b32 m0, s17
	ds_read_b128 v[208:211], v142 offset:49152
	ds_read_b128 v[212:215], v142 offset:50176
	ds_read_b128 v[216:219], v142 offset:51200
	ds_read_b128 v[220:223], v142 offset:52224
	ds_read_b128 v[224:227], v142 offset:53248
	ds_read_b128 v[228:231], v142 offset:54272
	ds_read_b128 v[232:235], v142 offset:55296
	ds_read_b128 v[236:239], v142 offset:56320
	global_load_lds_dwordx4 v[240:241], off
	s_add_i32 m0, s17, 0x2000
	s_add_u32 s40, s40, 0x20080
	v_lshl_add_u64 v[240:241], v[242:243], 0, s[24:25]
	s_addc_u32 s41, s41, 0
	s_add_i32 s17, s20, s5
	global_load_lds_dwordx4 v[240:241], off
	v_lshl_add_u64 v[240:241], s[40:41], 0, v[0:1]
	s_mov_b32 m0, s17
	s_nop 0
	global_load_lds_dwordx4 v[240:241], off
	v_lshl_add_u64 v[240:241], s[40:41], 0, v[134:135]
	s_add_i32 m0, s17, 0x2000
	s_nop 0
	global_load_lds_dwordx4 v[240:241], off
	v_lshl_add_u64 v[240:241], v[244:245], 0, s[24:25]
	s_mov_b32 m0, s12
	s_nop 0
	global_load_lds_dwordx4 v[240:241], off
	v_lshl_add_u64 v[240:241], v[246:247], 0, s[24:25]
	s_mov_b32 m0, s13
	s_nop 0
	global_load_lds_dwordx4 v[240:241], off
	s_waitcnt vmcnt(8)
	s_waitcnt lgkmcnt(0)
	s_setprio 1
	s_barrier
	s_waitcnt lgkmcnt(0)
	v_mfma_f32_16x16x32_bf16 v[62:65], v[144:147], v[208:211], v[62:65]
	v_mfma_f32_16x16x32_bf16 v[58:61], v[152:155], v[208:211], v[58:61]
	v_mfma_f32_16x16x32_bf16 v[46:49], v[144:147], v[216:219], v[46:49]
	v_mfma_f32_16x16x32_bf16 v[42:45], v[152:155], v[216:219], v[42:45]
	v_mfma_f32_16x16x32_bf16 v[30:33], v[144:147], v[224:227], v[30:33]
	v_mfma_f32_16x16x32_bf16 v[26:29], v[152:155], v[224:227], v[26:29]
	v_mfma_f32_16x16x32_bf16 v[14:17], v[144:147], v[232:235], v[14:17]
	v_mfma_f32_16x16x32_bf16 v[10:13], v[152:155], v[232:235], v[10:13]
	s_setprio 0
	s_setprio 1
	v_mfma_f32_16x16x32_bf16 v[62:65], v[148:151], v[212:215], v[62:65]
	v_mfma_f32_16x16x32_bf16 v[58:61], v[158:161], v[212:215], v[58:61]
	v_mfma_f32_16x16x32_bf16 v[46:49], v[148:151], v[220:223], v[46:49]
	v_mfma_f32_16x16x32_bf16 v[42:45], v[158:161], v[220:223], v[42:45]
	v_mfma_f32_16x16x32_bf16 v[30:33], v[148:151], v[228:231], v[30:33]
	v_mfma_f32_16x16x32_bf16 v[26:29], v[158:161], v[228:231], v[26:29]
	v_mfma_f32_16x16x32_bf16 v[14:17], v[148:151], v[236:239], v[14:17]
	v_mfma_f32_16x16x32_bf16 v[10:13], v[158:161], v[236:239], v[10:13]
	s_setprio 0
	s_setprio 1
	v_mfma_f32_16x16x32_bf16 v[54:57], v[162:165], v[208:211], v[54:57]
	v_mfma_f32_16x16x32_bf16 v[50:53], v[200:203], v[208:211], v[50:53]
	v_mfma_f32_16x16x32_bf16 v[38:41], v[162:165], v[216:219], v[38:41]
	v_mfma_f32_16x16x32_bf16 v[34:37], v[200:203], v[216:219], v[34:37]
	v_mfma_f32_16x16x32_bf16 v[22:25], v[162:165], v[224:227], v[22:25]
	v_mfma_f32_16x16x32_bf16 v[18:21], v[200:203], v[224:227], v[18:21]
	v_mfma_f32_16x16x32_bf16 v[6:9], v[162:165], v[232:235], v[6:9]
	v_mfma_f32_16x16x32_bf16 v[2:5], v[200:203], v[232:235], v[2:5]
	s_setprio 0
	s_setprio 1
	v_mfma_f32_16x16x32_bf16 v[54:57], v[196:199], v[212:215], v[54:57]
	v_mfma_f32_16x16x32_bf16 v[50:53], v[204:207], v[212:215], v[50:53]
	v_mfma_f32_16x16x32_bf16 v[38:41], v[196:199], v[220:223], v[38:41]
	v_mfma_f32_16x16x32_bf16 v[34:37], v[204:207], v[220:223], v[34:37]
	v_mfma_f32_16x16x32_bf16 v[22:25], v[196:199], v[228:231], v[22:25]
	v_mfma_f32_16x16x32_bf16 v[18:21], v[204:207], v[228:231], v[18:21]
	v_mfma_f32_16x16x32_bf16 v[6:9], v[196:199], v[236:239], v[6:9]
	v_mfma_f32_16x16x32_bf16 v[2:5], v[204:207], v[236:239], v[2:5]
	s_setprio 0
	s_barrier
	s_add_i32 s16, s16, 2
	s_add_u32 s18, s18, 0x100
	s_addc_u32 s19, s19, 0
	s_cmp_gt_u32 s16, 5
	s_cbranch_scc0 .LBB0_465
	s_waitcnt vmcnt(0)
	s_cmpk_lt_u32 s1, 0x100
	s_cbranch_scc0 .LBB0_461
	s_barrier
	s_branch .LBB0_461

.LBB0_476:
	s_add_i32 s6, s20, 0x100
	s_and_b64 s[4:5], s[46:47], exec
	s_cselect_b32 s6, 0, s6
	s_cselect_b32 s5, 0, 0
	s_add_u32 s50, s2, s6
	s_addc_u32 s51, s3, s5
	s_add_i32 s4, 0, 0x10000
	s_add_u32 s52, s40, s6
	s_addc_u32 s53, s41, s5
	s_add_i32 s5, 0, 0x14000
	s_add_u32 s56, s42, s20
	s_addc_u32 s57, s43, 0
	s_add_i32 s85, s4, s11
	s_add_i32 m0, s12, 0xc000
	s_add_i32 s86, s12, 0xe000
	s_add_i32 s67, s85, 0x2000
	s_add_u32 s54, s52, 0x20000
	v_add_u32_e32 v142, s4, v140
	s_addc_u32 s55, s53, 0
	s_add_i32 s84, s5, s11
	ds_read_b128 v[146:149], v142
	ds_read_b128 v[150:153], v142 offset:1024
	ds_read_b128 v[158:161], v142 offset:2048
	ds_read_b128 v[162:165], v142 offset:3072
	v_add_u32_e32 v142, s5, v140
	s_add_i32 s70, s84, 0x2000
	s_add_i32 s6, 0, 0x18000
	s_add_i32 s7, 0, 0x1c000
	ds_read_b128 v[196:199], v142
	ds_read_b128 v[200:203], v142 offset:1024
	ds_read_b128 v[204:207], v142 offset:2048
	ds_read_b128 v[208:211], v142 offset:3072
	s_add_u32 s48, s50, 0x10000
	s_addc_u32 s49, s51, 0
	s_add_i32 s66, s6, s11
	s_add_i32 s63, s66, 0x2000
	s_add_u32 s46, s52, 0x20080
	s_addc_u32 s47, s53, 0
	s_add_i32 s65, s7, s11
	s_add_i32 s20, s65, 0x2000
	v_lshl_add_u64 v[142:143], s[56:57], 0, v[26:27]
	v_lshl_add_u64 v[142:143], v[142:143], 0, s[24:25]
	ds_read_b128 v[212:215], v141
	ds_read_b128 v[216:219], v141 offset:1024
	ds_read_b128 v[220:223], v141 offset:2048
	ds_read_b128 v[224:227], v141 offset:3072
	ds_read_b128 v[228:231], v141 offset:4096
	ds_read_b128 v[232:235], v141 offset:5120
	ds_read_b128 v[236:239], v141 offset:6144
	ds_read_b128 v[240:243], v141 offset:7168
	global_load_lds_dwordx4 v[142:143], off
	v_lshl_add_u64 v[142:143], s[56:57], 0, v[28:29]
	v_lshl_add_u64 v[142:143], v[142:143], 0, s[24:25]
	s_mov_b32 m0, s86
	s_nop 0
	global_load_lds_dwordx4 v[142:143], off
	s_waitcnt vmcnt(8)
	s_waitcnt lgkmcnt(0)
	s_setprio 1
	s_barrier
	s_waitcnt lgkmcnt(0)
	v_mfma_f32_16x16x32_bf16 v[134:137], v[146:149], v[212:215], v[134:137]
	v_mfma_f32_16x16x32_bf16 v[130:133], v[158:161], v[212:215], v[130:133]
	v_mfma_f32_16x16x32_bf16 v[118:121], v[146:149], v[220:223], v[118:121]
	v_mfma_f32_16x16x32_bf16 v[114:117], v[158:161], v[220:223], v[114:117]
	v_mfma_f32_16x16x32_bf16 v[102:105], v[146:149], v[228:231], v[102:105]
	v_mfma_f32_16x16x32_bf16 v[98:101], v[158:161], v[228:231], v[98:101]
	v_mfma_f32_16x16x32_bf16 v[86:89], v[146:149], v[236:239], v[86:89]
	v_mfma_f32_16x16x32_bf16 v[82:85], v[158:161], v[236:239], v[82:85]
	s_setprio 0
	s_setprio 1
	v_mfma_f32_16x16x32_bf16 v[134:137], v[150:153], v[216:219], v[134:137]
	v_mfma_f32_16x16x32_bf16 v[130:133], v[162:165], v[216:219], v[130:133]
	v_mfma_f32_16x16x32_bf16 v[118:121], v[150:153], v[224:227], v[118:121]
	v_mfma_f32_16x16x32_bf16 v[114:117], v[162:165], v[224:227], v[114:117]
	v_mfma_f32_16x16x32_bf16 v[102:105], v[150:153], v[232:235], v[102:105]
	v_mfma_f32_16x16x32_bf16 v[98:101], v[162:165], v[232:235], v[98:101]
	v_mfma_f32_16x16x32_bf16 v[86:89], v[150:153], v[240:243], v[86:89]
	v_mfma_f32_16x16x32_bf16 v[82:85], v[162:165], v[240:243], v[82:85]
	s_setprio 0
	s_setprio 1
	v_mfma_f32_16x16x32_bf16 v[126:129], v[196:199], v[212:215], v[126:129]
	v_mfma_f32_16x16x32_bf16 v[122:125], v[204:207], v[212:215], v[122:125]
	v_mfma_f32_16x16x32_bf16 v[110:113], v[196:199], v[220:223], v[110:113]
	v_mfma_f32_16x16x32_bf16 v[106:109], v[204:207], v[220:223], v[106:109]
	v_mfma_f32_16x16x32_bf16 v[94:97], v[196:199], v[228:231], v[94:97]
	v_mfma_f32_16x16x32_bf16 v[90:93], v[204:207], v[228:231], v[90:93]
	v_mfma_f32_16x16x32_bf16 v[78:81], v[196:199], v[236:239], v[78:81]
	v_mfma_f32_16x16x32_bf16 v[74:77], v[204:207], v[236:239], v[74:77]
	s_setprio 0
	s_setprio 1
	v_mfma_f32_16x16x32_bf16 v[126:129], v[200:203], v[216:219], v[126:129]
	v_mfma_f32_16x16x32_bf16 v[122:125], v[208:211], v[216:219], v[122:125]
	v_mfma_f32_16x16x32_bf16 v[110:113], v[200:203], v[224:227], v[110:113]
	v_mfma_f32_16x16x32_bf16 v[106:109], v[208:211], v[224:227], v[106:109]
	v_mfma_f32_16x16x32_bf16 v[94:97], v[200:203], v[232:235], v[94:97]
	v_mfma_f32_16x16x32_bf16 v[90:93], v[208:211], v[232:235], v[90:93]
	v_mfma_f32_16x16x32_bf16 v[78:81], v[200:203], v[240:243], v[78:81]
	v_mfma_f32_16x16x32_bf16 v[74:77], v[208:211], v[240:243], v[74:77]
	s_setprio 0
	s_barrier
	s_mov_b32 m0, s85
	v_lshl_add_u64 v[142:143], s[52:53], 0, v[0:1]
	ds_read_b128 v[212:215], v141 offset:16384
	ds_read_b128 v[216:219], v141 offset:17408
	ds_read_b128 v[220:223], v141 offset:18432
	ds_read_b128 v[224:227], v141 offset:19456
	ds_read_b128 v[228:231], v141 offset:20480
	ds_read_b128 v[232:235], v141 offset:21504
	ds_read_b128 v[236:239], v141 offset:22528
	ds_read_b128 v[240:243], v141 offset:23552
	global_load_lds_dwordx4 v[142:143], off
	v_lshl_add_u64 v[154:155], s[52:53], 0, v[38:39]
	s_mov_b32 m0, s67
	v_lshl_add_u64 v[244:245], s[54:55], 0, v[0:1]
	global_load_lds_dwordx4 v[154:155], off
	s_mov_b32 m0, s84
	v_lshl_add_u64 v[246:247], s[50:51], 0, v[28:29]
	global_load_lds_dwordx4 v[244:245], off
	v_lshl_add_u64 v[244:245], s[54:55], 0, v[38:39]
	s_mov_b32 m0, s70
	s_nop 0
	global_load_lds_dwordx4 v[244:245], off
	v_lshl_add_u64 v[244:245], s[50:51], 0, v[26:27]
	s_mov_b32 m0, s12
	s_nop 0
	global_load_lds_dwordx4 v[244:245], off
	s_mov_b32 m0, s13
	s_nop 0
	global_load_lds_dwordx4 v[246:247], off
	s_waitcnt vmcnt(8)
	s_waitcnt lgkmcnt(0)
	s_setprio 1
	s_barrier
	s_waitcnt lgkmcnt(0)
	v_mfma_f32_16x16x32_bf16 v[70:73], v[146:149], v[212:215], v[70:73]
	v_mfma_f32_16x16x32_bf16 v[66:69], v[158:161], v[212:215], v[66:69]
	v_mfma_f32_16x16x32_bf16 v[54:57], v[146:149], v[220:223], v[54:57]
	v_mfma_f32_16x16x32_bf16 v[50:53], v[158:161], v[220:223], v[50:53]
	v_mfma_f32_16x16x32_bf16 v[34:37], v[146:149], v[228:231], v[34:37]
	v_mfma_f32_16x16x32_bf16 v[30:33], v[158:161], v[228:231], v[30:33]
	v_mfma_f32_16x16x32_bf16 v[14:17], v[146:149], v[236:239], v[14:17]
	v_mfma_f32_16x16x32_bf16 v[10:13], v[158:161], v[236:239], v[10:13]
	s_setprio 0
	s_setprio 1
	v_mfma_f32_16x16x32_bf16 v[70:73], v[150:153], v[216:219], v[70:73]
	v_mfma_f32_16x16x32_bf16 v[66:69], v[162:165], v[216:219], v[66:69]
	v_mfma_f32_16x16x32_bf16 v[54:57], v[150:153], v[224:227], v[54:57]
	v_mfma_f32_16x16x32_bf16 v[50:53], v[162:165], v[224:227], v[50:53]
	v_mfma_f32_16x16x32_bf16 v[34:37], v[150:153], v[232:235], v[34:37]
	v_mfma_f32_16x16x32_bf16 v[30:33], v[162:165], v[232:235], v[30:33]
	v_mfma_f32_16x16x32_bf16 v[14:17], v[150:153], v[240:243], v[14:17]
	v_mfma_f32_16x16x32_bf16 v[10:13], v[162:165], v[240:243], v[10:13]
	s_setprio 0
	s_setprio 1
	v_mfma_f32_16x16x32_bf16 v[62:65], v[196:199], v[212:215], v[62:65]
	v_mfma_f32_16x16x32_bf16 v[58:61], v[204:207], v[212:215], v[58:61]
	v_mfma_f32_16x16x32_bf16 v[46:49], v[196:199], v[220:223], v[46:49]
	v_mfma_f32_16x16x32_bf16 v[42:45], v[204:207], v[220:223], v[42:45]
	v_mfma_f32_16x16x32_bf16 v[22:25], v[196:199], v[228:231], v[22:25]
	v_mfma_f32_16x16x32_bf16 v[18:21], v[204:207], v[228:231], v[18:21]
	v_mfma_f32_16x16x32_bf16 v[6:9], v[196:199], v[236:239], v[6:9]
	v_mfma_f32_16x16x32_bf16 v[2:5], v[204:207], v[236:239], v[2:5]
	s_setprio 0
	s_setprio 1
	v_mfma_f32_16x16x32_bf16 v[62:65], v[200:203], v[216:219], v[62:65]
	v_mfma_f32_16x16x32_bf16 v[58:61], v[208:211], v[216:219], v[58:61]
	v_mfma_f32_16x16x32_bf16 v[46:49], v[200:203], v[224:227], v[46:49]
	v_mfma_f32_16x16x32_bf16 v[42:45], v[208:211], v[224:227], v[42:45]
	v_mfma_f32_16x16x32_bf16 v[22:25], v[200:203], v[232:235], v[22:25]
	v_mfma_f32_16x16x32_bf16 v[18:21], v[208:211], v[232:235], v[18:21]
	v_mfma_f32_16x16x32_bf16 v[6:9], v[200:203], v[240:243], v[6:9]
	v_mfma_f32_16x16x32_bf16 v[2:5], v[208:211], v[240:243], v[2:5]
	s_setprio 0
	s_barrier
	v_add_u32_e32 v145, s6, v140
	ds_read_b128 v[146:149], v145
	ds_read_b128 v[150:153], v145 offset:1024
	ds_read_b128 v[158:161], v145 offset:2048
	ds_read_b128 v[162:165], v145 offset:3072
	v_add_u32_e32 v145, s7, v140
	ds_read_b128 v[196:199], v145
	ds_read_b128 v[200:203], v145 offset:1024
	ds_read_b128 v[204:207], v145 offset:2048
	ds_read_b128 v[208:211], v145 offset:3072
	s_mov_b32 m0, s16
	v_lshl_add_u64 v[248:249], s[48:49], 0, v[26:27]
	ds_read_b128 v[212:215], v141 offset:32768
	ds_read_b128 v[216:219], v141 offset:33792
	ds_read_b128 v[220:223], v141 offset:34816
	ds_read_b128 v[224:227], v141 offset:35840
	ds_read_b128 v[228:231], v141 offset:36864
	ds_read_b128 v[232:235], v141 offset:37888
	ds_read_b128 v[236:239], v141 offset:38912
	ds_read_b128 v[240:243], v141 offset:39936
	global_load_lds_dwordx4 v[248:249], off
	v_lshl_add_u64 v[248:249], s[48:49], 0, v[28:29]
	s_mov_b32 m0, s17
	s_nop 0
	global_load_lds_dwordx4 v[248:249], off
	s_waitcnt vmcnt(8)
	s_waitcnt lgkmcnt(0)
	s_setprio 1
	s_barrier
	s_waitcnt lgkmcnt(0)
	v_mfma_f32_16x16x32_bf16 v[134:137], v[146:149], v[212:215], v[134:137]
	v_mfma_f32_16x16x32_bf16 v[130:133], v[158:161], v[212:215], v[130:133]
	v_mfma_f32_16x16x32_bf16 v[118:121], v[146:149], v[220:223], v[118:121]
	v_mfma_f32_16x16x32_bf16 v[114:117], v[158:161], v[220:223], v[114:117]
	v_mfma_f32_16x16x32_bf16 v[102:105], v[146:149], v[228:231], v[102:105]
	v_mfma_f32_16x16x32_bf16 v[98:101], v[158:161], v[228:231], v[98:101]
	v_mfma_f32_16x16x32_bf16 v[86:89], v[146:149], v[236:239], v[86:89]
	v_mfma_f32_16x16x32_bf16 v[82:85], v[158:161], v[236:239], v[82:85]
	s_setprio 0
	s_setprio 1
	v_mfma_f32_16x16x32_bf16 v[134:137], v[150:153], v[216:219], v[134:137]
	v_mfma_f32_16x16x32_bf16 v[130:133], v[162:165], v[216:219], v[130:133]
	v_mfma_f32_16x16x32_bf16 v[118:121], v[150:153], v[224:227], v[118:121]
	v_mfma_f32_16x16x32_bf16 v[114:117], v[162:165], v[224:227], v[114:117]
	v_mfma_f32_16x16x32_bf16 v[102:105], v[150:153], v[232:235], v[102:105]
	v_mfma_f32_16x16x32_bf16 v[98:101], v[162:165], v[232:235], v[98:101]
	v_mfma_f32_16x16x32_bf16 v[86:89], v[150:153], v[240:243], v[86:89]
	v_mfma_f32_16x16x32_bf16 v[82:85], v[162:165], v[240:243], v[82:85]
	s_setprio 0
	s_setprio 1
	v_mfma_f32_16x16x32_bf16 v[126:129], v[196:199], v[212:215], v[126:129]
	v_mfma_f32_16x16x32_bf16 v[122:125], v[204:207], v[212:215], v[122:125]
	v_mfma_f32_16x16x32_bf16 v[110:113], v[196:199], v[220:223], v[110:113]
	v_mfma_f32_16x16x32_bf16 v[106:109], v[204:207], v[220:223], v[106:109]
	v_mfma_f32_16x16x32_bf16 v[94:97], v[196:199], v[228:231], v[94:97]
	v_mfma_f32_16x16x32_bf16 v[90:93], v[204:207], v[228:231], v[90:93]
	v_mfma_f32_16x16x32_bf16 v[78:81], v[196:199], v[236:239], v[78:81]
	v_mfma_f32_16x16x32_bf16 v[74:77], v[204:207], v[236:239], v[74:77]
	s_setprio 0
	s_setprio 1
	v_mfma_f32_16x16x32_bf16 v[126:129], v[200:203], v[216:219], v[126:129]
	v_mfma_f32_16x16x32_bf16 v[122:125], v[208:211], v[216:219], v[122:125]
	v_mfma_f32_16x16x32_bf16 v[110:113], v[200:203], v[224:227], v[110:113]
	v_mfma_f32_16x16x32_bf16 v[106:109], v[208:211], v[224:227], v[106:109]
	v_mfma_f32_16x16x32_bf16 v[94:97], v[200:203], v[232:235], v[94:97]
	v_mfma_f32_16x16x32_bf16 v[90:93], v[208:211], v[232:235], v[90:93]
	v_mfma_f32_16x16x32_bf16 v[78:81], v[200:203], v[240:243], v[78:81]
	v_mfma_f32_16x16x32_bf16 v[74:77], v[208:211], v[240:243], v[74:77]
	s_setprio 0
	s_barrier
	s_mov_b32 m0, s66
	v_lshl_add_u64 v[142:143], v[142:143], 0, s[24:25]
	ds_read_b128 v[212:215], v141 offset:49152
	ds_read_b128 v[216:219], v141 offset:50176
	ds_read_b128 v[220:223], v141 offset:51200
	ds_read_b128 v[224:227], v141 offset:52224
	ds_read_b128 v[228:231], v141 offset:53248
	ds_read_b128 v[232:235], v141 offset:54272
	ds_read_b128 v[236:239], v141 offset:55296
	ds_read_b128 v[240:243], v141 offset:56320
	global_load_lds_dwordx4 v[142:143], off
	v_lshl_add_u64 v[142:143], v[154:155], 0, s[24:25]
	s_mov_b32 m0, s63
	s_nop 0
	global_load_lds_dwordx4 v[142:143], off
	v_lshl_add_u64 v[142:143], s[46:47], 0, v[0:1]
	s_mov_b32 m0, s65
	s_nop 0
	global_load_lds_dwordx4 v[142:143], off
	v_lshl_add_u64 v[142:143], s[46:47], 0, v[38:39]
	s_mov_b32 m0, s20
	s_nop 0
	global_load_lds_dwordx4 v[142:143], off
	v_lshl_add_u64 v[142:143], v[244:245], 0, s[24:25]
	s_mov_b32 m0, s19
	s_nop 0
	global_load_lds_dwordx4 v[142:143], off
	v_lshl_add_u64 v[142:143], v[246:247], 0, s[24:25]
	s_mov_b32 m0, s62
	s_nop 0
	global_load_lds_dwordx4 v[142:143], off
	s_waitcnt vmcnt(8)
	s_waitcnt lgkmcnt(0)
	s_setprio 1
	s_barrier
	s_waitcnt lgkmcnt(0)
	v_mfma_f32_16x16x32_bf16 v[70:73], v[146:149], v[212:215], v[70:73]
	v_mfma_f32_16x16x32_bf16 v[66:69], v[158:161], v[212:215], v[66:69]
	v_mfma_f32_16x16x32_bf16 v[54:57], v[146:149], v[220:223], v[54:57]
	v_mfma_f32_16x16x32_bf16 v[50:53], v[158:161], v[220:223], v[50:53]
	v_mfma_f32_16x16x32_bf16 v[34:37], v[146:149], v[228:231], v[34:37]
	v_mfma_f32_16x16x32_bf16 v[30:33], v[158:161], v[228:231], v[30:33]
	v_mfma_f32_16x16x32_bf16 v[14:17], v[146:149], v[236:239], v[14:17]
	v_mfma_f32_16x16x32_bf16 v[10:13], v[158:161], v[236:239], v[10:13]
	s_setprio 0
	s_setprio 1
	v_mfma_f32_16x16x32_bf16 v[70:73], v[150:153], v[216:219], v[70:73]
	v_mfma_f32_16x16x32_bf16 v[66:69], v[162:165], v[216:219], v[66:69]
	v_mfma_f32_16x16x32_bf16 v[54:57], v[150:153], v[224:227], v[54:57]
	v_mfma_f32_16x16x32_bf16 v[50:53], v[162:165], v[224:227], v[50:53]
	v_mfma_f32_16x16x32_bf16 v[34:37], v[150:153], v[232:235], v[34:37]
	v_mfma_f32_16x16x32_bf16 v[30:33], v[162:165], v[232:235], v[30:33]
	v_mfma_f32_16x16x32_bf16 v[14:17], v[150:153], v[240:243], v[14:17]
	v_mfma_f32_16x16x32_bf16 v[10:13], v[162:165], v[240:243], v[10:13]
	s_setprio 0
	s_setprio 1
	v_mfma_f32_16x16x32_bf16 v[62:65], v[196:199], v[212:215], v[62:65]
	v_mfma_f32_16x16x32_bf16 v[58:61], v[204:207], v[212:215], v[58:61]
	v_mfma_f32_16x16x32_bf16 v[46:49], v[196:199], v[220:223], v[46:49]
	v_mfma_f32_16x16x32_bf16 v[42:45], v[204:207], v[220:223], v[42:45]
	v_mfma_f32_16x16x32_bf16 v[22:25], v[196:199], v[228:231], v[22:25]
	v_mfma_f32_16x16x32_bf16 v[18:21], v[204:207], v[228:231], v[18:21]
	v_mfma_f32_16x16x32_bf16 v[6:9], v[196:199], v[236:239], v[6:9]
	v_mfma_f32_16x16x32_bf16 v[2:5], v[204:207], v[236:239], v[2:5]
	s_setprio 0
	s_setprio 1
	v_mfma_f32_16x16x32_bf16 v[62:65], v[200:203], v[216:219], v[62:65]
	v_mfma_f32_16x16x32_bf16 v[58:61], v[208:211], v[216:219], v[58:61]
	v_mfma_f32_16x16x32_bf16 v[46:49], v[200:203], v[224:227], v[46:49]
	v_mfma_f32_16x16x32_bf16 v[42:45], v[208:211], v[224:227], v[42:45]
	v_mfma_f32_16x16x32_bf16 v[22:25], v[200:203], v[232:235], v[22:25]
	v_mfma_f32_16x16x32_bf16 v[18:21], v[208:211], v[232:235], v[18:21]
	v_mfma_f32_16x16x32_bf16 v[6:9], v[200:203], v[240:243], v[6:9]
	v_mfma_f32_16x16x32_bf16 v[2:5], v[208:211], v[240:243], v[2:5]
	s_setprio 0
	s_barrier
	s_andn2_b64 vcc, exec, s[44:45]
	s_mov_b64 s[46:47], -1
	s_mov_b64 s[44:45], 0
	s_movk_i32 s20, 0x100
	s_cbranch_vccz .LBB0_476
	s_waitcnt vmcnt(0)
	s_cmpk_lt_u32 s10, 0x100
	s_cbranch_scc0 .LBB0_479
	s_barrier

.LBB0_482:
	s_add_i32 s48, s20, 0x100
	s_and_b64 s[46:47], s[46:47], exec
	s_cselect_b32 s47, 0, s48
	s_cselect_b32 s46, 0, 0
	s_add_u32 s50, s2, s47
	s_addc_u32 s51, s3, s46
	s_add_u32 s52, s40, s47
	s_addc_u32 s53, s41, s46
	s_add_u32 s66, s42, s20
	s_addc_u32 s67, s43, 0
	s_add_i32 s65, s4, s10
	s_add_i32 m0, s11, 0xc000
	s_add_i32 s63, s11, 0xe000
	s_add_i32 s70, s65, 0x2000
	s_add_u32 s54, s52, 0x20200
	v_add_u32_e32 v142, s4, v40
	s_addc_u32 s55, s53, 0
	s_add_i32 s82, s5, s10
	ds_read_b128 v[138:141], v142
	ds_read_b128 v[146:149], v142 offset:1024
	ds_read_b128 v[150:153], v142 offset:2048
	ds_read_b128 v[158:161], v142 offset:3072
	v_add_u32_e32 v142, s5, v40
	s_add_i32 s83, s82, 0x2000
	ds_read_b128 v[162:165], v142
	ds_read_b128 v[196:199], v142 offset:1024
	ds_read_b128 v[200:203], v142 offset:2048
	ds_read_b128 v[204:207], v142 offset:3072
	s_add_u32 s48, s50, 0x10000
	s_addc_u32 s49, s51, 0
	s_add_i32 s62, s6, s10
	s_add_i32 s56, s62, 0x2000
	s_add_u32 s46, s52, 0x20280
	s_addc_u32 s47, s53, 0
	s_add_i32 s57, s7, s10
	s_add_i32 s20, s57, 0x2000
	v_lshl_add_u64 v[142:143], s[66:67], 0, v[26:27]
	v_lshl_add_u64 v[142:143], v[142:143], 0, s[24:25]
	ds_read_b128 v[208:211], v41
	ds_read_b128 v[212:215], v41 offset:1024
	ds_read_b128 v[216:219], v41 offset:2048
	ds_read_b128 v[220:223], v41 offset:3072
	ds_read_b128 v[224:227], v41 offset:4096
	ds_read_b128 v[228:231], v41 offset:5120
	ds_read_b128 v[232:235], v41 offset:6144
	ds_read_b128 v[236:239], v41 offset:7168
	global_load_lds_dwordx4 v[142:143], off
	v_lshl_add_u64 v[142:143], s[66:67], 0, v[28:29]
	v_lshl_add_u64 v[142:143], v[142:143], 0, s[24:25]
	s_mov_b32 m0, s63
	s_nop 0
	global_load_lds_dwordx4 v[142:143], off
	s_waitcnt vmcnt(8)
	s_waitcnt lgkmcnt(0)
	s_setprio 1
	s_barrier
	s_waitcnt lgkmcnt(0)
	v_mfma_f32_16x16x32_bf16 v[134:137], v[138:141], v[208:211], v[134:137]
	v_mfma_f32_16x16x32_bf16 v[130:133], v[150:153], v[208:211], v[130:133]
	v_mfma_f32_16x16x32_bf16 v[118:121], v[138:141], v[216:219], v[118:121]
	v_mfma_f32_16x16x32_bf16 v[114:117], v[150:153], v[216:219], v[114:117]
	v_mfma_f32_16x16x32_bf16 v[102:105], v[138:141], v[224:227], v[102:105]
	v_mfma_f32_16x16x32_bf16 v[98:101], v[150:153], v[224:227], v[98:101]
	v_mfma_f32_16x16x32_bf16 v[86:89], v[138:141], v[232:235], v[86:89]
	v_mfma_f32_16x16x32_bf16 v[82:85], v[150:153], v[232:235], v[82:85]
	s_setprio 0
	s_setprio 1
	v_mfma_f32_16x16x32_bf16 v[134:137], v[146:149], v[212:215], v[134:137]
	v_mfma_f32_16x16x32_bf16 v[130:133], v[158:161], v[212:215], v[130:133]
	v_mfma_f32_16x16x32_bf16 v[118:121], v[146:149], v[220:223], v[118:121]
	v_mfma_f32_16x16x32_bf16 v[114:117], v[158:161], v[220:223], v[114:117]
	v_mfma_f32_16x16x32_bf16 v[102:105], v[146:149], v[228:231], v[102:105]
	v_mfma_f32_16x16x32_bf16 v[98:101], v[158:161], v[228:231], v[98:101]
	v_mfma_f32_16x16x32_bf16 v[86:89], v[146:149], v[236:239], v[86:89]
	v_mfma_f32_16x16x32_bf16 v[82:85], v[158:161], v[236:239], v[82:85]
	s_setprio 0
	s_setprio 1
	v_mfma_f32_16x16x32_bf16 v[126:129], v[162:165], v[208:211], v[126:129]
	v_mfma_f32_16x16x32_bf16 v[122:125], v[200:203], v[208:211], v[122:125]
	v_mfma_f32_16x16x32_bf16 v[110:113], v[162:165], v[216:219], v[110:113]
	v_mfma_f32_16x16x32_bf16 v[106:109], v[200:203], v[216:219], v[106:109]
	v_mfma_f32_16x16x32_bf16 v[94:97], v[162:165], v[224:227], v[94:97]
	v_mfma_f32_16x16x32_bf16 v[90:93], v[200:203], v[224:227], v[90:93]
	v_mfma_f32_16x16x32_bf16 v[78:81], v[162:165], v[232:235], v[78:81]
	v_mfma_f32_16x16x32_bf16 v[74:77], v[200:203], v[232:235], v[74:77]
	s_setprio 0
	s_setprio 1
	v_mfma_f32_16x16x32_bf16 v[126:129], v[196:199], v[212:215], v[126:129]
	v_mfma_f32_16x16x32_bf16 v[122:125], v[204:207], v[212:215], v[122:125]
	v_mfma_f32_16x16x32_bf16 v[110:113], v[196:199], v[220:223], v[110:113]
	v_mfma_f32_16x16x32_bf16 v[106:109], v[204:207], v[220:223], v[106:109]
	v_mfma_f32_16x16x32_bf16 v[94:97], v[196:199], v[228:231], v[94:97]
	v_mfma_f32_16x16x32_bf16 v[90:93], v[204:207], v[228:231], v[90:93]
	v_mfma_f32_16x16x32_bf16 v[78:81], v[196:199], v[236:239], v[78:81]
	v_mfma_f32_16x16x32_bf16 v[74:77], v[204:207], v[236:239], v[74:77]
	s_setprio 0
	s_barrier
	v_lshl_add_u64 v[142:143], s[52:53], 0, v[0:1]
	s_mov_b32 m0, s65
	v_lshl_add_u64 v[154:155], v[142:143], 0, s[84:85]
	ds_read_b128 v[208:211], v41 offset:16384
	ds_read_b128 v[212:215], v41 offset:17408
	ds_read_b128 v[216:219], v41 offset:18432
	ds_read_b128 v[220:223], v41 offset:19456
	ds_read_b128 v[224:227], v41 offset:20480
	ds_read_b128 v[228:231], v41 offset:21504
	ds_read_b128 v[232:235], v41 offset:22528
	ds_read_b128 v[236:239], v41 offset:23552
	global_load_lds_dwordx4 v[154:155], off
	v_lshl_add_u64 v[154:155], s[52:53], 0, v[38:39]
	v_lshl_add_u64 v[240:241], v[154:155], 0, s[84:85]
	s_mov_b32 m0, s70
	v_lshl_add_u64 v[242:243], s[50:51], 0, v[28:29]
	global_load_lds_dwordx4 v[240:241], off
	v_lshl_add_u64 v[240:241], s[54:55], 0, v[0:1]
	s_mov_b32 m0, s82
	s_nop 0
	global_load_lds_dwordx4 v[240:241], off
	v_lshl_add_u64 v[240:241], s[54:55], 0, v[38:39]
	s_mov_b32 m0, s83
	s_nop 0
	global_load_lds_dwordx4 v[240:241], off
	v_lshl_add_u64 v[240:241], s[50:51], 0, v[26:27]
	s_mov_b32 m0, s11
	s_nop 0
	global_load_lds_dwordx4 v[240:241], off
	s_mov_b32 m0, s12
	s_nop 0
	global_load_lds_dwordx4 v[242:243], off
	s_waitcnt vmcnt(8)
	s_waitcnt lgkmcnt(0)
	s_setprio 1
	s_barrier
	s_waitcnt lgkmcnt(0)
	v_mfma_f32_16x16x32_bf16 v[70:73], v[138:141], v[208:211], v[70:73]
	v_mfma_f32_16x16x32_bf16 v[66:69], v[150:153], v[208:211], v[66:69]
	v_mfma_f32_16x16x32_bf16 v[54:57], v[138:141], v[216:219], v[54:57]
	v_mfma_f32_16x16x32_bf16 v[50:53], v[150:153], v[216:219], v[50:53]
	v_mfma_f32_16x16x32_bf16 v[34:37], v[138:141], v[224:227], v[34:37]
	v_mfma_f32_16x16x32_bf16 v[30:33], v[150:153], v[224:227], v[30:33]
	v_mfma_f32_16x16x32_bf16 v[14:17], v[138:141], v[232:235], v[14:17]
	v_mfma_f32_16x16x32_bf16 v[10:13], v[150:153], v[232:235], v[10:13]
	s_setprio 0
	s_setprio 1
	v_mfma_f32_16x16x32_bf16 v[70:73], v[146:149], v[212:215], v[70:73]
	v_mfma_f32_16x16x32_bf16 v[66:69], v[158:161], v[212:215], v[66:69]
	v_mfma_f32_16x16x32_bf16 v[54:57], v[146:149], v[220:223], v[54:57]
	v_mfma_f32_16x16x32_bf16 v[50:53], v[158:161], v[220:223], v[50:53]
	v_mfma_f32_16x16x32_bf16 v[34:37], v[146:149], v[228:231], v[34:37]
	v_mfma_f32_16x16x32_bf16 v[30:33], v[158:161], v[228:231], v[30:33]
	v_mfma_f32_16x16x32_bf16 v[14:17], v[146:149], v[236:239], v[14:17]
	v_mfma_f32_16x16x32_bf16 v[10:13], v[158:161], v[236:239], v[10:13]
	s_setprio 0
	s_setprio 1
	v_mfma_f32_16x16x32_bf16 v[62:65], v[162:165], v[208:211], v[62:65]
	v_mfma_f32_16x16x32_bf16 v[58:61], v[200:203], v[208:211], v[58:61]
	v_mfma_f32_16x16x32_bf16 v[46:49], v[162:165], v[216:219], v[46:49]
	v_mfma_f32_16x16x32_bf16 v[42:45], v[200:203], v[216:219], v[42:45]
	v_mfma_f32_16x16x32_bf16 v[22:25], v[162:165], v[224:227], v[22:25]
	v_mfma_f32_16x16x32_bf16 v[18:21], v[200:203], v[224:227], v[18:21]
	v_mfma_f32_16x16x32_bf16 v[6:9], v[162:165], v[232:235], v[6:9]
	v_mfma_f32_16x16x32_bf16 v[2:5], v[200:203], v[232:235], v[2:5]
	s_setprio 0
	s_setprio 1
	v_mfma_f32_16x16x32_bf16 v[62:65], v[196:199], v[212:215], v[62:65]
	v_mfma_f32_16x16x32_bf16 v[58:61], v[204:207], v[212:215], v[58:61]
	v_mfma_f32_16x16x32_bf16 v[46:49], v[196:199], v[220:223], v[46:49]
	v_mfma_f32_16x16x32_bf16 v[42:45], v[204:207], v[220:223], v[42:45]
	v_mfma_f32_16x16x32_bf16 v[22:25], v[196:199], v[228:231], v[22:25]
	v_mfma_f32_16x16x32_bf16 v[18:21], v[204:207], v[228:231], v[18:21]
	v_mfma_f32_16x16x32_bf16 v[6:9], v[196:199], v[236:239], v[6:9]
	v_mfma_f32_16x16x32_bf16 v[2:5], v[204:207], v[236:239], v[2:5]
	s_setprio 0
	s_barrier
	v_add_u32_e32 v145, s6, v40
	ds_read_b128 v[138:141], v145
	ds_read_b128 v[146:149], v145 offset:1024
	ds_read_b128 v[150:153], v145 offset:2048
	ds_read_b128 v[158:161], v145 offset:3072
	v_add_u32_e32 v145, s7, v40
	ds_read_b128 v[162:165], v145
	ds_read_b128 v[196:199], v145 offset:1024
	ds_read_b128 v[200:203], v145 offset:2048
	ds_read_b128 v[204:207], v145 offset:3072
	s_mov_b32 m0, s13
	v_lshl_add_u64 v[244:245], s[48:49], 0, v[26:27]
	ds_read_b128 v[208:211], v41 offset:32768
	ds_read_b128 v[212:215], v41 offset:33792
	ds_read_b128 v[216:219], v41 offset:34816
	ds_read_b128 v[220:223], v41 offset:35840
	ds_read_b128 v[224:227], v41 offset:36864
	ds_read_b128 v[228:231], v41 offset:37888
	ds_read_b128 v[232:235], v41 offset:38912
	ds_read_b128 v[236:239], v41 offset:39936
	global_load_lds_dwordx4 v[244:245], off
	v_lshl_add_u64 v[244:245], s[48:49], 0, v[28:29]
	s_mov_b32 m0, s16
	s_mov_b64 s[48:49], 0x280
	global_load_lds_dwordx4 v[244:245], off
	s_waitcnt vmcnt(8)
	s_waitcnt lgkmcnt(0)
	s_setprio 1
	s_barrier
	s_waitcnt lgkmcnt(0)
	v_mfma_f32_16x16x32_bf16 v[134:137], v[138:141], v[208:211], v[134:137]
	v_mfma_f32_16x16x32_bf16 v[130:133], v[150:153], v[208:211], v[130:133]
	v_mfma_f32_16x16x32_bf16 v[118:121], v[138:141], v[216:219], v[118:121]
	v_mfma_f32_16x16x32_bf16 v[114:117], v[150:153], v[216:219], v[114:117]
	v_mfma_f32_16x16x32_bf16 v[102:105], v[138:141], v[224:227], v[102:105]
	v_mfma_f32_16x16x32_bf16 v[98:101], v[150:153], v[224:227], v[98:101]
	v_mfma_f32_16x16x32_bf16 v[86:89], v[138:141], v[232:235], v[86:89]
	v_mfma_f32_16x16x32_bf16 v[82:85], v[150:153], v[232:235], v[82:85]
	s_setprio 0
	s_setprio 1
	v_mfma_f32_16x16x32_bf16 v[134:137], v[146:149], v[212:215], v[134:137]
	v_mfma_f32_16x16x32_bf16 v[130:133], v[158:161], v[212:215], v[130:133]
	v_mfma_f32_16x16x32_bf16 v[118:121], v[146:149], v[220:223], v[118:121]
	v_mfma_f32_16x16x32_bf16 v[114:117], v[158:161], v[220:223], v[114:117]
	v_mfma_f32_16x16x32_bf16 v[102:105], v[146:149], v[228:231], v[102:105]
	v_mfma_f32_16x16x32_bf16 v[98:101], v[158:161], v[228:231], v[98:101]
	v_mfma_f32_16x16x32_bf16 v[86:89], v[146:149], v[236:239], v[86:89]
	v_mfma_f32_16x16x32_bf16 v[82:85], v[158:161], v[236:239], v[82:85]
	s_setprio 0
	s_setprio 1
	v_mfma_f32_16x16x32_bf16 v[126:129], v[162:165], v[208:211], v[126:129]
	v_mfma_f32_16x16x32_bf16 v[122:125], v[200:203], v[208:211], v[122:125]
	v_mfma_f32_16x16x32_bf16 v[110:113], v[162:165], v[216:219], v[110:113]
	v_mfma_f32_16x16x32_bf16 v[106:109], v[200:203], v[216:219], v[106:109]
	v_mfma_f32_16x16x32_bf16 v[94:97], v[162:165], v[224:227], v[94:97]
	v_mfma_f32_16x16x32_bf16 v[90:93], v[200:203], v[224:227], v[90:93]
	v_mfma_f32_16x16x32_bf16 v[78:81], v[162:165], v[232:235], v[78:81]
	v_mfma_f32_16x16x32_bf16 v[74:77], v[200:203], v[232:235], v[74:77]
	s_setprio 0
	s_setprio 1
	v_mfma_f32_16x16x32_bf16 v[126:129], v[196:199], v[212:215], v[126:129]
	v_mfma_f32_16x16x32_bf16 v[122:125], v[204:207], v[212:215], v[122:125]
	v_mfma_f32_16x16x32_bf16 v[110:113], v[196:199], v[220:223], v[110:113]
	v_mfma_f32_16x16x32_bf16 v[106:109], v[204:207], v[220:223], v[106:109]
	v_mfma_f32_16x16x32_bf16 v[94:97], v[196:199], v[228:231], v[94:97]
	v_mfma_f32_16x16x32_bf16 v[90:93], v[204:207], v[228:231], v[90:93]
	v_mfma_f32_16x16x32_bf16 v[78:81], v[196:199], v[236:239], v[78:81]
	v_mfma_f32_16x16x32_bf16 v[74:77], v[204:207], v[236:239], v[74:77]
	s_setprio 0
	s_barrier
	s_mov_b32 m0, s62
	v_lshl_add_u64 v[142:143], v[142:143], 0, s[48:49]
	ds_read_b128 v[208:211], v41 offset:49152
	ds_read_b128 v[212:215], v41 offset:50176
	ds_read_b128 v[216:219], v41 offset:51200
	ds_read_b128 v[220:223], v41 offset:52224
	ds_read_b128 v[224:227], v41 offset:53248
	ds_read_b128 v[228:231], v41 offset:54272
	ds_read_b128 v[232:235], v41 offset:55296
	ds_read_b128 v[236:239], v41 offset:56320
	global_load_lds_dwordx4 v[142:143], off
	v_lshl_add_u64 v[142:143], v[154:155], 0, s[48:49]
	s_mov_b32 m0, s56
	s_nop 0
	global_load_lds_dwordx4 v[142:143], off
	v_lshl_add_u64 v[142:143], s[46:47], 0, v[0:1]
	s_mov_b32 m0, s57
	s_nop 0
	global_load_lds_dwordx4 v[142:143], off
	v_lshl_add_u64 v[142:143], s[46:47], 0, v[38:39]
	s_mov_b32 m0, s20
	s_nop 0
	global_load_lds_dwordx4 v[142:143], off
	v_lshl_add_u64 v[142:143], v[240:241], 0, s[24:25]
	s_mov_b32 m0, s17
	s_nop 0
	global_load_lds_dwordx4 v[142:143], off
	v_lshl_add_u64 v[142:143], v[242:243], 0, s[24:25]
	s_mov_b32 m0, s19
	s_nop 0
	global_load_lds_dwordx4 v[142:143], off
	s_waitcnt vmcnt(8)
	s_waitcnt lgkmcnt(0)
	s_setprio 1
	s_barrier
	s_waitcnt lgkmcnt(0)
	v_mfma_f32_16x16x32_bf16 v[70:73], v[138:141], v[208:211], v[70:73]
	v_mfma_f32_16x16x32_bf16 v[66:69], v[150:153], v[208:211], v[66:69]
	v_mfma_f32_16x16x32_bf16 v[54:57], v[138:141], v[216:219], v[54:57]
	v_mfma_f32_16x16x32_bf16 v[50:53], v[150:153], v[216:219], v[50:53]
	v_mfma_f32_16x16x32_bf16 v[34:37], v[138:141], v[224:227], v[34:37]
	v_mfma_f32_16x16x32_bf16 v[30:33], v[150:153], v[224:227], v[30:33]
	v_mfma_f32_16x16x32_bf16 v[14:17], v[138:141], v[232:235], v[14:17]
	v_mfma_f32_16x16x32_bf16 v[10:13], v[150:153], v[232:235], v[10:13]
	s_setprio 0
	s_setprio 1
	v_mfma_f32_16x16x32_bf16 v[70:73], v[146:149], v[212:215], v[70:73]
	v_mfma_f32_16x16x32_bf16 v[66:69], v[158:161], v[212:215], v[66:69]
	v_mfma_f32_16x16x32_bf16 v[54:57], v[146:149], v[220:223], v[54:57]
	v_mfma_f32_16x16x32_bf16 v[50:53], v[158:161], v[220:223], v[50:53]
	v_mfma_f32_16x16x32_bf16 v[34:37], v[146:149], v[228:231], v[34:37]
	v_mfma_f32_16x16x32_bf16 v[30:33], v[158:161], v[228:231], v[30:33]
	v_mfma_f32_16x16x32_bf16 v[14:17], v[146:149], v[236:239], v[14:17]
	v_mfma_f32_16x16x32_bf16 v[10:13], v[158:161], v[236:239], v[10:13]
	s_setprio 0
	s_setprio 1
	v_mfma_f32_16x16x32_bf16 v[62:65], v[162:165], v[208:211], v[62:65]
	v_mfma_f32_16x16x32_bf16 v[58:61], v[200:203], v[208:211], v[58:61]
	v_mfma_f32_16x16x32_bf16 v[46:49], v[162:165], v[216:219], v[46:49]
	v_mfma_f32_16x16x32_bf16 v[42:45], v[200:203], v[216:219], v[42:45]
	v_mfma_f32_16x16x32_bf16 v[22:25], v[162:165], v[224:227], v[22:25]
	v_mfma_f32_16x16x32_bf16 v[18:21], v[200:203], v[224:227], v[18:21]
	v_mfma_f32_16x16x32_bf16 v[6:9], v[162:165], v[232:235], v[6:9]
	v_mfma_f32_16x16x32_bf16 v[2:5], v[200:203], v[232:235], v[2:5]
	s_setprio 0
	s_setprio 1
	v_mfma_f32_16x16x32_bf16 v[62:65], v[196:199], v[212:215], v[62:65]
	v_mfma_f32_16x16x32_bf16 v[58:61], v[204:207], v[212:215], v[58:61]
	v_mfma_f32_16x16x32_bf16 v[46:49], v[196:199], v[220:223], v[46:49]
	v_mfma_f32_16x16x32_bf16 v[42:45], v[204:207], v[220:223], v[42:45]
	v_mfma_f32_16x16x32_bf16 v[22:25], v[196:199], v[228:231], v[22:25]
	v_mfma_f32_16x16x32_bf16 v[18:21], v[204:207], v[228:231], v[18:21]
	v_mfma_f32_16x16x32_bf16 v[6:9], v[196:199], v[236:239], v[6:9]
	v_mfma_f32_16x16x32_bf16 v[2:5], v[204:207], v[236:239], v[2:5]
	s_setprio 0
	s_barrier
	s_andn2_b64 vcc, exec, s[44:45]
	s_mov_b64 s[46:47], -1
	s_mov_b64 s[44:45], 0
	s_movk_i32 s20, 0x100
	s_cbranch_vccz .LBB0_482
	s_waitcnt vmcnt(0)
	s_cmpk_lt_u32 s9, 0x100
	s_movk_i32 s83, 0x2000
	s_movk_i32 s86, 0x1fff
	s_cbranch_scc0 .LBB0_485
	s_barrier

.LBB0_1254:
	s_add_i32 s44, s20, 0x100
	s_and_b64 s[42:43], s[42:43], exec
	s_cselect_b32 s43, 0, s44
	s_cselect_b32 s42, 0, 0
	s_add_u32 s46, s2, s43
	s_addc_u32 s47, s3, s42
	s_add_i32 s70, 0, 0x10000
	s_add_u32 s52, s8, s43
	s_addc_u32 s53, s9, s42
	s_add_i32 s43, 0, 0x14000
	s_add_u32 s56, s18, s20
	s_addc_u32 s57, s19, 0
	s_add_i32 s67, s70, s10
	s_add_i32 m0, s11, 0xc000
	s_add_i32 s82, s11, 0xe000
	s_add_i32 s63, s67, 0x2000
	v_add_u32_e32 v139, s70, v137
	s_add_u32 s54, s52, 0x10000
	ds_read_b128 v[140:143], v139
	ds_read_b128 v[144:147], v139 offset:1024
	ds_read_b128 v[148:151], v139 offset:2048
	ds_read_b128 v[152:155], v139 offset:3072
	v_add_u32_e32 v139, s43, v137
	s_addc_u32 s55, s53, 0
	s_add_i32 s66, s43, s10
	ds_read_b128 v[158:161], v139
	ds_read_b128 v[162:165], v139 offset:1024
	ds_read_b128 v[196:199], v139 offset:2048
	ds_read_b128 v[200:203], v139 offset:3072
	s_add_i32 s65, s66, 0x2000
	s_add_i32 s62, 0, 0x18000
	s_add_i32 s59, 0, 0x1c000
	s_add_u32 s44, s46, 0x10000
	s_addc_u32 s45, s47, 0
	s_add_i32 s58, s62, s10
	s_add_i32 s20, s58, 0x2000
	s_add_u32 s42, s52, 0x10080
	s_addc_u32 s43, s53, 0
	s_add_i32 s84, s59, s10
	s_add_i32 s70, s84, 0x2000
	v_lshl_add_u64 v[236:237], s[56:57], 0, v[130:131]
	v_lshl_add_u64 v[236:237], v[236:237], 0, s[24:25]
	ds_read_b128 v[204:207], v138
	ds_read_b128 v[208:211], v138 offset:1024
	ds_read_b128 v[212:215], v138 offset:2048
	ds_read_b128 v[216:219], v138 offset:3072
	ds_read_b128 v[220:223], v138 offset:4096
	ds_read_b128 v[224:227], v138 offset:5120
	ds_read_b128 v[228:231], v138 offset:6144
	ds_read_b128 v[232:235], v138 offset:7168
	global_load_lds_dwordx4 v[236:237], off
	v_lshl_add_u64 v[236:237], s[56:57], 0, v[132:133]
	v_lshl_add_u64 v[236:237], v[236:237], 0, s[24:25]
	s_mov_b32 m0, s82
	s_nop 0
	global_load_lds_dwordx4 v[236:237], off
	s_waitcnt vmcnt(8)
	s_waitcnt lgkmcnt(0)
	s_setprio 1
	s_barrier
	s_waitcnt lgkmcnt(0)
	v_mfma_f32_16x16x32_bf16 v[126:129], v[140:143], v[204:207], v[126:129]
	v_mfma_f32_16x16x32_bf16 v[122:125], v[148:151], v[204:207], v[122:125]
	v_mfma_f32_16x16x32_bf16 v[118:121], v[140:143], v[212:215], v[118:121]
	v_mfma_f32_16x16x32_bf16 v[114:117], v[148:151], v[212:215], v[114:117]
	v_mfma_f32_16x16x32_bf16 v[102:105], v[140:143], v[220:223], v[102:105]
	v_mfma_f32_16x16x32_bf16 v[98:101], v[148:151], v[220:223], v[98:101]
	v_mfma_f32_16x16x32_bf16 v[86:89], v[140:143], v[228:231], v[86:89]
	v_mfma_f32_16x16x32_bf16 v[82:85], v[148:151], v[228:231], v[82:85]
	s_setprio 0
	s_setprio 1
	v_mfma_f32_16x16x32_bf16 v[126:129], v[144:147], v[208:211], v[126:129]
	v_mfma_f32_16x16x32_bf16 v[122:125], v[152:155], v[208:211], v[122:125]
	v_mfma_f32_16x16x32_bf16 v[118:121], v[144:147], v[216:219], v[118:121]
	v_mfma_f32_16x16x32_bf16 v[114:117], v[152:155], v[216:219], v[114:117]
	v_mfma_f32_16x16x32_bf16 v[102:105], v[144:147], v[224:227], v[102:105]
	v_mfma_f32_16x16x32_bf16 v[98:101], v[152:155], v[224:227], v[98:101]
	v_mfma_f32_16x16x32_bf16 v[86:89], v[144:147], v[232:235], v[86:89]
	v_mfma_f32_16x16x32_bf16 v[82:85], v[152:155], v[232:235], v[82:85]
	s_setprio 0
	s_setprio 1
	v_mfma_f32_16x16x32_bf16 v[110:113], v[158:161], v[204:207], v[110:113]
	v_mfma_f32_16x16x32_bf16 v[106:109], v[196:199], v[204:207], v[106:109]
	v_mfma_f32_16x16x32_bf16 v[94:97], v[158:161], v[212:215], v[94:97]
	v_mfma_f32_16x16x32_bf16 v[90:93], v[196:199], v[212:215], v[90:93]
	v_mfma_f32_16x16x32_bf16 v[78:81], v[158:161], v[220:223], v[78:81]
	v_mfma_f32_16x16x32_bf16 v[74:77], v[196:199], v[220:223], v[74:77]
	v_mfma_f32_16x16x32_bf16 v[70:73], v[158:161], v[228:231], v[70:73]
	v_mfma_f32_16x16x32_bf16 v[66:69], v[196:199], v[228:231], v[66:69]
	s_setprio 0
	s_setprio 1
	v_mfma_f32_16x16x32_bf16 v[110:113], v[162:165], v[208:211], v[110:113]
	v_mfma_f32_16x16x32_bf16 v[106:109], v[200:203], v[208:211], v[106:109]
	v_mfma_f32_16x16x32_bf16 v[94:97], v[162:165], v[216:219], v[94:97]
	v_mfma_f32_16x16x32_bf16 v[90:93], v[200:203], v[216:219], v[90:93]
	v_mfma_f32_16x16x32_bf16 v[78:81], v[162:165], v[224:227], v[78:81]
	v_mfma_f32_16x16x32_bf16 v[74:77], v[200:203], v[224:227], v[74:77]
	v_mfma_f32_16x16x32_bf16 v[70:73], v[162:165], v[232:235], v[70:73]
	v_mfma_f32_16x16x32_bf16 v[66:69], v[200:203], v[232:235], v[66:69]
	s_setprio 0
	s_barrier
	s_mov_b32 m0, s67
	v_lshl_add_u64 v[236:237], s[52:53], 0, v[0:1]
	ds_read_b128 v[204:207], v138 offset:16384
	ds_read_b128 v[208:211], v138 offset:17408
	ds_read_b128 v[212:215], v138 offset:18432
	ds_read_b128 v[216:219], v138 offset:19456
	ds_read_b128 v[220:223], v138 offset:20480
	ds_read_b128 v[224:227], v138 offset:21504
	ds_read_b128 v[228:231], v138 offset:22528
	ds_read_b128 v[232:235], v138 offset:23552
	global_load_lds_dwordx4 v[236:237], off
	v_lshl_add_u64 v[238:239], s[52:53], 0, v[134:135]
	s_mov_b32 m0, s63
	v_lshl_add_u64 v[240:241], s[54:55], 0, v[0:1]
	global_load_lds_dwordx4 v[238:239], off
	s_mov_b32 m0, s66
	v_lshl_add_u64 v[242:243], s[46:47], 0, v[132:133]
	global_load_lds_dwordx4 v[240:241], off
	v_lshl_add_u64 v[240:241], s[54:55], 0, v[134:135]
	s_mov_b32 m0, s65
	s_nop 0
	global_load_lds_dwordx4 v[240:241], off
	v_lshl_add_u64 v[240:241], s[46:47], 0, v[130:131]
	s_mov_b32 m0, s11
	s_nop 0
	global_load_lds_dwordx4 v[240:241], off
	s_mov_b32 m0, s12
	s_nop 0
	global_load_lds_dwordx4 v[242:243], off
	s_waitcnt vmcnt(8)
	s_waitcnt lgkmcnt(0)
	s_setprio 1
	s_barrier
	s_waitcnt lgkmcnt(0)
	v_mfma_f32_16x16x32_bf16 v[62:65], v[140:143], v[204:207], v[62:65]
	v_mfma_f32_16x16x32_bf16 v[58:61], v[148:151], v[204:207], v[58:61]
	v_mfma_f32_16x16x32_bf16 v[54:57], v[140:143], v[212:215], v[54:57]
	v_mfma_f32_16x16x32_bf16 v[50:53], v[148:151], v[212:215], v[50:53]
	v_mfma_f32_16x16x32_bf16 v[38:41], v[140:143], v[220:223], v[38:41]
	v_mfma_f32_16x16x32_bf16 v[34:37], v[148:151], v[220:223], v[34:37]
	v_mfma_f32_16x16x32_bf16 v[22:25], v[140:143], v[228:231], v[22:25]
	v_mfma_f32_16x16x32_bf16 v[18:21], v[148:151], v[228:231], v[18:21]
	s_setprio 0
	s_setprio 1
	v_mfma_f32_16x16x32_bf16 v[62:65], v[144:147], v[208:211], v[62:65]
	v_mfma_f32_16x16x32_bf16 v[58:61], v[152:155], v[208:211], v[58:61]
	v_mfma_f32_16x16x32_bf16 v[54:57], v[144:147], v[216:219], v[54:57]
	v_mfma_f32_16x16x32_bf16 v[50:53], v[152:155], v[216:219], v[50:53]
	v_mfma_f32_16x16x32_bf16 v[38:41], v[144:147], v[224:227], v[38:41]
	v_mfma_f32_16x16x32_bf16 v[34:37], v[152:155], v[224:227], v[34:37]
	v_mfma_f32_16x16x32_bf16 v[22:25], v[144:147], v[232:235], v[22:25]
	v_mfma_f32_16x16x32_bf16 v[18:21], v[152:155], v[232:235], v[18:21]
	s_setprio 0
	s_setprio 1
	v_mfma_f32_16x16x32_bf16 v[46:49], v[158:161], v[204:207], v[46:49]
	v_mfma_f32_16x16x32_bf16 v[42:45], v[196:199], v[204:207], v[42:45]
	v_mfma_f32_16x16x32_bf16 v[30:33], v[158:161], v[212:215], v[30:33]
	v_mfma_f32_16x16x32_bf16 v[26:29], v[196:199], v[212:215], v[26:29]
	v_mfma_f32_16x16x32_bf16 v[14:17], v[158:161], v[220:223], v[14:17]
	v_mfma_f32_16x16x32_bf16 v[10:13], v[196:199], v[220:223], v[10:13]
	v_mfma_f32_16x16x32_bf16 v[6:9], v[158:161], v[228:231], v[6:9]
	v_mfma_f32_16x16x32_bf16 v[2:5], v[196:199], v[228:231], v[2:5]
	s_setprio 0
	s_setprio 1
	v_mfma_f32_16x16x32_bf16 v[46:49], v[162:165], v[208:211], v[46:49]
	v_mfma_f32_16x16x32_bf16 v[42:45], v[200:203], v[208:211], v[42:45]
	v_mfma_f32_16x16x32_bf16 v[30:33], v[162:165], v[216:219], v[30:33]
	v_mfma_f32_16x16x32_bf16 v[26:29], v[200:203], v[216:219], v[26:29]
	v_mfma_f32_16x16x32_bf16 v[14:17], v[162:165], v[224:227], v[14:17]
	v_mfma_f32_16x16x32_bf16 v[10:13], v[200:203], v[224:227], v[10:13]
	v_mfma_f32_16x16x32_bf16 v[6:9], v[162:165], v[232:235], v[6:9]
	v_mfma_f32_16x16x32_bf16 v[2:5], v[200:203], v[232:235], v[2:5]
	s_setprio 0
	s_barrier
	v_add_u32_e32 v139, s62, v137
	ds_read_b128 v[140:143], v139
	ds_read_b128 v[144:147], v139 offset:1024
	ds_read_b128 v[148:151], v139 offset:2048
	ds_read_b128 v[152:155], v139 offset:3072
	v_add_u32_e32 v139, s59, v137
	ds_read_b128 v[158:161], v139
	ds_read_b128 v[162:165], v139 offset:1024
	ds_read_b128 v[196:199], v139 offset:2048
	ds_read_b128 v[200:203], v139 offset:3072
	s_mov_b32 m0, s13
	v_lshl_add_u64 v[244:245], s[44:45], 0, v[130:131]
	ds_read_b128 v[204:207], v138 offset:32768
	ds_read_b128 v[208:211], v138 offset:33792
	ds_read_b128 v[212:215], v138 offset:34816
	ds_read_b128 v[216:219], v138 offset:35840
	ds_read_b128 v[220:223], v138 offset:36864
	ds_read_b128 v[224:227], v138 offset:37888
	ds_read_b128 v[228:231], v138 offset:38912
	ds_read_b128 v[232:235], v138 offset:39936
	global_load_lds_dwordx4 v[244:245], off
	v_lshl_add_u64 v[244:245], s[44:45], 0, v[132:133]
	s_mov_b32 m0, s16
	s_nop 0
	global_load_lds_dwordx4 v[244:245], off
	s_waitcnt vmcnt(8)
	s_waitcnt lgkmcnt(0)
	s_setprio 1
	s_barrier
	s_waitcnt lgkmcnt(0)
	v_mfma_f32_16x16x32_bf16 v[126:129], v[140:143], v[204:207], v[126:129]
	v_mfma_f32_16x16x32_bf16 v[122:125], v[148:151], v[204:207], v[122:125]
	v_mfma_f32_16x16x32_bf16 v[118:121], v[140:143], v[212:215], v[118:121]
	v_mfma_f32_16x16x32_bf16 v[114:117], v[148:151], v[212:215], v[114:117]
	v_mfma_f32_16x16x32_bf16 v[102:105], v[140:143], v[220:223], v[102:105]
	v_mfma_f32_16x16x32_bf16 v[98:101], v[148:151], v[220:223], v[98:101]
	v_mfma_f32_16x16x32_bf16 v[86:89], v[140:143], v[228:231], v[86:89]
	v_mfma_f32_16x16x32_bf16 v[82:85], v[148:151], v[228:231], v[82:85]
	s_setprio 0
	s_setprio 1
	v_mfma_f32_16x16x32_bf16 v[126:129], v[144:147], v[208:211], v[126:129]
	v_mfma_f32_16x16x32_bf16 v[122:125], v[152:155], v[208:211], v[122:125]
	v_mfma_f32_16x16x32_bf16 v[118:121], v[144:147], v[216:219], v[118:121]
	v_mfma_f32_16x16x32_bf16 v[114:117], v[152:155], v[216:219], v[114:117]
	v_mfma_f32_16x16x32_bf16 v[102:105], v[144:147], v[224:227], v[102:105]
	v_mfma_f32_16x16x32_bf16 v[98:101], v[152:155], v[224:227], v[98:101]
	v_mfma_f32_16x16x32_bf16 v[86:89], v[144:147], v[232:235], v[86:89]
	v_mfma_f32_16x16x32_bf16 v[82:85], v[152:155], v[232:235], v[82:85]
	s_setprio 0
	s_setprio 1
	v_mfma_f32_16x16x32_bf16 v[110:113], v[158:161], v[204:207], v[110:113]
	v_mfma_f32_16x16x32_bf16 v[106:109], v[196:199], v[204:207], v[106:109]
	v_mfma_f32_16x16x32_bf16 v[94:97], v[158:161], v[212:215], v[94:97]
	v_mfma_f32_16x16x32_bf16 v[90:93], v[196:199], v[212:215], v[90:93]
	v_mfma_f32_16x16x32_bf16 v[78:81], v[158:161], v[220:223], v[78:81]
	v_mfma_f32_16x16x32_bf16 v[74:77], v[196:199], v[220:223], v[74:77]
	v_mfma_f32_16x16x32_bf16 v[70:73], v[158:161], v[228:231], v[70:73]
	v_mfma_f32_16x16x32_bf16 v[66:69], v[196:199], v[228:231], v[66:69]
	s_setprio 0
	s_setprio 1
	v_mfma_f32_16x16x32_bf16 v[110:113], v[162:165], v[208:211], v[110:113]
	v_mfma_f32_16x16x32_bf16 v[106:109], v[200:203], v[208:211], v[106:109]
	v_mfma_f32_16x16x32_bf16 v[94:97], v[162:165], v[216:219], v[94:97]
	v_mfma_f32_16x16x32_bf16 v[90:93], v[200:203], v[216:219], v[90:93]
	v_mfma_f32_16x16x32_bf16 v[78:81], v[162:165], v[224:227], v[78:81]
	v_mfma_f32_16x16x32_bf16 v[74:77], v[200:203], v[224:227], v[74:77]
	v_mfma_f32_16x16x32_bf16 v[70:73], v[162:165], v[232:235], v[70:73]
	v_mfma_f32_16x16x32_bf16 v[66:69], v[200:203], v[232:235], v[66:69]
	s_setprio 0
	s_barrier
	s_mov_b32 m0, s58
	v_lshl_add_u64 v[236:237], v[236:237], 0, s[24:25]
	ds_read_b128 v[204:207], v138 offset:49152
	ds_read_b128 v[208:211], v138 offset:50176
	ds_read_b128 v[212:215], v138 offset:51200
	ds_read_b128 v[216:219], v138 offset:52224
	ds_read_b128 v[220:223], v138 offset:53248
	ds_read_b128 v[224:227], v138 offset:54272
	ds_read_b128 v[228:231], v138 offset:55296
	ds_read_b128 v[232:235], v138 offset:56320
	global_load_lds_dwordx4 v[236:237], off
	v_lshl_add_u64 v[236:237], v[238:239], 0, s[24:25]
	s_mov_b32 m0, s20
	s_nop 0
	global_load_lds_dwordx4 v[236:237], off
	v_lshl_add_u64 v[236:237], s[42:43], 0, v[0:1]
	s_mov_b32 m0, s84
	s_nop 0
	global_load_lds_dwordx4 v[236:237], off
	v_lshl_add_u64 v[236:237], s[42:43], 0, v[134:135]
	s_mov_b32 m0, s70
	s_nop 0
	global_load_lds_dwordx4 v[236:237], off
	v_lshl_add_u64 v[236:237], v[240:241], 0, s[24:25]
	s_mov_b32 m0, s17
	s_nop 0
	global_load_lds_dwordx4 v[236:237], off
	v_lshl_add_u64 v[236:237], v[242:243], 0, s[24:25]
	s_mov_b32 m0, s28
	s_nop 0
	global_load_lds_dwordx4 v[236:237], off
	s_waitcnt vmcnt(8)
	s_waitcnt lgkmcnt(0)
	s_setprio 1
	s_barrier
	s_waitcnt lgkmcnt(0)
	v_mfma_f32_16x16x32_bf16 v[62:65], v[140:143], v[204:207], v[62:65]
	v_mfma_f32_16x16x32_bf16 v[58:61], v[148:151], v[204:207], v[58:61]
	v_mfma_f32_16x16x32_bf16 v[54:57], v[140:143], v[212:215], v[54:57]
	v_mfma_f32_16x16x32_bf16 v[50:53], v[148:151], v[212:215], v[50:53]
	v_mfma_f32_16x16x32_bf16 v[38:41], v[140:143], v[220:223], v[38:41]
	v_mfma_f32_16x16x32_bf16 v[34:37], v[148:151], v[220:223], v[34:37]
	v_mfma_f32_16x16x32_bf16 v[22:25], v[140:143], v[228:231], v[22:25]
	v_mfma_f32_16x16x32_bf16 v[18:21], v[148:151], v[228:231], v[18:21]
	s_setprio 0
	s_setprio 1
	v_mfma_f32_16x16x32_bf16 v[62:65], v[144:147], v[208:211], v[62:65]
	v_mfma_f32_16x16x32_bf16 v[58:61], v[152:155], v[208:211], v[58:61]
	v_mfma_f32_16x16x32_bf16 v[54:57], v[144:147], v[216:219], v[54:57]
	v_mfma_f32_16x16x32_bf16 v[50:53], v[152:155], v[216:219], v[50:53]
	v_mfma_f32_16x16x32_bf16 v[38:41], v[144:147], v[224:227], v[38:41]
	v_mfma_f32_16x16x32_bf16 v[34:37], v[152:155], v[224:227], v[34:37]
	v_mfma_f32_16x16x32_bf16 v[22:25], v[144:147], v[232:235], v[22:25]
	v_mfma_f32_16x16x32_bf16 v[18:21], v[152:155], v[232:235], v[18:21]
	s_setprio 0
	s_setprio 1
	v_mfma_f32_16x16x32_bf16 v[46:49], v[158:161], v[204:207], v[46:49]
	v_mfma_f32_16x16x32_bf16 v[42:45], v[196:199], v[204:207], v[42:45]
	v_mfma_f32_16x16x32_bf16 v[30:33], v[158:161], v[212:215], v[30:33]
	v_mfma_f32_16x16x32_bf16 v[26:29], v[196:199], v[212:215], v[26:29]
	v_mfma_f32_16x16x32_bf16 v[14:17], v[158:161], v[220:223], v[14:17]
	v_mfma_f32_16x16x32_bf16 v[10:13], v[196:199], v[220:223], v[10:13]
	v_mfma_f32_16x16x32_bf16 v[6:9], v[158:161], v[228:231], v[6:9]
	v_mfma_f32_16x16x32_bf16 v[2:5], v[196:199], v[228:231], v[2:5]
	s_setprio 0
	s_setprio 1
	v_mfma_f32_16x16x32_bf16 v[46:49], v[162:165], v[208:211], v[46:49]
	v_mfma_f32_16x16x32_bf16 v[42:45], v[200:203], v[208:211], v[42:45]
	v_mfma_f32_16x16x32_bf16 v[30:33], v[162:165], v[216:219], v[30:33]
	v_mfma_f32_16x16x32_bf16 v[26:29], v[200:203], v[216:219], v[26:29]
	v_mfma_f32_16x16x32_bf16 v[14:17], v[162:165], v[224:227], v[14:17]
	v_mfma_f32_16x16x32_bf16 v[10:13], v[200:203], v[224:227], v[10:13]
	v_mfma_f32_16x16x32_bf16 v[6:9], v[162:165], v[232:235], v[6:9]
	v_mfma_f32_16x16x32_bf16 v[2:5], v[200:203], v[232:235], v[2:5]
	s_setprio 0
	s_barrier
	s_andn2_b64 vcc, exec, s[40:41]
	s_mov_b64 s[42:43], -1
	s_mov_b64 s[40:41], 0
	s_movk_i32 s20, 0x100
	s_cbranch_vccz .LBB0_1254
	s_waitcnt vmcnt(0)
	s_cmpk_lt_u32 s7, 0x100
	s_cbranch_scc0 .LBB0_1257
	s_barrier

.LBB0_1302:
	s_add_u32 s17, s40, 0xfce78080
	s_addc_u32 s20, s41, -1
	s_cmp_lg_u32 s16, 12
	s_cselect_b32 s17, s17, 0
	s_cselect_b32 s20, s20, 0
	s_add_u32 s44, s6, s17
	s_addc_u32 s45, s7, s20
	s_add_i32 s46, 0, 0x10000
	s_add_u32 s42, s8, s17
	v_add_u32_e32 v143, s46, v141
	s_addc_u32 s43, s9, s20
	s_add_i32 s17, 0, 0x14000
	ds_read_b128 v[144:147], v143
	ds_read_b128 v[148:151], v143 offset:1024
	ds_read_b128 v[152:155], v143 offset:2048
	ds_read_b128 v[158:161], v143 offset:3072
	v_add_u32_e32 v143, s17, v141
	ds_read_b128 v[162:165], v143
	ds_read_b128 v[196:199], v143 offset:1024
	ds_read_b128 v[200:203], v143 offset:2048
	ds_read_b128 v[204:207], v143 offset:3072
	v_lshl_add_u64 v[240:241], v[138:139], 0, s[40:41]
	s_add_i32 m0, s4, 0xc000
	ds_read_b128 v[208:211], v142
	ds_read_b128 v[212:215], v142 offset:1024
	ds_read_b128 v[216:219], v142 offset:2048
	ds_read_b128 v[220:223], v142 offset:3072
	ds_read_b128 v[224:227], v142 offset:4096
	ds_read_b128 v[228:231], v142 offset:5120
	ds_read_b128 v[232:235], v142 offset:6144
	ds_read_b128 v[236:239], v142 offset:7168
	global_load_lds_dwordx4 v[240:241], off
	v_lshl_add_u64 v[240:241], v[136:137], 0, s[40:41]
	s_add_i32 m0, s4, 0xe000
	s_nop 0
	global_load_lds_dwordx4 v[240:241], off
	s_waitcnt vmcnt(8)
	s_waitcnt lgkmcnt(0)
	s_setprio 1
	s_barrier
	s_waitcnt lgkmcnt(0)
	v_mfma_f32_16x16x32_bf16 v[126:129], v[144:147], v[208:211], v[126:129]
	v_mfma_f32_16x16x32_bf16 v[122:125], v[152:155], v[208:211], v[122:125]
	v_mfma_f32_16x16x32_bf16 v[110:113], v[144:147], v[216:219], v[110:113]
	v_mfma_f32_16x16x32_bf16 v[106:109], v[152:155], v[216:219], v[106:109]
	v_mfma_f32_16x16x32_bf16 v[94:97], v[144:147], v[224:227], v[94:97]
	v_mfma_f32_16x16x32_bf16 v[90:93], v[152:155], v[224:227], v[90:93]
	v_mfma_f32_16x16x32_bf16 v[78:81], v[144:147], v[232:235], v[78:81]
	v_mfma_f32_16x16x32_bf16 v[74:77], v[152:155], v[232:235], v[74:77]
	s_setprio 0
	s_setprio 1
	v_mfma_f32_16x16x32_bf16 v[126:129], v[148:151], v[212:215], v[126:129]
	v_mfma_f32_16x16x32_bf16 v[122:125], v[158:161], v[212:215], v[122:125]
	v_mfma_f32_16x16x32_bf16 v[110:113], v[148:151], v[220:223], v[110:113]
	v_mfma_f32_16x16x32_bf16 v[106:109], v[158:161], v[220:223], v[106:109]
	v_mfma_f32_16x16x32_bf16 v[94:97], v[148:151], v[228:231], v[94:97]
	v_mfma_f32_16x16x32_bf16 v[90:93], v[158:161], v[228:231], v[90:93]
	v_mfma_f32_16x16x32_bf16 v[78:81], v[148:151], v[236:239], v[78:81]
	v_mfma_f32_16x16x32_bf16 v[74:77], v[158:161], v[236:239], v[74:77]
	s_setprio 0
	s_setprio 1
	v_mfma_f32_16x16x32_bf16 v[118:121], v[162:165], v[208:211], v[118:121]
	v_mfma_f32_16x16x32_bf16 v[114:117], v[200:203], v[208:211], v[114:117]
	v_mfma_f32_16x16x32_bf16 v[102:105], v[162:165], v[216:219], v[102:105]
	v_mfma_f32_16x16x32_bf16 v[98:101], v[200:203], v[216:219], v[98:101]
	v_mfma_f32_16x16x32_bf16 v[86:89], v[162:165], v[224:227], v[86:89]
	v_mfma_f32_16x16x32_bf16 v[82:85], v[200:203], v[224:227], v[82:85]
	v_mfma_f32_16x16x32_bf16 v[70:73], v[162:165], v[232:235], v[70:73]
	v_mfma_f32_16x16x32_bf16 v[66:69], v[200:203], v[232:235], v[66:69]
	s_setprio 0
	s_setprio 1
	v_mfma_f32_16x16x32_bf16 v[118:121], v[196:199], v[212:215], v[118:121]
	v_mfma_f32_16x16x32_bf16 v[114:117], v[204:207], v[212:215], v[114:117]
	v_mfma_f32_16x16x32_bf16 v[102:105], v[196:199], v[220:223], v[102:105]
	v_mfma_f32_16x16x32_bf16 v[98:101], v[204:207], v[220:223], v[98:101]
	v_mfma_f32_16x16x32_bf16 v[86:89], v[196:199], v[228:231], v[86:89]
	v_mfma_f32_16x16x32_bf16 v[82:85], v[204:207], v[228:231], v[82:85]
	v_mfma_f32_16x16x32_bf16 v[70:73], v[196:199], v[236:239], v[70:73]
	v_mfma_f32_16x16x32_bf16 v[66:69], v[204:207], v[236:239], v[66:69]
	s_setprio 0
	s_barrier
	s_add_i32 s20, s46, s3
	v_lshl_add_u64 v[240:241], s[42:43], 0, v[0:1]
	s_mov_b32 m0, s20
	ds_read_b128 v[208:211], v142 offset:16384
	ds_read_b128 v[212:215], v142 offset:17408
	ds_read_b128 v[216:219], v142 offset:18432
	ds_read_b128 v[220:223], v142 offset:19456
	ds_read_b128 v[224:227], v142 offset:20480
	ds_read_b128 v[228:231], v142 offset:21504
	ds_read_b128 v[232:235], v142 offset:22528
	ds_read_b128 v[236:239], v142 offset:23552
	global_load_lds_dwordx4 v[240:241], off
	s_add_i32 m0, s20, 0x2000
	s_add_u32 s46, s42, 0x10000
	v_lshl_add_u64 v[242:243], s[42:43], 0, v[134:135]
	s_addc_u32 s47, s43, 0
	s_add_i32 s17, s17, s3
	global_load_lds_dwordx4 v[242:243], off
	v_lshl_add_u64 v[244:245], s[46:47], 0, v[0:1]
	s_mov_b32 m0, s17
	v_lshl_add_u64 v[246:247], s[44:45], 0, v[132:133]
	global_load_lds_dwordx4 v[244:245], off
	v_lshl_add_u64 v[244:245], s[46:47], 0, v[134:135]
	s_add_i32 m0, s17, 0x2000
	s_nop 0
	global_load_lds_dwordx4 v[244:245], off
	v_lshl_add_u64 v[244:245], s[44:45], 0, v[130:131]
	s_mov_b32 m0, s4
	s_nop 0
	global_load_lds_dwordx4 v[244:245], off
	s_mov_b32 m0, s5
	s_nop 0
	global_load_lds_dwordx4 v[246:247], off
	s_waitcnt vmcnt(8)
	s_waitcnt lgkmcnt(0)
	s_setprio 1
	s_barrier
	s_waitcnt lgkmcnt(0)
	v_mfma_f32_16x16x32_bf16 v[62:65], v[144:147], v[208:211], v[62:65]
	v_mfma_f32_16x16x32_bf16 v[58:61], v[152:155], v[208:211], v[58:61]
	v_mfma_f32_16x16x32_bf16 v[46:49], v[144:147], v[216:219], v[46:49]
	v_mfma_f32_16x16x32_bf16 v[42:45], v[152:155], v[216:219], v[42:45]
	v_mfma_f32_16x16x32_bf16 v[30:33], v[144:147], v[224:227], v[30:33]
	v_mfma_f32_16x16x32_bf16 v[26:29], v[152:155], v[224:227], v[26:29]
	v_mfma_f32_16x16x32_bf16 v[14:17], v[144:147], v[232:235], v[14:17]
	v_mfma_f32_16x16x32_bf16 v[10:13], v[152:155], v[232:235], v[10:13]
	s_setprio 0
	s_setprio 1
	v_mfma_f32_16x16x32_bf16 v[62:65], v[148:151], v[212:215], v[62:65]
	v_mfma_f32_16x16x32_bf16 v[58:61], v[158:161], v[212:215], v[58:61]
	v_mfma_f32_16x16x32_bf16 v[46:49], v[148:151], v[220:223], v[46:49]
	v_mfma_f32_16x16x32_bf16 v[42:45], v[158:161], v[220:223], v[42:45]
	v_mfma_f32_16x16x32_bf16 v[30:33], v[148:151], v[228:231], v[30:33]
	v_mfma_f32_16x16x32_bf16 v[26:29], v[158:161], v[228:231], v[26:29]
	v_mfma_f32_16x16x32_bf16 v[14:17], v[148:151], v[236:239], v[14:17]
	v_mfma_f32_16x16x32_bf16 v[10:13], v[158:161], v[236:239], v[10:13]
	s_setprio 0
	s_setprio 1
	v_mfma_f32_16x16x32_bf16 v[54:57], v[162:165], v[208:211], v[54:57]
	v_mfma_f32_16x16x32_bf16 v[50:53], v[200:203], v[208:211], v[50:53]
	v_mfma_f32_16x16x32_bf16 v[38:41], v[162:165], v[216:219], v[38:41]
	v_mfma_f32_16x16x32_bf16 v[34:37], v[200:203], v[216:219], v[34:37]
	v_mfma_f32_16x16x32_bf16 v[22:25], v[162:165], v[224:227], v[22:25]
	v_mfma_f32_16x16x32_bf16 v[18:21], v[200:203], v[224:227], v[18:21]
	v_mfma_f32_16x16x32_bf16 v[6:9], v[162:165], v[232:235], v[6:9]
	v_mfma_f32_16x16x32_bf16 v[2:5], v[200:203], v[232:235], v[2:5]
	s_setprio 0
	s_setprio 1
	v_mfma_f32_16x16x32_bf16 v[54:57], v[196:199], v[212:215], v[54:57]
	v_mfma_f32_16x16x32_bf16 v[50:53], v[204:207], v[212:215], v[50:53]
	v_mfma_f32_16x16x32_bf16 v[38:41], v[196:199], v[220:223], v[38:41]
	v_mfma_f32_16x16x32_bf16 v[34:37], v[204:207], v[220:223], v[34:37]
	v_mfma_f32_16x16x32_bf16 v[22:25], v[196:199], v[228:231], v[22:25]
	v_mfma_f32_16x16x32_bf16 v[18:21], v[204:207], v[228:231], v[18:21]
	v_mfma_f32_16x16x32_bf16 v[6:9], v[196:199], v[236:239], v[6:9]
	v_mfma_f32_16x16x32_bf16 v[2:5], v[204:207], v[236:239], v[2:5]
	s_setprio 0
	s_barrier
	s_add_i32 s17, 0, 0x18000
	v_add_u32_e32 v143, s17, v141
	s_add_i32 s20, 0, 0x1c000
	ds_read_b128 v[144:147], v143
	ds_read_b128 v[148:151], v143 offset:1024
	ds_read_b128 v[152:155], v143 offset:2048
	ds_read_b128 v[158:161], v143 offset:3072
	v_add_u32_e32 v143, s20, v141
	ds_read_b128 v[162:165], v143
	ds_read_b128 v[196:199], v143 offset:1024
	ds_read_b128 v[200:203], v143 offset:2048
	ds_read_b128 v[204:207], v143 offset:3072
	s_add_u32 s44, s44, 0x40000
	s_addc_u32 s45, s45, 0
	s_mov_b32 m0, s10
	v_lshl_add_u64 v[248:249], s[44:45], 0, v[130:131]
	ds_read_b128 v[208:211], v142 offset:32768
	ds_read_b128 v[212:215], v142 offset:33792
	ds_read_b128 v[216:219], v142 offset:34816
	ds_read_b128 v[220:223], v142 offset:35840
	ds_read_b128 v[224:227], v142 offset:36864
	ds_read_b128 v[228:231], v142 offset:37888
	ds_read_b128 v[232:235], v142 offset:38912
	ds_read_b128 v[236:239], v142 offset:39936
	global_load_lds_dwordx4 v[248:249], off
	v_lshl_add_u64 v[248:249], s[44:45], 0, v[132:133]
	s_mov_b32 m0, s11
	s_nop 0
	global_load_lds_dwordx4 v[248:249], off
	s_waitcnt vmcnt(8)
	s_waitcnt lgkmcnt(0)
	s_setprio 1
	s_barrier
	s_waitcnt lgkmcnt(0)
	v_mfma_f32_16x16x32_bf16 v[126:129], v[144:147], v[208:211], v[126:129]
	v_mfma_f32_16x16x32_bf16 v[122:125], v[152:155], v[208:211], v[122:125]
	v_mfma_f32_16x16x32_bf16 v[110:113], v[144:147], v[216:219], v[110:113]
	v_mfma_f32_16x16x32_bf16 v[106:109], v[152:155], v[216:219], v[106:109]
	v_mfma_f32_16x16x32_bf16 v[94:97], v[144:147], v[224:227], v[94:97]
	v_mfma_f32_16x16x32_bf16 v[90:93], v[152:155], v[224:227], v[90:93]
	v_mfma_f32_16x16x32_bf16 v[78:81], v[144:147], v[232:235], v[78:81]
	v_mfma_f32_16x16x32_bf16 v[74:77], v[152:155], v[232:235], v[74:77]
	s_setprio 0
	s_setprio 1
	v_mfma_f32_16x16x32_bf16 v[126:129], v[148:151], v[212:215], v[126:129]
	v_mfma_f32_16x16x32_bf16 v[122:125], v[158:161], v[212:215], v[122:125]
	v_mfma_f32_16x16x32_bf16 v[110:113], v[148:151], v[220:223], v[110:113]
	v_mfma_f32_16x16x32_bf16 v[106:109], v[158:161], v[220:223], v[106:109]
	v_mfma_f32_16x16x32_bf16 v[94:97], v[148:151], v[228:231], v[94:97]
	v_mfma_f32_16x16x32_bf16 v[90:93], v[158:161], v[228:231], v[90:93]
	v_mfma_f32_16x16x32_bf16 v[78:81], v[148:151], v[236:239], v[78:81]
	v_mfma_f32_16x16x32_bf16 v[74:77], v[158:161], v[236:239], v[74:77]
	s_setprio 0
	s_setprio 1
	v_mfma_f32_16x16x32_bf16 v[118:121], v[162:165], v[208:211], v[118:121]
	v_mfma_f32_16x16x32_bf16 v[114:117], v[200:203], v[208:211], v[114:117]
	v_mfma_f32_16x16x32_bf16 v[102:105], v[162:165], v[216:219], v[102:105]
	v_mfma_f32_16x16x32_bf16 v[98:101], v[200:203], v[216:219], v[98:101]
	v_mfma_f32_16x16x32_bf16 v[86:89], v[162:165], v[224:227], v[86:89]
	v_mfma_f32_16x16x32_bf16 v[82:85], v[200:203], v[224:227], v[82:85]
	v_mfma_f32_16x16x32_bf16 v[70:73], v[162:165], v[232:235], v[70:73]
	v_mfma_f32_16x16x32_bf16 v[66:69], v[200:203], v[232:235], v[66:69]
	s_setprio 0
	s_setprio 1
	v_mfma_f32_16x16x32_bf16 v[118:121], v[196:199], v[212:215], v[118:121]
	v_mfma_f32_16x16x32_bf16 v[114:117], v[204:207], v[212:215], v[114:117]
	v_mfma_f32_16x16x32_bf16 v[102:105], v[196:199], v[220:223], v[102:105]
	v_mfma_f32_16x16x32_bf16 v[98:101], v[204:207], v[220:223], v[98:101]
	v_mfma_f32_16x16x32_bf16 v[86:89], v[196:199], v[228:231], v[86:89]
	v_mfma_f32_16x16x32_bf16 v[82:85], v[204:207], v[228:231], v[82:85]
	v_mfma_f32_16x16x32_bf16 v[70:73], v[196:199], v[236:239], v[70:73]
	v_mfma_f32_16x16x32_bf16 v[66:69], v[204:207], v[236:239], v[66:69]
	s_setprio 0
	s_barrier
	s_add_i32 s17, s17, s3
	v_lshl_add_u64 v[240:241], v[240:241], 0, s[24:25]
	s_mov_b32 m0, s17
	ds_read_b128 v[208:211], v142 offset:49152
	ds_read_b128 v[212:215], v142 offset:50176
	ds_read_b128 v[216:219], v142 offset:51200
	ds_read_b128 v[220:223], v142 offset:52224
	ds_read_b128 v[224:227], v142 offset:53248
	ds_read_b128 v[228:231], v142 offset:54272
	ds_read_b128 v[232:235], v142 offset:55296
	ds_read_b128 v[236:239], v142 offset:56320
	global_load_lds_dwordx4 v[240:241], off
	s_add_i32 m0, s17, 0x2000
	s_add_u32 s42, s42, 0x10080
	v_lshl_add_u64 v[240:241], v[242:243], 0, s[24:25]
	s_addc_u32 s43, s43, 0
	s_add_i32 s17, s20, s3
	global_load_lds_dwordx4 v[240:241], off
	v_lshl_add_u64 v[240:241], s[42:43], 0, v[0:1]
	s_mov_b32 m0, s17
	s_nop 0
	global_load_lds_dwordx4 v[240:241], off
	v_lshl_add_u64 v[240:241], s[42:43], 0, v[134:135]
	s_add_i32 m0, s17, 0x2000
	s_nop 0
	global_load_lds_dwordx4 v[240:241], off
	v_lshl_add_u64 v[240:241], v[244:245], 0, s[24:25]
	s_mov_b32 m0, s12
	s_nop 0
	global_load_lds_dwordx4 v[240:241], off
	v_lshl_add_u64 v[240:241], v[246:247], 0, s[24:25]
	s_mov_b32 m0, s13
	s_nop 0
	global_load_lds_dwordx4 v[240:241], off
	s_waitcnt vmcnt(8)
	s_waitcnt lgkmcnt(0)
	s_setprio 1
	s_barrier
	s_waitcnt lgkmcnt(0)
	v_mfma_f32_16x16x32_bf16 v[62:65], v[144:147], v[208:211], v[62:65]
	v_mfma_f32_16x16x32_bf16 v[58:61], v[152:155], v[208:211], v[58:61]
	v_mfma_f32_16x16x32_bf16 v[46:49], v[144:147], v[216:219], v[46:49]
	v_mfma_f32_16x16x32_bf16 v[42:45], v[152:155], v[216:219], v[42:45]
	v_mfma_f32_16x16x32_bf16 v[30:33], v[144:147], v[224:227], v[30:33]
	v_mfma_f32_16x16x32_bf16 v[26:29], v[152:155], v[224:227], v[26:29]
	v_mfma_f32_16x16x32_bf16 v[14:17], v[144:147], v[232:235], v[14:17]
	v_mfma_f32_16x16x32_bf16 v[10:13], v[152:155], v[232:235], v[10:13]
	s_setprio 0
	s_setprio 1
	v_mfma_f32_16x16x32_bf16 v[62:65], v[148:151], v[212:215], v[62:65]
	v_mfma_f32_16x16x32_bf16 v[58:61], v[158:161], v[212:215], v[58:61]
	v_mfma_f32_16x16x32_bf16 v[46:49], v[148:151], v[220:223], v[46:49]
	v_mfma_f32_16x16x32_bf16 v[42:45], v[158:161], v[220:223], v[42:45]
	v_mfma_f32_16x16x32_bf16 v[30:33], v[148:151], v[228:231], v[30:33]
	v_mfma_f32_16x16x32_bf16 v[26:29], v[158:161], v[228:231], v[26:29]
	v_mfma_f32_16x16x32_bf16 v[14:17], v[148:151], v[236:239], v[14:17]
	v_mfma_f32_16x16x32_bf16 v[10:13], v[158:161], v[236:239], v[10:13]
	s_setprio 0
	s_setprio 1
	v_mfma_f32_16x16x32_bf16 v[54:57], v[162:165], v[208:211], v[54:57]
	v_mfma_f32_16x16x32_bf16 v[50:53], v[200:203], v[208:211], v[50:53]
	v_mfma_f32_16x16x32_bf16 v[38:41], v[162:165], v[216:219], v[38:41]
	v_mfma_f32_16x16x32_bf16 v[34:37], v[200:203], v[216:219], v[34:37]
	v_mfma_f32_16x16x32_bf16 v[22:25], v[162:165], v[224:227], v[22:25]
	v_mfma_f32_16x16x32_bf16 v[18:21], v[200:203], v[224:227], v[18:21]
	v_mfma_f32_16x16x32_bf16 v[6:9], v[162:165], v[232:235], v[6:9]
	v_mfma_f32_16x16x32_bf16 v[2:5], v[200:203], v[232:235], v[2:5]
	s_setprio 0
	s_setprio 1
	v_mfma_f32_16x16x32_bf16 v[54:57], v[196:199], v[212:215], v[54:57]
	v_mfma_f32_16x16x32_bf16 v[50:53], v[204:207], v[212:215], v[50:53]
	v_mfma_f32_16x16x32_bf16 v[38:41], v[196:199], v[220:223], v[38:41]
	v_mfma_f32_16x16x32_bf16 v[34:37], v[204:207], v[220:223], v[34:37]
	v_mfma_f32_16x16x32_bf16 v[22:25], v[196:199], v[228:231], v[22:25]
	v_mfma_f32_16x16x32_bf16 v[18:21], v[204:207], v[228:231], v[18:21]
	v_mfma_f32_16x16x32_bf16 v[6:9], v[196:199], v[236:239], v[6:9]
	v_mfma_f32_16x16x32_bf16 v[2:5], v[204:207], v[236:239], v[2:5]
	s_setprio 0
	s_barrier
	s_add_i32 s16, s16, 2
	s_add_u32 s40, s40, 0x100
	s_addc_u32 s41, s41, 0
	s_cmp_gt_u32 s16, 13
	s_cbranch_scc0 .LBB0_1302
	s_waitcnt vmcnt(0)
	s_mov_b32 s12, s58
	s_cmpk_lt_u32 s1, 0x100
	s_cbranch_scc0 .LBB0_1305
	s_barrier
